# speedup vs baseline: 1.0128x; 1.0008x over previous
; __device__ __forceinline__ void phase0(const Params& p) {
;     ...
;   for (int row = blockIdx.x * 8 + wid; row < TOK; row += gridDim.x * 8) {
;     const float4* xr = (const float4*)(p.x + (size_t)row * DM);
;     float ss = 0.f;
; #pragma unroll
;     for (int i = 0; i < 8; ++i) {
;       float4 v = xr[lane + 64 * i];
;       ss += v.x * v.x + v.y * v.y + v.z * v.z + v.w * v.w;
;       u32x2 o = {pk2(v.x, v.y), pk2(v.z, v.w)};
;       *(u32x2*)(xb + (size_t)row * DM + (lane + 64 * i) * 4) = o;
;     }
;     ss = wave_sum(ss);
;     if (lane == 0) rowsq[row] = (rsq_t)(ss * RSQ_SCALE);
;   }
.LBB0_75:
	v_ashrrev_i32_e32 v1, 31, v0
	s_waitcnt lgkmcnt(0)
	v_lshlrev_b64 v[32:33], 13, v[0:1]
	v_lshl_add_u64 v[60:61], s[72:73], 0, v[32:33]
	v_lshl_add_u64 v[44:45], v[60:61], 0, v[2:3]
	v_readlane_b32 s0, v236, 14
	v_lshlrev_b64 v[36:37], 12, v[0:1]
	v_readlane_b32 s1, v236, 15
	v_lshl_add_u64 v[50:51], v[60:61], 0, v[12:13]
	v_lshl_add_u64 v[54:55], v[60:61], 0, v[16:17]
	v_lshl_add_u64 v[64:65], s[0:1], 0, v[36:37]
	v_lshl_add_u64 v[58:59], v[60:61], 0, v[20:21]
	v_lshl_add_u64 v[60:61], v[60:61], 0, v[24:25]
	v_lshl_add_u64 v[238:239], v[64:65], 0, v[4:5]
	v_lshl_add_u64 v[240:241], v[64:65], 0, v[6:7]
	v_lshl_add_u64 v[242:243], v[64:65], 0, v[8:9]
	v_lshl_add_u64 v[244:245], v[64:65], 0, v[10:11]
	v_lshl_add_u64 v[246:247], v[64:65], 0, v[14:15]
	v_lshl_add_u64 v[248:249], v[64:65], 0, v[18:19]
	v_lshl_add_u64 v[250:251], v[64:65], 0, v[22:23]
	v_lshl_add_u64 v[252:253], v[64:65], 0, v[26:27]
	global_load_dwordx4 v[32:35], v[44:45], off
	global_load_dwordx4 v[36:39], v[44:45], off offset:1024
	global_load_dwordx4 v[40:43], v[44:45], off offset:2048
	global_load_dwordx4 v[44:47], v[44:45], off offset:3072
	global_load_dwordx4 v[48:51], v[50:51], off
	global_load_dwordx4 v[52:55], v[54:55], off
	global_load_dwordx4 v[56:59], v[58:59], off
	global_load_dwordx4 v[60:63], v[60:61], off
	s_waitcnt vmcnt(7)
	v_cvt_pk_bf16_f32 v254, v32, v33
	v_cvt_pk_bf16_f32 v255, v34, v35
	global_store_dwordx2 v[238:239], v[254:255], off
	v_pk_mul_f32 v[32:33], v[32:33], v[32:33]
	v_pk_mul_f32 v[34:35], v[34:35], v[34:35]
	v_add_f32_e32 v31, v32, v33
	v_add_f32_e32 v31, v31, v34
	v_add_f32_e32 v31, v31, v35
	s_waitcnt vmcnt(7)
	v_cvt_pk_bf16_f32 v254, v36, v37
	v_cvt_pk_bf16_f32 v255, v38, v39
	global_store_dwordx2 v[240:241], v[254:255], off
	v_pk_mul_f32 v[32:33], v[36:37], v[36:37]
	v_pk_mul_f32 v[34:35], v[38:39], v[38:39]
	v_add_f32_e32 v32, v32, v33
	v_add_f32_e32 v32, v32, v34
	v_add_f32_e32 v32, v32, v35
	v_add_f32_e32 v31, v31, v32
	s_waitcnt vmcnt(7)
	v_cvt_pk_bf16_f32 v254, v40, v41
	v_cvt_pk_bf16_f32 v255, v42, v43
	global_store_dwordx2 v[242:243], v[254:255], off
	v_pk_mul_f32 v[32:33], v[40:41], v[40:41]
	v_pk_mul_f32 v[34:35], v[42:43], v[42:43]
	v_add_f32_e32 v32, v32, v33
	v_add_f32_e32 v32, v32, v34
	v_add_f32_e32 v32, v32, v35
	v_add_f32_e32 v31, v31, v32
	s_waitcnt vmcnt(7)
	v_cvt_pk_bf16_f32 v254, v44, v45
	v_cvt_pk_bf16_f32 v255, v46, v47
	global_store_dwordx2 v[244:245], v[254:255], off
	v_pk_mul_f32 v[32:33], v[44:45], v[44:45]
	v_pk_mul_f32 v[34:35], v[46:47], v[46:47]
	v_add_f32_e32 v32, v32, v33
	v_add_f32_e32 v32, v32, v34
	v_add_f32_e32 v32, v32, v35
	v_add_f32_e32 v31, v31, v32
	s_waitcnt vmcnt(7)
	v_cvt_pk_bf16_f32 v254, v48, v49
	v_cvt_pk_bf16_f32 v255, v50, v51
	global_store_dwordx2 v[246:247], v[254:255], off
	v_pk_mul_f32 v[32:33], v[48:49], v[48:49]
	v_pk_mul_f32 v[34:35], v[50:51], v[50:51]
	v_add_f32_e32 v32, v32, v33
	v_add_f32_e32 v32, v32, v34
	v_add_f32_e32 v32, v32, v35
	v_add_f32_e32 v31, v31, v32
	s_waitcnt vmcnt(7)
	v_cvt_pk_bf16_f32 v254, v52, v53
	v_cvt_pk_bf16_f32 v255, v54, v55
	global_store_dwordx2 v[248:249], v[254:255], off
	v_pk_mul_f32 v[32:33], v[52:53], v[52:53]
	v_pk_mul_f32 v[34:35], v[54:55], v[54:55]
	v_add_f32_e32 v32, v32, v33
	v_add_f32_e32 v32, v32, v34
	v_add_f32_e32 v32, v32, v35
	v_add_f32_e32 v31, v31, v32
	s_waitcnt vmcnt(7)
	v_cvt_pk_bf16_f32 v254, v56, v57
	v_cvt_pk_bf16_f32 v255, v58, v59
	global_store_dwordx2 v[250:251], v[254:255], off
	v_pk_mul_f32 v[32:33], v[56:57], v[56:57]
	v_pk_mul_f32 v[34:35], v[58:59], v[58:59]
	v_add_f32_e32 v32, v32, v33
	v_add_f32_e32 v32, v32, v34
	v_add_f32_e32 v32, v32, v35
	v_add_f32_e32 v31, v31, v32
	s_waitcnt vmcnt(7)
	v_cvt_pk_bf16_f32 v254, v60, v61
	v_cvt_pk_bf16_f32 v255, v62, v63
	global_store_dwordx2 v[252:253], v[254:255], off
	v_pk_mul_f32 v[32:33], v[60:61], v[60:61]
	v_pk_mul_f32 v[34:35], v[62:63], v[62:63]
	v_add_f32_e32 v32, v32, v33
	v_add_f32_e32 v32, v32, v34
	v_add_f32_e32 v32, v32, v35
	v_add_f32_e32 v31, v31, v32
	s_nop 1
	v_add_f32_dpp v31, v31, v31 row_ror:8 row_mask:0xf bank_mask:0xf bound_ctrl:1
	s_nop 1
	v_add_f32_dpp v31, v31, v31 row_ror:4 row_mask:0xf bank_mask:0xf bound_ctrl:1
	s_nop 1
	v_add_f32_dpp v31, v31, v31 row_ror:2 row_mask:0xf bank_mask:0xf bound_ctrl:1
	s_nop 1
	v_add_f32_dpp v31, v31, v31 row_ror:1 row_mask:0xf bank_mask:0xf bound_ctrl:1
	ds_bpermute_b32 v32, v29, v31
	s_waitcnt lgkmcnt(0)
	v_add_f32_e32 v31, v31, v32
	ds_bpermute_b32 v32, v30, v31
	s_and_saveexec_b64 s[0:1], vcc
	s_cbranch_execz .LBB0_74
	s_waitcnt lgkmcnt(0)
	v_add_f32_e32 v31, v31, v32
	v_mul_f32_e32 v31, 0x49800000, v31
	v_trunc_f32_e32 v31, v31
	v_mul_f32_e32 v32, 0x2f800000, v31
	v_floor_f32_e32 v33, v32
	v_fmac_f32_e32 v31, 0xcf800000, v33
	v_cvt_u32_f32_e32 v32, v31
	v_cvt_u32_f32_e32 v33, v33
	v_lshl_add_u64 v[34:35], v[0:1], 3, s[14:15]
	global_store_dwordx2 v[34:35], v[32:33], off
	s_branch .LBB0_74

; #define STAGE_A(POFF, h, kt) STAGE_AX(POFF, h, kt, brow)
; #define STAGE_B(POFF, h, kt) STAGE_BX(POFF, h, kt, bcol)
; #define LDA(dst, b, h) _Pragma("unroll") for (int m = 0; m < 4; ++m) _Pragma("unroll") for (int k = 0; k < 2; ++k) \
;     dst[m][k] = *reinterpret_cast<const bf16x8*>((char*)SA(b, h) + lds_byte(wr * 64 + m * 16 + fr, k * 32 + fq * 8))
; #define LDB(dst, b, h) _Pragma("unroll") for (int n = 0; n < 2; ++n) _Pragma("unroll") for (int k = 0; k < 2; ++k) \
;     dst[n][k] = *reinterpret_cast<const bf16x8*>((char*)SB(b, h) + lds_byte(wc * 32 + n * 16 + fr, k * 32 + fq * 8))
; #define MMA(ai, bj, At_, Bt_) do { __builtin_amdgcn_s_setprio(1); \
;     _Pragma("unroll") for (int k = 0; k < 2; ++k) _Pragma("unroll") for (int m = 0; m < 4; ++m) _Pragma("unroll") for (int n = 0; n < 2; ++n) \
;       acc[ai][bj][m][n] = __builtin_amdgcn_mfma_f32_16x16x32_bf16(At_[m][k], Bt_[n][k], acc[ai][bj][m][n], 0, 0, 0); \
;     __builtin_amdgcn_s_setprio(0); } while (0)
; #define WAIT_V(n) asm volatile("s_waitcnt vmcnt(" #n ")" ::: "memory")
; #define BAR __builtin_amdgcn_s_barrier()
; #define SCHED __builtin_amdgcn_sched_barrier(0)
; template <int EPI, int N, int K>
; __device__ __forceinline__ void gemm_phase(const bf16_t* __restrict__ A, const bf16_t* __restrict__ Bt, const EpiArgs ea) {
;     ...
;     int brow, bcol; TILE_RC(w, brow, bcol);
;     f32x4 acc[2][2][4][2];
; #pragma unroll
;     for (int a = 0; a < 2; ++a)
; #pragma unroll
;       for (int b = 0; b < 2; ++b)
; #pragma unroll
;         for (int m = 0; m < 4; ++m)
; #pragma unroll
;           for (int n = 0; n < 2; ++n) acc[a][b][m][n] = (f32x4){0.f, 0.f, 0.f, 0.f};
;     bf16x8 At[4][2], B0[2][2], B1[2][2];
;     if (wr == 1) BAR;
;     if (w == (int)blockIdx.x) { WAIT_V(0); } else { WAIT_V(24); }
;     BAR;
;     BAR;
;     for (int t = 0; t < nt - 2; t += 2) {
;       LDB(B0, 0, 0); SCHED; LDA(At, 0, 0); STAGE_A(SA_OFF(1, 1), 1, t + 1);
;       WAIT_L(8); BAR; WAIT_L(0); MMA(0, 0, At, B0); BAR; SCHED;
;       LDB(B1, 0, 1); STAGE_B(SB_OFF(0, 0), 0, t + 2);
;       BAR; WAIT_L(0); MMA(0, 1, At, B1); BAR;
;       LDA(At, 0, 1); STAGE_A(SA_OFF(0, 0), 0, t + 2);
;       BAR; WAIT_L(0); MMA(1, 0, At, B0); BAR; SCHED;
.LBB0_132:
	s_and_b32 s0, s26, 7
	s_mulk_i32 s0, 0xc0
	s_ashr_i32 s1, s26, 3
	s_add_i32 s1, s0, s1
	s_mul_hi_i32 s0, s1, 0x2aaaaaab
	s_lshr_b32 s2, s0, 31
	s_ashr_i32 s0, s0, 5
	s_add_i32 s0, s0, s2
	s_mul_i32 s2, s0, 0xc0
	s_sub_i32 s27, s1, s2
	s_lshl_b32 s1, s27, 8
	s_lshl_b32 s2, s27, 5
	s_lshl_b32 s3, s27, 17
	s_and_b32 s27, s27, 7
	s_lshl_b32 s28, s0, 23
	s_lshl_b32 s27, s27, 20
	s_and_b32 s3, s3, 0xfff00000
	s_or_b32 s27, s28, s27
	s_mov_b32 s28, -2
	s_mov_b32 s29, 0
	s_barrier
	s_barrier
	ds_read_b128 v[154:157], v145
	ds_read_b128 v[158:161], v145 offset:1024
	ds_read_b128 v[162:165], v145 offset:2048
	ds_read_b128 v[166:169], v145 offset:3072
	ds_read_b128 v[170:173], v146
	ds_read_b128 v[174:177], v146 offset:1024
	ds_read_b128 v[178:181], v147
	ds_read_b128 v[182:185], v147 offset:1024
	ds_read_b128 v[186:189], v148
	ds_read_b128 v[190:193], v148 offset:1024
	ds_read_b128 v[194:197], v149
	ds_read_b128 v[198:201], v149 offset:1024
	ds_read_b128 v[218:221], v146 offset:16384
	ds_read_b128 v[222:225], v146 offset:17408
	ds_read_b128 v[226:229], v147 offset:16384
	ds_read_b128 v[230:233], v147 offset:17408
	ds_read_b128 v[238:241], v148 offset:16384
	ds_read_b128 v[242:245], v148 offset:17408
	s_add_i32 s30, s27, s29
	s_mov_b32 m0, s24
	s_or_b32 s31, s30, 0x80080
	buffer_load_dwordx4 v131, s[48:51], s31 offen lds
	s_mov_b32 m0, s25
	s_or_b32 s31, s30, 0xc0080
	buffer_load_dwordx4 v131, s[48:51], s31 offen lds
	s_setprio 1
	s_barrier
	s_waitcnt lgkmcnt(6)
	v_mfma_f32_16x16x32_bf16 v[124:127], v[170:173], v[154:157], 0
	v_mfma_f32_16x16x32_bf16 v[120:123], v[170:173], v[162:165], 0
	v_mfma_f32_16x16x32_bf16 v[116:119], v[178:181], v[154:157], 0
	v_mfma_f32_16x16x32_bf16 v[112:115], v[178:181], v[162:165], 0
	v_mfma_f32_16x16x32_bf16 v[108:111], v[186:189], v[154:157], 0
	v_mfma_f32_16x16x32_bf16 v[104:107], v[186:189], v[162:165], 0
	v_mfma_f32_16x16x32_bf16 v[100:103], v[194:197], v[154:157], 0
	v_mfma_f32_16x16x32_bf16 v[96:99], v[194:197], v[162:165], 0
	v_mfma_f32_16x16x32_bf16 v[124:127], v[174:177], v[158:161], v[124:127]
	v_mfma_f32_16x16x32_bf16 v[120:123], v[174:177], v[166:169], v[120:123]
	v_mfma_f32_16x16x32_bf16 v[116:119], v[182:185], v[158:161], v[116:119]
	v_mfma_f32_16x16x32_bf16 v[112:115], v[182:185], v[166:169], v[112:115]
	v_mfma_f32_16x16x32_bf16 v[108:111], v[190:193], v[158:161], v[108:111]
	v_mfma_f32_16x16x32_bf16 v[104:107], v[190:193], v[166:169], v[104:107]
	v_mfma_f32_16x16x32_bf16 v[100:103], v[198:201], v[158:161], v[100:103]
	v_mfma_f32_16x16x32_bf16 v[96:99], v[198:201], v[166:169], v[96:99]
	s_barrier
	s_setprio 0
	ds_read_b128 v[202:205], v150
	ds_read_b128 v[206:209], v150 offset:1024
	ds_read_b128 v[210:213], v150 offset:2048
	ds_read_b128 v[214:217], v150 offset:3072
	ds_read_b128 v[246:249], v149 offset:16384
	ds_read_b128 v[250:253], v149 offset:17408
	s_add_i32 s31, s3, s29
	s_mov_b32 m0, s11
	s_add_i32 s34, s31, 0x100
	buffer_load_dwordx4 v134, s[72:75], s34 offen lds
	s_mov_b32 m0, s12
	s_add_i32 s34, s31, 0x80100
	buffer_load_dwordx4 v134, s[72:75], s34 offen lds
	s_waitcnt vmcnt(6)
	s_setprio 1
	s_barrier
	s_waitcnt lgkmcnt(2)
	v_mfma_f32_16x16x32_bf16 v[92:95], v[170:173], v[202:205], 0
	v_mfma_f32_16x16x32_bf16 v[88:91], v[170:173], v[210:213], 0
	v_mfma_f32_16x16x32_bf16 v[84:87], v[178:181], v[202:205], 0
	v_mfma_f32_16x16x32_bf16 v[80:83], v[178:181], v[210:213], 0
	v_mfma_f32_16x16x32_bf16 v[76:79], v[186:189], v[202:205], 0
	v_mfma_f32_16x16x32_bf16 v[72:75], v[186:189], v[210:213], 0
	v_mfma_f32_16x16x32_bf16 v[68:71], v[194:197], v[202:205], 0
	v_mfma_f32_16x16x32_bf16 v[64:67], v[194:197], v[210:213], 0
	v_mfma_f32_16x16x32_bf16 v[92:95], v[174:177], v[206:209], v[92:95]
	v_mfma_f32_16x16x32_bf16 v[88:91], v[174:177], v[214:217], v[88:91]
	v_mfma_f32_16x16x32_bf16 v[84:87], v[182:185], v[206:209], v[84:87]
	v_mfma_f32_16x16x32_bf16 v[80:83], v[182:185], v[214:217], v[80:83]
	v_mfma_f32_16x16x32_bf16 v[76:79], v[190:193], v[206:209], v[76:79]
	v_mfma_f32_16x16x32_bf16 v[72:75], v[190:193], v[214:217], v[72:75]
	v_mfma_f32_16x16x32_bf16 v[68:71], v[198:201], v[206:209], v[68:71]
	v_mfma_f32_16x16x32_bf16 v[64:67], v[198:201], v[214:217], v[64:67]
	s_barrier
	s_setprio 0
	ds_read_b128 v[170:173], v146 offset:32768
	ds_read_b128 v[174:177], v146 offset:33792
	ds_read_b128 v[178:181], v147 offset:32768
	ds_read_b128 v[182:185], v147 offset:33792
	ds_read_b128 v[186:189], v148 offset:32768
	ds_read_b128 v[190:193], v148 offset:33792
	s_mov_b32 m0, s10
	s_add_i32 s34, s30, 0x100
	buffer_load_dwordx4 v131, s[48:51], s34 offen lds
	s_mov_b32 m0, s13
	s_add_i32 s35, s30, 0x40100
	buffer_load_dwordx4 v131, s[48:51], s35 offen lds
	s_waitcnt vmcnt(10)
	s_setprio 1
	s_barrier
	s_waitcnt lgkmcnt(6)
	v_mfma_f32_16x16x32_bf16 v[60:63], v[218:221], v[154:157], 0
	v_mfma_f32_16x16x32_bf16 v[56:59], v[218:221], v[162:165], 0
	v_mfma_f32_16x16x32_bf16 v[52:55], v[226:229], v[154:157], 0
	v_mfma_f32_16x16x32_bf16 v[48:51], v[226:229], v[162:165], 0
	v_mfma_f32_16x16x32_bf16 v[44:47], v[238:241], v[154:157], 0
	v_mfma_f32_16x16x32_bf16 v[40:43], v[238:241], v[162:165], 0
	v_mfma_f32_16x16x32_bf16 v[36:39], v[246:249], v[154:157], 0
	v_mfma_f32_16x16x32_bf16 v[32:35], v[246:249], v[162:165], 0
	v_mfma_f32_16x16x32_bf16 v[60:63], v[222:225], v[158:161], v[60:63]
	v_mfma_f32_16x16x32_bf16 v[56:59], v[222:225], v[166:169], v[56:59]
	v_mfma_f32_16x16x32_bf16 v[52:55], v[230:233], v[158:161], v[52:55]
	v_mfma_f32_16x16x32_bf16 v[48:51], v[230:233], v[166:169], v[48:51]
	v_mfma_f32_16x16x32_bf16 v[44:47], v[242:245], v[158:161], v[44:47]
	v_mfma_f32_16x16x32_bf16 v[40:43], v[242:245], v[166:169], v[40:43]
	v_mfma_f32_16x16x32_bf16 v[36:39], v[250:253], v[158:161], v[36:39]
	v_mfma_f32_16x16x32_bf16 v[32:35], v[250:253], v[166:169], v[32:35]
	s_barrier
; #define STAGE_A(POFF, h, kt) STAGE_AX(POFF, h, kt, brow)
; #define STAGE_B(POFF, h, kt) STAGE_BX(POFF, h, kt, bcol)
; #define LDA(dst, b, h) _Pragma("unroll") for (int m = 0; m < 4; ++m) _Pragma("unroll") for (int k = 0; k < 2; ++k) \
;     dst[m][k] = *reinterpret_cast<const bf16x8*>((char*)SA(b, h) + lds_byte(wr * 64 + m * 16 + fr, k * 32 + fq * 8))
; #define LDB(dst, b, h) _Pragma("unroll") for (int n = 0; n < 2; ++n) _Pragma("unroll") for (int k = 0; k < 2; ++k) \
;     dst[n][k] = *reinterpret_cast<const bf16x8*>((char*)SB(b, h) + lds_byte(wc * 32 + n * 16 + fr, k * 32 + fq * 8))
; #define MMA(ai, bj, At_, Bt_) do { __builtin_amdgcn_s_setprio(1); \
;     _Pragma("unroll") for (int k = 0; k < 2; ++k) _Pragma("unroll") for (int m = 0; m < 4; ++m) _Pragma("unroll") for (int n = 0; n < 2; ++n) \
;       acc[ai][bj][m][n] = __builtin_amdgcn_mfma_f32_16x16x32_bf16(At_[m][k], Bt_[n][k], acc[ai][bj][m][n], 0, 0, 0); \
;     __builtin_amdgcn_s_setprio(0); } while (0)
; #define WAIT_V(n) asm volatile("s_waitcnt vmcnt(" #n ")" ::: "memory")
; #define BAR __builtin_amdgcn_s_barrier()
; #define SCHED __builtin_amdgcn_sched_barrier(0)
; template <int EPI, int N, int K>
; __device__ __forceinline__ void gemm_phase(const bf16_t* __restrict__ A, const bf16_t* __restrict__ Bt, const EpiArgs ea) {
;     ...
;       BAR; WAIT_L(0); MMA(1, 0, At, B0); BAR; SCHED;
;       STAGE_B(SB_OFF(0, 1), 1, t + 2);
;       WAIT_V(6); BAR; MMA(1, 1, At, B1); BAR;
;       LDB(B0, 1, 0); SCHED; LDA(At, 1, 0); STAGE_A(SA_OFF(0, 1), 1, t + 2);
;       WAIT_L(8); BAR; WAIT_L(0); MMA(0, 0, At, B0); BAR; SCHED;
;       LDB(B1, 1, 1); STAGE_B(SB_OFF(1, 0), 0, t + 3);
;       BAR; WAIT_L(0); MMA(0, 1, At, B1); BAR;
;       LDA(At, 1, 1); STAGE_A(SA_OFF(1, 0), 0, t + 3);
;       BAR; WAIT_L(0); MMA(1, 0, At, B0); BAR; SCHED;
	s_setprio 0
	ds_read_b128 v[154:157], v151
	ds_read_b128 v[158:161], v151 offset:1024
	ds_read_b128 v[162:165], v151 offset:2048
	ds_read_b128 v[166:169], v151 offset:3072
	ds_read_b128 v[194:197], v149 offset:32768
	ds_read_b128 v[198:201], v149 offset:33792
	s_mov_b32 m0, s14
	s_add_i32 s35, s31, 0x2100
	buffer_load_dwordx4 v134, s[72:75], s35 offen lds
	s_mov_b32 m0, s15
	s_add_i32 s35, s31, 0x82100
	buffer_load_dwordx4 v134, s[72:75], s35 offen lds
	s_waitcnt vmcnt(6)
	s_setprio 1
	s_barrier
	v_mfma_f32_16x16x32_bf16 v[28:31], v[218:221], v[202:205], 0
	v_mfma_f32_16x16x32_bf16 v[24:27], v[218:221], v[210:213], 0
	v_mfma_f32_16x16x32_bf16 v[20:23], v[226:229], v[202:205], 0
	v_mfma_f32_16x16x32_bf16 v[16:19], v[226:229], v[210:213], 0
	v_mfma_f32_16x16x32_bf16 v[12:15], v[238:241], v[202:205], 0
	v_mfma_f32_16x16x32_bf16 v[8:11], v[238:241], v[210:213], 0
	v_mfma_f32_16x16x32_bf16 v[4:7], v[246:249], v[202:205], 0
	v_mfma_f32_16x16x32_bf16 v[0:3], v[246:249], v[210:213], 0
	v_mfma_f32_16x16x32_bf16 v[28:31], v[222:225], v[206:209], v[28:31]
	v_mfma_f32_16x16x32_bf16 v[24:27], v[222:225], v[214:217], v[24:27]
	v_mfma_f32_16x16x32_bf16 v[20:23], v[230:233], v[206:209], v[20:23]
	v_mfma_f32_16x16x32_bf16 v[16:19], v[230:233], v[214:217], v[16:19]
	v_mfma_f32_16x16x32_bf16 v[12:15], v[242:245], v[206:209], v[12:15]
	v_mfma_f32_16x16x32_bf16 v[8:11], v[242:245], v[214:217], v[8:11]
	v_mfma_f32_16x16x32_bf16 v[4:7], v[250:253], v[206:209], v[4:7]
	v_mfma_f32_16x16x32_bf16 v[0:3], v[250:253], v[214:217], v[0:3]
	s_barrier
	s_setprio 0
	ds_read_b128 v[218:221], v146 offset:49152
	ds_read_b128 v[222:225], v146 offset:50176
	ds_read_b128 v[226:229], v147 offset:49152
	ds_read_b128 v[230:233], v147 offset:50176
	ds_read_b128 v[238:241], v148 offset:49152
	ds_read_b128 v[242:245], v148 offset:50176
	s_mov_b32 m0, s16
	s_or_b32 s35, s34, 0x80000
	buffer_load_dwordx4 v131, s[48:51], s35 offen lds
	s_mov_b32 m0, s17
	s_or_b32 s34, s34, 0xc0000
	buffer_load_dwordx4 v131, s[48:51], s34 offen lds
	s_setprio 1
	s_barrier
	s_waitcnt lgkmcnt(6)
	v_mfma_f32_16x16x32_bf16 v[124:127], v[170:173], v[154:157], v[124:127]
	v_mfma_f32_16x16x32_bf16 v[120:123], v[170:173], v[162:165], v[120:123]
	v_mfma_f32_16x16x32_bf16 v[116:119], v[178:181], v[154:157], v[116:119]
	v_mfma_f32_16x16x32_bf16 v[112:115], v[178:181], v[162:165], v[112:115]
	v_mfma_f32_16x16x32_bf16 v[108:111], v[186:189], v[154:157], v[108:111]
	v_mfma_f32_16x16x32_bf16 v[104:107], v[186:189], v[162:165], v[104:107]
	v_mfma_f32_16x16x32_bf16 v[100:103], v[194:197], v[154:157], v[100:103]
	v_mfma_f32_16x16x32_bf16 v[96:99], v[194:197], v[162:165], v[96:99]
	v_mfma_f32_16x16x32_bf16 v[124:127], v[174:177], v[158:161], v[124:127]
	v_mfma_f32_16x16x32_bf16 v[120:123], v[174:177], v[166:169], v[120:123]
	v_mfma_f32_16x16x32_bf16 v[116:119], v[182:185], v[158:161], v[116:119]
	v_mfma_f32_16x16x32_bf16 v[112:115], v[182:185], v[166:169], v[112:115]
	v_mfma_f32_16x16x32_bf16 v[108:111], v[190:193], v[158:161], v[108:111]
	v_mfma_f32_16x16x32_bf16 v[104:107], v[190:193], v[166:169], v[104:107]
	v_mfma_f32_16x16x32_bf16 v[100:103], v[198:201], v[158:161], v[100:103]
	v_mfma_f32_16x16x32_bf16 v[96:99], v[198:201], v[166:169], v[96:99]
	s_barrier
	s_setprio 0
	ds_read_b128 v[202:205], v152
	ds_read_b128 v[206:209], v152 offset:1024
	ds_read_b128 v[210:213], v152 offset:2048
	ds_read_b128 v[214:217], v152 offset:3072
	ds_read_b128 v[246:249], v149 offset:49152
	ds_read_b128 v[250:253], v149 offset:50176
	s_mov_b32 m0, s18
	s_add_i32 s34, s31, 0x180
	buffer_load_dwordx4 v134, s[72:75], s34 offen lds
	s_mov_b32 m0, s19
	s_add_i32 s34, s31, 0x80180
	buffer_load_dwordx4 v134, s[72:75], s34 offen lds
	s_waitcnt vmcnt(6)
	s_setprio 1
	s_barrier
	s_waitcnt lgkmcnt(2)
	v_mfma_f32_16x16x32_bf16 v[92:95], v[170:173], v[202:205], v[92:95]
	v_mfma_f32_16x16x32_bf16 v[88:91], v[170:173], v[210:213], v[88:91]
	v_mfma_f32_16x16x32_bf16 v[84:87], v[178:181], v[202:205], v[84:87]
	v_mfma_f32_16x16x32_bf16 v[80:83], v[178:181], v[210:213], v[80:83]
	v_mfma_f32_16x16x32_bf16 v[76:79], v[186:189], v[202:205], v[76:79]
	v_mfma_f32_16x16x32_bf16 v[72:75], v[186:189], v[210:213], v[72:75]
	v_mfma_f32_16x16x32_bf16 v[68:71], v[194:197], v[202:205], v[68:71]
	v_mfma_f32_16x16x32_bf16 v[64:67], v[194:197], v[210:213], v[64:67]
	v_mfma_f32_16x16x32_bf16 v[92:95], v[174:177], v[206:209], v[92:95]
	v_mfma_f32_16x16x32_bf16 v[88:91], v[174:177], v[214:217], v[88:91]
	v_mfma_f32_16x16x32_bf16 v[84:87], v[182:185], v[206:209], v[84:87]
	v_mfma_f32_16x16x32_bf16 v[80:83], v[182:185], v[214:217], v[80:83]
	v_mfma_f32_16x16x32_bf16 v[76:79], v[190:193], v[206:209], v[76:79]
	v_mfma_f32_16x16x32_bf16 v[72:75], v[190:193], v[214:217], v[72:75]
	v_mfma_f32_16x16x32_bf16 v[68:71], v[198:201], v[206:209], v[68:71]
	v_mfma_f32_16x16x32_bf16 v[64:67], v[198:201], v[214:217], v[64:67]
	s_barrier
	s_setprio 0
	ds_read_b128 v[170:173], v146
	ds_read_b128 v[174:177], v146 offset:1024
	ds_read_b128 v[178:181], v147
	ds_read_b128 v[182:185], v147 offset:1024
	ds_read_b128 v[186:189], v148
	ds_read_b128 v[190:193], v148 offset:1024
	s_mov_b32 m0, s20
	s_add_i32 s34, s30, 0x180
	buffer_load_dwordx4 v131, s[48:51], s34 offen lds
	s_mov_b32 m0, s21
	s_add_i32 s30, s30, 0x40180
	buffer_load_dwordx4 v131, s[48:51], s30 offen lds
	s_waitcnt vmcnt(10)
	s_setprio 1
	s_barrier
; #define STAGE_A(POFF, h, kt) STAGE_AX(POFF, h, kt, brow)
; #define STAGE_B(POFF, h, kt) STAGE_BX(POFF, h, kt, bcol)
; #define LDA(dst, b, h) _Pragma("unroll") for (int m = 0; m < 4; ++m) _Pragma("unroll") for (int k = 0; k < 2; ++k) \
;     dst[m][k] = *reinterpret_cast<const bf16x8*>((char*)SA(b, h) + lds_byte(wr * 64 + m * 16 + fr, k * 32 + fq * 8))
; #define LDB(dst, b, h) _Pragma("unroll") for (int n = 0; n < 2; ++n) _Pragma("unroll") for (int k = 0; k < 2; ++k) \
;     dst[n][k] = *reinterpret_cast<const bf16x8*>((char*)SB(b, h) + lds_byte(wc * 32 + n * 16 + fr, k * 32 + fq * 8))
; #define MMA(ai, bj, At_, Bt_) do { __builtin_amdgcn_s_setprio(1); \
;     _Pragma("unroll") for (int k = 0; k < 2; ++k) _Pragma("unroll") for (int m = 0; m < 4; ++m) _Pragma("unroll") for (int n = 0; n < 2; ++n) \
;       acc[ai][bj][m][n] = __builtin_amdgcn_mfma_f32_16x16x32_bf16(At_[m][k], Bt_[n][k], acc[ai][bj][m][n], 0, 0, 0); \
;     __builtin_amdgcn_s_setprio(0); } while (0)
; #define WAIT_V(n) asm volatile("s_waitcnt vmcnt(" #n ")" ::: "memory")
; #define BAR __builtin_amdgcn_s_barrier()
; #define SCHED __builtin_amdgcn_sched_barrier(0)
; template <int EPI, int N, int K>
; __device__ __forceinline__ void gemm_phase(const bf16_t* __restrict__ A, const bf16_t* __restrict__ Bt, const EpiArgs ea) {
;     ...
;       LDB(B0, 0, 0); SCHED; LDA(At, 0, 0); STAGE_A(SA_OFF(1, 1), 1, t + 1);
;       WAIT_L(8); BAR; WAIT_L(0); MMA(0, 0, At, B0); BAR; SCHED;
;       LDB(B1, 0, 1); STAGE_B(SB_OFF(0, 0), 0, t + 2);
;       BAR; WAIT_L(0); MMA(0, 1, At, B1); BAR;
;     ...
;       WAIT_V(6); BAR; MMA(1, 1, At, B1); BAR;
;       LDB(B0, 1, 0); SCHED; LDA(At, 1, 0); STAGE_A(SA_OFF(0, 1), 1, t + 2);
;       WAIT_L(8); BAR; WAIT_L(0); MMA(0, 0, At, B0); BAR; SCHED;
;       LDB(B1, 1, 1); STAGE_B(SB_OFF(1, 0), 0, t + 3);
;       BAR; WAIT_L(0); MMA(0, 1, At, B1); BAR;
;       LDA(At, 1, 1); STAGE_A(SA_OFF(1, 0), 0, t + 3);
;       BAR; WAIT_L(0); MMA(1, 0, At, B0); BAR; SCHED;
;       STAGE_B(SB_OFF(1, 1), 1, t + 3);
;       WAIT_V(6); BAR; MMA(1, 1, At, B1); BAR;
	s_waitcnt lgkmcnt(6)
	v_mfma_f32_16x16x32_bf16 v[60:63], v[218:221], v[154:157], v[60:63]
	v_mfma_f32_16x16x32_bf16 v[56:59], v[218:221], v[162:165], v[56:59]
	v_mfma_f32_16x16x32_bf16 v[52:55], v[226:229], v[154:157], v[52:55]
	v_mfma_f32_16x16x32_bf16 v[48:51], v[226:229], v[162:165], v[48:51]
	v_mfma_f32_16x16x32_bf16 v[44:47], v[238:241], v[154:157], v[44:47]
	v_mfma_f32_16x16x32_bf16 v[40:43], v[238:241], v[162:165], v[40:43]
	v_mfma_f32_16x16x32_bf16 v[36:39], v[246:249], v[154:157], v[36:39]
	v_mfma_f32_16x16x32_bf16 v[32:35], v[246:249], v[162:165], v[32:35]
	v_mfma_f32_16x16x32_bf16 v[60:63], v[222:225], v[158:161], v[60:63]
	v_mfma_f32_16x16x32_bf16 v[56:59], v[222:225], v[166:169], v[56:59]
	v_mfma_f32_16x16x32_bf16 v[52:55], v[230:233], v[158:161], v[52:55]
	v_mfma_f32_16x16x32_bf16 v[48:51], v[230:233], v[166:169], v[48:51]
	v_mfma_f32_16x16x32_bf16 v[44:47], v[242:245], v[158:161], v[44:47]
	v_mfma_f32_16x16x32_bf16 v[40:43], v[242:245], v[166:169], v[40:43]
	v_mfma_f32_16x16x32_bf16 v[36:39], v[250:253], v[158:161], v[36:39]
	v_mfma_f32_16x16x32_bf16 v[32:35], v[250:253], v[166:169], v[32:35]
	s_barrier
	s_setprio 0
	ds_read_b128 v[154:157], v145
	ds_read_b128 v[158:161], v145 offset:1024
	ds_read_b128 v[162:165], v145 offset:2048
	ds_read_b128 v[166:169], v145 offset:3072
	ds_read_b128 v[194:197], v149
	ds_read_b128 v[198:201], v149 offset:1024
	s_mov_b32 m0, s22
	s_add_i32 s30, s31, 0x2180
	buffer_load_dwordx4 v134, s[72:75], s30 offen lds
	s_mov_b32 m0, s23
	s_add_i32 s31, s31, 0x82180
	buffer_load_dwordx4 v134, s[72:75], s31 offen lds
	s_waitcnt vmcnt(6)
	s_setprio 1
	s_barrier
	v_mfma_f32_16x16x32_bf16 v[28:31], v[218:221], v[202:205], v[28:31]
	v_mfma_f32_16x16x32_bf16 v[24:27], v[218:221], v[210:213], v[24:27]
	v_mfma_f32_16x16x32_bf16 v[20:23], v[226:229], v[202:205], v[20:23]
	v_mfma_f32_16x16x32_bf16 v[16:19], v[226:229], v[210:213], v[16:19]
	v_mfma_f32_16x16x32_bf16 v[12:15], v[238:241], v[202:205], v[12:15]
	v_mfma_f32_16x16x32_bf16 v[8:11], v[238:241], v[210:213], v[8:11]
	v_mfma_f32_16x16x32_bf16 v[4:7], v[246:249], v[202:205], v[4:7]
	v_mfma_f32_16x16x32_bf16 v[0:3], v[246:249], v[210:213], v[0:3]
	v_mfma_f32_16x16x32_bf16 v[28:31], v[222:225], v[206:209], v[28:31]
	v_mfma_f32_16x16x32_bf16 v[24:27], v[222:225], v[214:217], v[24:27]
	v_mfma_f32_16x16x32_bf16 v[20:23], v[230:233], v[206:209], v[20:23]
	v_mfma_f32_16x16x32_bf16 v[16:19], v[230:233], v[214:217], v[16:19]
	v_mfma_f32_16x16x32_bf16 v[12:15], v[242:245], v[206:209], v[12:15]
	v_mfma_f32_16x16x32_bf16 v[8:11], v[242:245], v[214:217], v[8:11]
	v_mfma_f32_16x16x32_bf16 v[4:7], v[250:253], v[206:209], v[4:7]
	v_mfma_f32_16x16x32_bf16 v[0:3], v[250:253], v[214:217], v[0:3]
	s_barrier
	s_setprio 0
	s_add_i32 s28, s28, 2
	s_addk_i32 s29, 0x100
	s_cmp_lt_u32 s28, 28
.LBB0_133:
	ds_read_b128 v[218:221], v146 offset:16384
	ds_read_b128 v[222:225], v146 offset:17408
	ds_read_b128 v[226:229], v147 offset:16384
	ds_read_b128 v[230:233], v147 offset:17408
	ds_read_b128 v[238:241], v148 offset:16384
	ds_read_b128 v[242:245], v148 offset:17408
	s_add_i32 s30, s27, s29
	s_mov_b32 m0, s24
	s_or_b32 s31, s30, 0x80080
	buffer_load_dwordx4 v131, s[48:51], s31 offen lds
	s_mov_b32 m0, s25
	s_or_b32 s31, s30, 0xc0080
	buffer_load_dwordx4 v131, s[48:51], s31 offen lds
	s_setprio 1
	s_barrier
	s_waitcnt lgkmcnt(6)
	v_mfma_f32_16x16x32_bf16 v[124:127], v[170:173], v[154:157], v[124:127]
	v_mfma_f32_16x16x32_bf16 v[120:123], v[170:173], v[162:165], v[120:123]
	v_mfma_f32_16x16x32_bf16 v[116:119], v[178:181], v[154:157], v[116:119]
	v_mfma_f32_16x16x32_bf16 v[112:115], v[178:181], v[162:165], v[112:115]
	v_mfma_f32_16x16x32_bf16 v[108:111], v[186:189], v[154:157], v[108:111]
	v_mfma_f32_16x16x32_bf16 v[104:107], v[186:189], v[162:165], v[104:107]
	v_mfma_f32_16x16x32_bf16 v[100:103], v[194:197], v[154:157], v[100:103]
	v_mfma_f32_16x16x32_bf16 v[96:99], v[194:197], v[162:165], v[96:99]
	v_mfma_f32_16x16x32_bf16 v[124:127], v[174:177], v[158:161], v[124:127]
	v_mfma_f32_16x16x32_bf16 v[120:123], v[174:177], v[166:169], v[120:123]
	v_mfma_f32_16x16x32_bf16 v[116:119], v[182:185], v[158:161], v[116:119]
	v_mfma_f32_16x16x32_bf16 v[112:115], v[182:185], v[166:169], v[112:115]
	v_mfma_f32_16x16x32_bf16 v[108:111], v[190:193], v[158:161], v[108:111]
	v_mfma_f32_16x16x32_bf16 v[104:107], v[190:193], v[166:169], v[104:107]
	v_mfma_f32_16x16x32_bf16 v[100:103], v[198:201], v[158:161], v[100:103]
	v_mfma_f32_16x16x32_bf16 v[96:99], v[198:201], v[166:169], v[96:99]
	s_barrier
	s_setprio 0
	ds_read_b128 v[202:205], v150
	ds_read_b128 v[206:209], v150 offset:1024
	ds_read_b128 v[210:213], v150 offset:2048
	ds_read_b128 v[214:217], v150 offset:3072
	ds_read_b128 v[246:249], v149 offset:16384
	ds_read_b128 v[250:253], v149 offset:17408
	s_add_i32 s31, s3, s29
	s_mov_b32 m0, s11
	s_add_i32 s34, s31, 0x100
	buffer_load_dwordx4 v134, s[72:75], s34 offen lds
	s_mov_b32 m0, s12
	s_add_i32 s34, s31, 0x80100
	buffer_load_dwordx4 v134, s[72:75], s34 offen lds
	s_waitcnt vmcnt(6)
	s_setprio 1
	s_barrier
	s_waitcnt lgkmcnt(2)
	v_mfma_f32_16x16x32_bf16 v[92:95], v[170:173], v[202:205], v[92:95]
	v_mfma_f32_16x16x32_bf16 v[88:91], v[170:173], v[210:213], v[88:91]
	v_mfma_f32_16x16x32_bf16 v[84:87], v[178:181], v[202:205], v[84:87]
	v_mfma_f32_16x16x32_bf16 v[80:83], v[178:181], v[210:213], v[80:83]
	v_mfma_f32_16x16x32_bf16 v[76:79], v[186:189], v[202:205], v[76:79]
	v_mfma_f32_16x16x32_bf16 v[72:75], v[186:189], v[210:213], v[72:75]
	v_mfma_f32_16x16x32_bf16 v[68:71], v[194:197], v[202:205], v[68:71]
	v_mfma_f32_16x16x32_bf16 v[64:67], v[194:197], v[210:213], v[64:67]
	v_mfma_f32_16x16x32_bf16 v[92:95], v[174:177], v[206:209], v[92:95]
	v_mfma_f32_16x16x32_bf16 v[88:91], v[174:177], v[214:217], v[88:91]
	v_mfma_f32_16x16x32_bf16 v[84:87], v[182:185], v[206:209], v[84:87]
	v_mfma_f32_16x16x32_bf16 v[80:83], v[182:185], v[214:217], v[80:83]
	v_mfma_f32_16x16x32_bf16 v[76:79], v[190:193], v[206:209], v[76:79]
	v_mfma_f32_16x16x32_bf16 v[72:75], v[190:193], v[214:217], v[72:75]
	v_mfma_f32_16x16x32_bf16 v[68:71], v[198:201], v[206:209], v[68:71]
	v_mfma_f32_16x16x32_bf16 v[64:67], v[198:201], v[214:217], v[64:67]
	s_barrier
; #define STAGE_A(POFF, h, kt) STAGE_AX(POFF, h, kt, brow)
; #define STAGE_B(POFF, h, kt) STAGE_BX(POFF, h, kt, bcol)
; #define LDA(dst, b, h) _Pragma("unroll") for (int m = 0; m < 4; ++m) _Pragma("unroll") for (int k = 0; k < 2; ++k) \
;     dst[m][k] = *reinterpret_cast<const bf16x8*>((char*)SA(b, h) + lds_byte(wr * 64 + m * 16 + fr, k * 32 + fq * 8))
; #define LDB(dst, b, h) _Pragma("unroll") for (int n = 0; n < 2; ++n) _Pragma("unroll") for (int k = 0; k < 2; ++k) \
;     dst[n][k] = *reinterpret_cast<const bf16x8*>((char*)SB(b, h) + lds_byte(wc * 32 + n * 16 + fr, k * 32 + fq * 8))
; #define MMA(ai, bj, At_, Bt_) do { __builtin_amdgcn_s_setprio(1); \
;     _Pragma("unroll") for (int k = 0; k < 2; ++k) _Pragma("unroll") for (int m = 0; m < 4; ++m) _Pragma("unroll") for (int n = 0; n < 2; ++n) \
;       acc[ai][bj][m][n] = __builtin_amdgcn_mfma_f32_16x16x32_bf16(At_[m][k], Bt_[n][k], acc[ai][bj][m][n], 0, 0, 0); \
;     __builtin_amdgcn_s_setprio(0); } while (0)
; #define WAIT_V(n) asm volatile("s_waitcnt vmcnt(" #n ")" ::: "memory")
; #define BAR __builtin_amdgcn_s_barrier()
; #define SCHED __builtin_amdgcn_sched_barrier(0)
; template <int EPI, int N, int K>
; __device__ __forceinline__ void gemm_phase(const bf16_t* __restrict__ A, const bf16_t* __restrict__ Bt, const EpiArgs ea) {
;     ...
;       BAR; WAIT_L(0); MMA(0, 1, At, B1); BAR;
;       LDA(At, 0, 1); STAGE_A(SA_OFF(0, 0), 0, t + 2);
;       BAR; WAIT_L(0); MMA(1, 0, At, B0); BAR; SCHED;
;       STAGE_B(SB_OFF(0, 1), 1, t + 2);
;       WAIT_V(6); BAR; MMA(1, 1, At, B1); BAR;
;       LDB(B0, 1, 0); SCHED; LDA(At, 1, 0); STAGE_A(SA_OFF(0, 1), 1, t + 2);
;       WAIT_L(8); BAR; WAIT_L(0); MMA(0, 0, At, B0); BAR; SCHED;
;       LDB(B1, 1, 1); STAGE_B(SB_OFF(1, 0), 0, t + 3);
	s_setprio 0
	ds_read_b128 v[170:173], v146 offset:32768
	ds_read_b128 v[174:177], v146 offset:33792
	ds_read_b128 v[178:181], v147 offset:32768
	ds_read_b128 v[182:185], v147 offset:33792
	ds_read_b128 v[186:189], v148 offset:32768
	ds_read_b128 v[190:193], v148 offset:33792
	s_mov_b32 m0, s10
	s_add_i32 s34, s30, 0x100
	buffer_load_dwordx4 v131, s[48:51], s34 offen lds
	s_mov_b32 m0, s13
	s_add_i32 s35, s30, 0x40100
	buffer_load_dwordx4 v131, s[48:51], s35 offen lds
	s_waitcnt vmcnt(10)
	s_setprio 1
	s_barrier
	s_waitcnt lgkmcnt(6)
	v_mfma_f32_16x16x32_bf16 v[60:63], v[218:221], v[154:157], v[60:63]
	v_mfma_f32_16x16x32_bf16 v[56:59], v[218:221], v[162:165], v[56:59]
	v_mfma_f32_16x16x32_bf16 v[52:55], v[226:229], v[154:157], v[52:55]
	v_mfma_f32_16x16x32_bf16 v[48:51], v[226:229], v[162:165], v[48:51]
	v_mfma_f32_16x16x32_bf16 v[44:47], v[238:241], v[154:157], v[44:47]
	v_mfma_f32_16x16x32_bf16 v[40:43], v[238:241], v[162:165], v[40:43]
	v_mfma_f32_16x16x32_bf16 v[36:39], v[246:249], v[154:157], v[36:39]
	v_mfma_f32_16x16x32_bf16 v[32:35], v[246:249], v[162:165], v[32:35]
	v_mfma_f32_16x16x32_bf16 v[60:63], v[222:225], v[158:161], v[60:63]
	v_mfma_f32_16x16x32_bf16 v[56:59], v[222:225], v[166:169], v[56:59]
	v_mfma_f32_16x16x32_bf16 v[52:55], v[230:233], v[158:161], v[52:55]
	v_mfma_f32_16x16x32_bf16 v[48:51], v[230:233], v[166:169], v[48:51]
	v_mfma_f32_16x16x32_bf16 v[44:47], v[242:245], v[158:161], v[44:47]
	v_mfma_f32_16x16x32_bf16 v[40:43], v[242:245], v[166:169], v[40:43]
	v_mfma_f32_16x16x32_bf16 v[36:39], v[250:253], v[158:161], v[36:39]
	v_mfma_f32_16x16x32_bf16 v[32:35], v[250:253], v[166:169], v[32:35]
	s_barrier
	s_setprio 0
	ds_read_b128 v[154:157], v151
	ds_read_b128 v[158:161], v151 offset:1024
	ds_read_b128 v[162:165], v151 offset:2048
	ds_read_b128 v[166:169], v151 offset:3072
	ds_read_b128 v[194:197], v149 offset:32768
	ds_read_b128 v[198:201], v149 offset:33792
	s_mov_b32 m0, s14
	s_add_i32 s35, s31, 0x2100
	buffer_load_dwordx4 v134, s[72:75], s35 offen lds
	s_mov_b32 m0, s15
	s_add_i32 s35, s31, 0x82100
	buffer_load_dwordx4 v134, s[72:75], s35 offen lds
	s_waitcnt vmcnt(6)
	s_setprio 1
	s_barrier
	v_mfma_f32_16x16x32_bf16 v[28:31], v[218:221], v[202:205], v[28:31]
	v_mfma_f32_16x16x32_bf16 v[24:27], v[218:221], v[210:213], v[24:27]
	v_mfma_f32_16x16x32_bf16 v[20:23], v[226:229], v[202:205], v[20:23]
	v_mfma_f32_16x16x32_bf16 v[16:19], v[226:229], v[210:213], v[16:19]
	v_mfma_f32_16x16x32_bf16 v[12:15], v[238:241], v[202:205], v[12:15]
	v_mfma_f32_16x16x32_bf16 v[8:11], v[238:241], v[210:213], v[8:11]
	v_mfma_f32_16x16x32_bf16 v[4:7], v[246:249], v[202:205], v[4:7]
	v_mfma_f32_16x16x32_bf16 v[0:3], v[246:249], v[210:213], v[0:3]
	v_mfma_f32_16x16x32_bf16 v[28:31], v[222:225], v[206:209], v[28:31]
	v_mfma_f32_16x16x32_bf16 v[24:27], v[222:225], v[214:217], v[24:27]
	v_mfma_f32_16x16x32_bf16 v[20:23], v[230:233], v[206:209], v[20:23]
	v_mfma_f32_16x16x32_bf16 v[16:19], v[230:233], v[214:217], v[16:19]
	v_mfma_f32_16x16x32_bf16 v[12:15], v[242:245], v[206:209], v[12:15]
	v_mfma_f32_16x16x32_bf16 v[8:11], v[242:245], v[214:217], v[8:11]
	v_mfma_f32_16x16x32_bf16 v[4:7], v[250:253], v[206:209], v[4:7]
	v_mfma_f32_16x16x32_bf16 v[0:3], v[250:253], v[214:217], v[0:3]
	s_barrier
	s_setprio 0
	ds_read_b128 v[218:221], v146 offset:49152
	ds_read_b128 v[222:225], v146 offset:50176
	ds_read_b128 v[226:229], v147 offset:49152
	ds_read_b128 v[230:233], v147 offset:50176
	ds_read_b128 v[238:241], v148 offset:49152
	ds_read_b128 v[242:245], v148 offset:50176
	s_mov_b32 m0, s16
	s_or_b32 s35, s34, 0x80000
	buffer_load_dwordx4 v131, s[48:51], s35 offen lds
	s_mov_b32 m0, s17
	s_or_b32 s34, s34, 0xc0000
	buffer_load_dwordx4 v131, s[48:51], s34 offen lds
	s_setprio 1
	s_barrier
	s_waitcnt lgkmcnt(6)
	v_mfma_f32_16x16x32_bf16 v[124:127], v[170:173], v[154:157], v[124:127]
	v_mfma_f32_16x16x32_bf16 v[120:123], v[170:173], v[162:165], v[120:123]
	v_mfma_f32_16x16x32_bf16 v[116:119], v[178:181], v[154:157], v[116:119]
	v_mfma_f32_16x16x32_bf16 v[112:115], v[178:181], v[162:165], v[112:115]
	v_mfma_f32_16x16x32_bf16 v[108:111], v[186:189], v[154:157], v[108:111]
	v_mfma_f32_16x16x32_bf16 v[104:107], v[186:189], v[162:165], v[104:107]
	v_mfma_f32_16x16x32_bf16 v[100:103], v[194:197], v[154:157], v[100:103]
	v_mfma_f32_16x16x32_bf16 v[96:99], v[194:197], v[162:165], v[96:99]
	v_mfma_f32_16x16x32_bf16 v[124:127], v[174:177], v[158:161], v[124:127]
	v_mfma_f32_16x16x32_bf16 v[120:123], v[174:177], v[166:169], v[120:123]
	v_mfma_f32_16x16x32_bf16 v[116:119], v[182:185], v[158:161], v[116:119]
	v_mfma_f32_16x16x32_bf16 v[112:115], v[182:185], v[166:169], v[112:115]
	v_mfma_f32_16x16x32_bf16 v[108:111], v[190:193], v[158:161], v[108:111]
	v_mfma_f32_16x16x32_bf16 v[104:107], v[190:193], v[166:169], v[104:107]
	v_mfma_f32_16x16x32_bf16 v[100:103], v[198:201], v[158:161], v[100:103]
	v_mfma_f32_16x16x32_bf16 v[96:99], v[198:201], v[166:169], v[96:99]
	s_barrier
	s_setprio 0
	ds_read_b128 v[202:205], v152
	ds_read_b128 v[206:209], v152 offset:1024
	ds_read_b128 v[210:213], v152 offset:2048
	ds_read_b128 v[214:217], v152 offset:3072
	ds_read_b128 v[246:249], v149 offset:49152
	ds_read_b128 v[250:253], v149 offset:50176
	s_mov_b32 m0, s18
	s_add_i32 s34, s31, 0x180
	buffer_load_dwordx4 v134, s[72:75], s34 offen lds
	s_mov_b32 m0, s19
	s_add_i32 s34, s31, 0x80180
	buffer_load_dwordx4 v134, s[72:75], s34 offen lds
	s_waitcnt vmcnt(6)
	s_setprio 1
	s_barrier
; #define STAGE_A(POFF, h, kt) STAGE_AX(POFF, h, kt, brow)
; #define STAGE_B(POFF, h, kt) STAGE_BX(POFF, h, kt, bcol)
; #define LDA(dst, b, h) _Pragma("unroll") for (int m = 0; m < 4; ++m) _Pragma("unroll") for (int k = 0; k < 2; ++k) \
;     dst[m][k] = *reinterpret_cast<const bf16x8*>((char*)SA(b, h) + lds_byte(wr * 64 + m * 16 + fr, k * 32 + fq * 8))
; #define LDB(dst, b, h) _Pragma("unroll") for (int n = 0; n < 2; ++n) _Pragma("unroll") for (int k = 0; k < 2; ++k) \
;     dst[n][k] = *reinterpret_cast<const bf16x8*>((char*)SB(b, h) + lds_byte(wc * 32 + n * 16 + fr, k * 32 + fq * 8))
; #define MMA(ai, bj, At_, Bt_) do { __builtin_amdgcn_s_setprio(1); \
;     _Pragma("unroll") for (int k = 0; k < 2; ++k) _Pragma("unroll") for (int m = 0; m < 4; ++m) _Pragma("unroll") for (int n = 0; n < 2; ++n) \
;       acc[ai][bj][m][n] = __builtin_amdgcn_mfma_f32_16x16x32_bf16(At_[m][k], Bt_[n][k], acc[ai][bj][m][n], 0, 0, 0); \
;     __builtin_amdgcn_s_setprio(0); } while (0)
; #define WAIT_V(n) asm volatile("s_waitcnt vmcnt(" #n ")" ::: "memory")
; #define BAR __builtin_amdgcn_s_barrier()
; #define SCHED __builtin_amdgcn_sched_barrier(0)
; template <int EPI, int N, int K>
; __device__ __forceinline__ void gemm_phase(const bf16_t* __restrict__ A, const bf16_t* __restrict__ Bt, const EpiArgs ea) {
;     ...
;       LDB(B1, 1, 1); STAGE_B(SB_OFF(1, 0), 0, t + 3);
;       BAR; WAIT_L(0); MMA(0, 1, At, B1); BAR;
;       LDA(At, 1, 1); STAGE_A(SA_OFF(1, 0), 0, t + 3);
;       BAR; WAIT_L(0); MMA(1, 0, At, B0); BAR; SCHED;
;       STAGE_B(SB_OFF(1, 1), 1, t + 3);
;       WAIT_V(6); BAR; MMA(1, 1, At, B1); BAR;
;     }
;     { LDB(B0, 0, 0); LDA(At, 0, 0); STAGE_A(SA_OFF(1, 1), 1, nt - 1);
	s_waitcnt lgkmcnt(2)
	v_mfma_f32_16x16x32_bf16 v[92:95], v[170:173], v[202:205], v[92:95]
	v_mfma_f32_16x16x32_bf16 v[88:91], v[170:173], v[210:213], v[88:91]
	v_mfma_f32_16x16x32_bf16 v[84:87], v[178:181], v[202:205], v[84:87]
	v_mfma_f32_16x16x32_bf16 v[80:83], v[178:181], v[210:213], v[80:83]
	v_mfma_f32_16x16x32_bf16 v[76:79], v[186:189], v[202:205], v[76:79]
	v_mfma_f32_16x16x32_bf16 v[72:75], v[186:189], v[210:213], v[72:75]
	v_mfma_f32_16x16x32_bf16 v[68:71], v[194:197], v[202:205], v[68:71]
	v_mfma_f32_16x16x32_bf16 v[64:67], v[194:197], v[210:213], v[64:67]
	v_mfma_f32_16x16x32_bf16 v[92:95], v[174:177], v[206:209], v[92:95]
	v_mfma_f32_16x16x32_bf16 v[88:91], v[174:177], v[214:217], v[88:91]
	v_mfma_f32_16x16x32_bf16 v[84:87], v[182:185], v[206:209], v[84:87]
	v_mfma_f32_16x16x32_bf16 v[80:83], v[182:185], v[214:217], v[80:83]
	v_mfma_f32_16x16x32_bf16 v[76:79], v[190:193], v[206:209], v[76:79]
	v_mfma_f32_16x16x32_bf16 v[72:75], v[190:193], v[214:217], v[72:75]
	v_mfma_f32_16x16x32_bf16 v[68:71], v[198:201], v[206:209], v[68:71]
	v_mfma_f32_16x16x32_bf16 v[64:67], v[198:201], v[214:217], v[64:67]
	s_barrier
	s_setprio 0
	ds_read_b128 v[170:173], v146
	ds_read_b128 v[174:177], v146 offset:1024
	ds_read_b128 v[178:181], v147
	ds_read_b128 v[182:185], v147 offset:1024
	ds_read_b128 v[186:189], v148
	ds_read_b128 v[190:193], v148 offset:1024
	s_mov_b32 m0, s20
	s_add_i32 s34, s30, 0x180
	buffer_load_dwordx4 v131, s[48:51], s34 offen lds
	s_mov_b32 m0, s21
	s_add_i32 s30, s30, 0x40180
	buffer_load_dwordx4 v131, s[48:51], s30 offen lds
	s_waitcnt vmcnt(10)
	s_setprio 1
	s_barrier
	s_waitcnt lgkmcnt(6)
	v_mfma_f32_16x16x32_bf16 v[60:63], v[218:221], v[154:157], v[60:63]
	v_mfma_f32_16x16x32_bf16 v[56:59], v[218:221], v[162:165], v[56:59]
	v_mfma_f32_16x16x32_bf16 v[52:55], v[226:229], v[154:157], v[52:55]
	v_mfma_f32_16x16x32_bf16 v[48:51], v[226:229], v[162:165], v[48:51]
	v_mfma_f32_16x16x32_bf16 v[44:47], v[238:241], v[154:157], v[44:47]
	v_mfma_f32_16x16x32_bf16 v[40:43], v[238:241], v[162:165], v[40:43]
	v_mfma_f32_16x16x32_bf16 v[36:39], v[246:249], v[154:157], v[36:39]
	v_mfma_f32_16x16x32_bf16 v[32:35], v[246:249], v[162:165], v[32:35]
	v_mfma_f32_16x16x32_bf16 v[60:63], v[222:225], v[158:161], v[60:63]
	v_mfma_f32_16x16x32_bf16 v[56:59], v[222:225], v[166:169], v[56:59]
	v_mfma_f32_16x16x32_bf16 v[52:55], v[230:233], v[158:161], v[52:55]
	v_mfma_f32_16x16x32_bf16 v[48:51], v[230:233], v[166:169], v[48:51]
	v_mfma_f32_16x16x32_bf16 v[44:47], v[242:245], v[158:161], v[44:47]
	v_mfma_f32_16x16x32_bf16 v[40:43], v[242:245], v[166:169], v[40:43]
	v_mfma_f32_16x16x32_bf16 v[36:39], v[250:253], v[158:161], v[36:39]
	v_mfma_f32_16x16x32_bf16 v[32:35], v[250:253], v[166:169], v[32:35]
	s_barrier
	s_setprio 0
	ds_read_b128 v[154:157], v145
	ds_read_b128 v[158:161], v145 offset:1024
	ds_read_b128 v[162:165], v145 offset:2048
	ds_read_b128 v[166:169], v145 offset:3072
	ds_read_b128 v[194:197], v149
	ds_read_b128 v[198:201], v149 offset:1024
	s_mov_b32 m0, s22
	s_add_i32 s30, s31, 0x2180
	buffer_load_dwordx4 v134, s[72:75], s30 offen lds
	s_mov_b32 m0, s23
	s_add_i32 s31, s31, 0x82180
	buffer_load_dwordx4 v134, s[72:75], s31 offen lds
	s_waitcnt vmcnt(6)
	s_setprio 1
	s_barrier
	v_mfma_f32_16x16x32_bf16 v[28:31], v[218:221], v[202:205], v[28:31]
	v_mfma_f32_16x16x32_bf16 v[24:27], v[218:221], v[210:213], v[24:27]
	v_mfma_f32_16x16x32_bf16 v[20:23], v[226:229], v[202:205], v[20:23]
	v_mfma_f32_16x16x32_bf16 v[16:19], v[226:229], v[210:213], v[16:19]
	v_mfma_f32_16x16x32_bf16 v[12:15], v[238:241], v[202:205], v[12:15]
	v_mfma_f32_16x16x32_bf16 v[8:11], v[238:241], v[210:213], v[8:11]
	v_mfma_f32_16x16x32_bf16 v[4:7], v[246:249], v[202:205], v[4:7]
	v_mfma_f32_16x16x32_bf16 v[0:3], v[246:249], v[210:213], v[0:3]
	v_mfma_f32_16x16x32_bf16 v[28:31], v[222:225], v[206:209], v[28:31]
	v_mfma_f32_16x16x32_bf16 v[24:27], v[222:225], v[214:217], v[24:27]
	v_mfma_f32_16x16x32_bf16 v[20:23], v[230:233], v[206:209], v[20:23]
	v_mfma_f32_16x16x32_bf16 v[16:19], v[230:233], v[214:217], v[16:19]
	v_mfma_f32_16x16x32_bf16 v[12:15], v[242:245], v[206:209], v[12:15]
	v_mfma_f32_16x16x32_bf16 v[8:11], v[242:245], v[214:217], v[8:11]
	v_mfma_f32_16x16x32_bf16 v[4:7], v[250:253], v[206:209], v[4:7]
	v_mfma_f32_16x16x32_bf16 v[0:3], v[250:253], v[214:217], v[0:3]
	s_barrier
	s_setprio 0
	s_add_i32 s28, s28, 2
	s_addk_i32 s29, 0x100
	s_cmp_lt_u32 s28, 28
	s_cbranch_scc1 .LBB0_133
	s_and_b32 s1, s1, 0x700
	s_lshl_b32 s0, s0, 11
	s_or_b32 s27, s1, s0
	s_lshl_b32 s0, s27, 12
	s_or_b32 s1, s0, 0x80f80
	s_mov_b32 m0, s24
	s_nop 0
	buffer_load_dwordx4 v131, s[48:51], s1 offen lds
	s_or_b32 s0, s0, 0xc0f80
	s_mov_b32 m0, s25
	s_nop 0
	buffer_load_dwordx4 v131, s[48:51], s0 offen lds
	s_barrier
	s_waitcnt lgkmcnt(0)
	s_setprio 1
	v_mfma_f32_16x16x32_bf16 v[124:127], v[170:173], v[154:157], v[124:127]
	v_mfma_f32_16x16x32_bf16 v[120:123], v[170:173], v[162:165], v[120:123]
	v_mfma_f32_16x16x32_bf16 v[116:119], v[178:181], v[154:157], v[116:119]
	v_mfma_f32_16x16x32_bf16 v[112:115], v[178:181], v[162:165], v[112:115]
	v_mfma_f32_16x16x32_bf16 v[108:111], v[186:189], v[154:157], v[108:111]
	v_mfma_f32_16x16x32_bf16 v[104:107], v[186:189], v[162:165], v[104:107]
	v_mfma_f32_16x16x32_bf16 v[100:103], v[194:197], v[154:157], v[100:103]
	v_mfma_f32_16x16x32_bf16 v[96:99], v[194:197], v[162:165], v[96:99]
	v_mfma_f32_16x16x32_bf16 v[124:127], v[174:177], v[158:161], v[124:127]
	v_mfma_f32_16x16x32_bf16 v[120:123], v[174:177], v[166:169], v[120:123]
	v_mfma_f32_16x16x32_bf16 v[116:119], v[182:185], v[158:161], v[116:119]
	v_mfma_f32_16x16x32_bf16 v[112:115], v[182:185], v[166:169], v[112:115]
	v_mfma_f32_16x16x32_bf16 v[108:111], v[190:193], v[158:161], v[108:111]
	v_mfma_f32_16x16x32_bf16 v[104:107], v[190:193], v[166:169], v[104:107]
	v_mfma_f32_16x16x32_bf16 v[100:103], v[198:201], v[158:161], v[100:103]
	v_mfma_f32_16x16x32_bf16 v[96:99], v[198:201], v[166:169], v[96:99]
	s_setprio 0
	s_barrier
; #define STAGE_A(POFF, h, kt) STAGE_AX(POFF, h, kt, brow)
; #define LDA(dst, b, h) _Pragma("unroll") for (int m = 0; m < 4; ++m) _Pragma("unroll") for (int k = 0; k < 2; ++k) \
;     dst[m][k] = *reinterpret_cast<const bf16x8*>((char*)SA(b, h) + lds_byte(wr * 64 + m * 16 + fr, k * 32 + fq * 8))
; #define LDB(dst, b, h) _Pragma("unroll") for (int n = 0; n < 2; ++n) _Pragma("unroll") for (int k = 0; k < 2; ++k) \
;     dst[n][k] = *reinterpret_cast<const bf16x8*>((char*)SB(b, h) + lds_byte(wc * 32 + n * 16 + fr, k * 32 + fq * 8))
; #define MMA(ai, bj, At_, Bt_) do { __builtin_amdgcn_s_setprio(1); \
;     _Pragma("unroll") for (int k = 0; k < 2; ++k) _Pragma("unroll") for (int m = 0; m < 4; ++m) _Pragma("unroll") for (int n = 0; n < 2; ++n) \
;       acc[ai][bj][m][n] = __builtin_amdgcn_mfma_f32_16x16x32_bf16(At_[m][k], Bt_[n][k], acc[ai][bj][m][n], 0, 0, 0); \
;     __builtin_amdgcn_s_setprio(0); } while (0)
; #define WAIT_V(n) asm volatile("s_waitcnt vmcnt(" #n ")" ::: "memory")
; #define BAR __builtin_amdgcn_s_barrier()
; template <int EPI, int N, int K>
; __device__ __forceinline__ void gemm_phase(const bf16_t* __restrict__ A, const bf16_t* __restrict__ Bt, const EpiArgs ea) {
;     ...
;     { LDB(B0, 0, 0); LDA(At, 0, 0); STAGE_A(SA_OFF(1, 1), 1, nt - 1);
;       BAR; WAIT_L(0); MMA(0, 0, At, B0); BAR;
;       LDB(B1, 0, 1); BAR; WAIT_L(0); MMA(0, 1, At, B1); BAR;
;       LDA(At, 0, 1); WAIT_V(4); BAR; WAIT_L(0); MMA(1, 0, At, B0); MMA(1, 1, At, B1); BAR; }
;     { LDB(B0, 1, 0); LDA(At, 1, 0); WAIT_V(2); BAR; WAIT_L(0); MMA(0, 0, At, B0); BAR;
	ds_read_b128 v[202:205], v150
	ds_read_b128 v[206:209], v150 offset:1024
	ds_read_b128 v[210:213], v150 offset:2048
	ds_read_b128 v[214:217], v150 offset:3072
	s_barrier
	s_waitcnt lgkmcnt(0)
	s_setprio 1
	v_mfma_f32_16x16x32_bf16 v[92:95], v[170:173], v[202:205], v[92:95]
	v_mfma_f32_16x16x32_bf16 v[88:91], v[170:173], v[210:213], v[88:91]
	v_mfma_f32_16x16x32_bf16 v[76:79], v[186:189], v[202:205], v[76:79]
	v_mfma_f32_16x16x32_bf16 v[72:75], v[186:189], v[210:213], v[72:75]
	v_mfma_f32_16x16x32_bf16 v[68:71], v[194:197], v[202:205], v[68:71]
	v_mfma_f32_16x16x32_bf16 v[64:67], v[194:197], v[210:213], v[64:67]
	v_mfma_f32_16x16x32_bf16 v[84:87], v[178:181], v[202:205], v[84:87]
	v_mfma_f32_16x16x32_bf16 v[80:83], v[178:181], v[210:213], v[80:83]
	v_mfma_f32_16x16x32_bf16 v[92:95], v[174:177], v[206:209], v[92:95]
	v_mfma_f32_16x16x32_bf16 v[88:91], v[174:177], v[214:217], v[88:91]
	v_mfma_f32_16x16x32_bf16 v[76:79], v[190:193], v[206:209], v[76:79]
	v_mfma_f32_16x16x32_bf16 v[72:75], v[190:193], v[214:217], v[72:75]
	v_mfma_f32_16x16x32_bf16 v[68:71], v[198:201], v[206:209], v[68:71]
	v_mfma_f32_16x16x32_bf16 v[64:67], v[198:201], v[214:217], v[64:67]
	v_mfma_f32_16x16x32_bf16 v[170:173], v[182:185], v[206:209], v[84:87]
	v_mfma_f32_16x16x32_bf16 v[174:177], v[182:185], v[214:217], v[80:83]
	s_setprio 0
	s_barrier
	s_nop 0
	ds_read_b128 v[80:83], v146 offset:16384
	ds_read_b128 v[84:87], v146 offset:17408
	ds_read_b128 v[178:181], v147 offset:16384
	ds_read_b128 v[182:185], v147 offset:17408
	ds_read_b128 v[186:189], v148 offset:16384
	ds_read_b128 v[190:193], v148 offset:17408
	ds_read_b128 v[194:197], v149 offset:16384
	ds_read_b128 v[198:201], v149 offset:17408
	s_waitcnt vmcnt(4)
	s_barrier
	s_waitcnt lgkmcnt(0)
	s_setprio 1
	v_mfma_f32_16x16x32_bf16 v[52:55], v[178:181], v[154:157], v[52:55]
	v_mfma_f32_16x16x32_bf16 v[48:51], v[178:181], v[162:165], v[48:51]
	v_mfma_f32_16x16x32_bf16 v[44:47], v[186:189], v[154:157], v[44:47]
	v_mfma_f32_16x16x32_bf16 v[40:43], v[186:189], v[162:165], v[40:43]
	v_mfma_f32_16x16x32_bf16 v[36:39], v[194:197], v[154:157], v[36:39]
	v_mfma_f32_16x16x32_bf16 v[32:35], v[194:197], v[162:165], v[32:35]
	v_mfma_f32_16x16x32_bf16 v[60:63], v[80:83], v[154:157], v[60:63]
	v_mfma_f32_16x16x32_bf16 v[56:59], v[80:83], v[162:165], v[56:59]
	v_mfma_f32_16x16x32_bf16 v[52:55], v[182:185], v[158:161], v[52:55]
	v_mfma_f32_16x16x32_bf16 v[48:51], v[182:185], v[166:169], v[48:51]
	v_mfma_f32_16x16x32_bf16 v[44:47], v[190:193], v[158:161], v[44:47]
	v_mfma_f32_16x16x32_bf16 v[40:43], v[190:193], v[166:169], v[40:43]
	v_mfma_f32_16x16x32_bf16 v[36:39], v[198:201], v[158:161], v[36:39]
	v_mfma_f32_16x16x32_bf16 v[32:35], v[198:201], v[166:169], v[32:35]
	v_mfma_f32_16x16x32_bf16 v[154:157], v[84:87], v[158:161], v[60:63]
	v_mfma_f32_16x16x32_bf16 v[162:165], v[84:87], v[166:169], v[56:59]
	s_setprio 0
	s_setprio 1
	v_mfma_f32_16x16x32_bf16 v[28:31], v[80:83], v[202:205], v[28:31]
	v_mfma_f32_16x16x32_bf16 v[24:27], v[80:83], v[210:213], v[24:27]
	v_mfma_f32_16x16x32_bf16 v[12:15], v[186:189], v[202:205], v[12:15]
	v_mfma_f32_16x16x32_bf16 v[8:11], v[186:189], v[210:213], v[8:11]
	v_mfma_f32_16x16x32_bf16 v[20:23], v[178:181], v[202:205], v[20:23]
	v_mfma_f32_16x16x32_bf16 v[16:19], v[178:181], v[210:213], v[16:19]
	v_mfma_f32_16x16x32_bf16 v[4:7], v[194:197], v[202:205], v[4:7]
	v_mfma_f32_16x16x32_bf16 v[0:3], v[194:197], v[210:213], v[0:3]
	v_mfma_f32_16x16x32_bf16 v[28:31], v[84:87], v[206:209], v[28:31]
	v_mfma_f32_16x16x32_bf16 v[24:27], v[84:87], v[214:217], v[24:27]
	v_mfma_f32_16x16x32_bf16 v[12:15], v[190:193], v[206:209], v[12:15]
	v_mfma_f32_16x16x32_bf16 v[8:11], v[190:193], v[214:217], v[8:11]
	v_mfma_f32_16x16x32_bf16 v[158:161], v[182:185], v[206:209], v[20:23]
	v_mfma_f32_16x16x32_bf16 v[166:169], v[182:185], v[214:217], v[16:19]
	v_mfma_f32_16x16x32_bf16 v[178:181], v[198:201], v[206:209], v[4:7]
	v_mfma_f32_16x16x32_bf16 v[182:185], v[198:201], v[214:217], v[0:3]
	s_setprio 0
	s_barrier
	s_nop 0
	ds_read_b128 v[0:3], v151
	ds_read_b128 v[4:7], v151 offset:1024
	ds_read_b128 v[16:19], v151 offset:2048
	ds_read_b128 v[186:189], v151 offset:3072
	ds_read_b128 v[20:23], v146 offset:32768
	ds_read_b128 v[190:193], v146 offset:33792
	ds_read_b128 v[194:197], v147 offset:32768
	ds_read_b128 v[198:201], v147 offset:33792
	ds_read_b128 v[202:205], v148 offset:32768
	ds_read_b128 v[206:209], v148 offset:33792
	ds_read_b128 v[210:213], v149 offset:32768
	ds_read_b128 v[214:217], v149 offset:33792
	s_waitcnt vmcnt(2)
	s_barrier
; #define LDA(dst, b, h) _Pragma("unroll") for (int m = 0; m < 4; ++m) _Pragma("unroll") for (int k = 0; k < 2; ++k) \
;     dst[m][k] = *reinterpret_cast<const bf16x8*>((char*)SA(b, h) + lds_byte(wr * 64 + m * 16 + fr, k * 32 + fq * 8))
; #define LDB(dst, b, h) _Pragma("unroll") for (int n = 0; n < 2; ++n) _Pragma("unroll") for (int k = 0; k < 2; ++k) \
;     dst[n][k] = *reinterpret_cast<const bf16x8*>((char*)SB(b, h) + lds_byte(wc * 32 + n * 16 + fr, k * 32 + fq * 8))
; #define MMA(ai, bj, At_, Bt_) do { __builtin_amdgcn_s_setprio(1); \
;     _Pragma("unroll") for (int k = 0; k < 2; ++k) _Pragma("unroll") for (int m = 0; m < 4; ++m) _Pragma("unroll") for (int n = 0; n < 2; ++n) \
;       acc[ai][bj][m][n] = __builtin_amdgcn_mfma_f32_16x16x32_bf16(At_[m][k], Bt_[n][k], acc[ai][bj][m][n], 0, 0, 0); \
;     __builtin_amdgcn_s_setprio(0); } while (0)
; #define WAIT_V(n) asm volatile("s_waitcnt vmcnt(" #n ")" ::: "memory")
; #define BAR __builtin_amdgcn_s_barrier()
; template <int EPI, int N, int K>
; __device__ __forceinline__ void gemm_phase(const bf16_t* __restrict__ A, const bf16_t* __restrict__ Bt, const EpiArgs ea) {
;     ...
;       LDA(At, 0, 1); WAIT_V(4); BAR; WAIT_L(0); MMA(1, 0, At, B0); MMA(1, 1, At, B1); BAR; }
;     { LDB(B0, 1, 0); LDA(At, 1, 0); WAIT_V(2); BAR; WAIT_L(0); MMA(0, 0, At, B0); BAR;
;       LDB(B1, 1, 1); WAIT_V(0); BAR; WAIT_L(0); MMA(0, 1, At, B1); BAR;
;       LDA(At, 1, 1); BAR; WAIT_L(0); MMA(1, 0, At, B0); MMA(1, 1, At, B1); BAR; }
;     if (wr == 0) BAR;
	s_waitcnt lgkmcnt(0)
	s_setprio 1
	v_mfma_f32_16x16x32_bf16 v[56:59], v[20:23], v[0:3], v[124:127]
	v_mfma_f32_16x16x32_bf16 v[60:63], v[20:23], v[16:19], v[120:123]
	v_mfma_f32_16x16x32_bf16 v[80:83], v[194:197], v[0:3], v[116:119]
	v_mfma_f32_16x16x32_bf16 v[84:87], v[194:197], v[16:19], v[112:115]
	v_mfma_f32_16x16x32_bf16 v[108:111], v[202:205], v[0:3], v[108:111]
	v_mfma_f32_16x16x32_bf16 v[104:107], v[202:205], v[16:19], v[104:107]
	v_mfma_f32_16x16x32_bf16 v[120:123], v[210:213], v[0:3], v[100:103]
	v_mfma_f32_16x16x32_bf16 v[124:127], v[210:213], v[16:19], v[96:99]
	v_mfma_f32_16x16x32_bf16 v[116:119], v[190:193], v[4:7], v[56:59]
	v_mfma_f32_16x16x32_bf16 v[112:115], v[190:193], v[186:189], v[60:63]
	v_mfma_f32_16x16x32_bf16 v[100:103], v[198:201], v[4:7], v[80:83]
	v_mfma_f32_16x16x32_bf16 v[96:99], v[198:201], v[186:189], v[84:87]
	v_mfma_f32_16x16x32_bf16 v[84:87], v[206:209], v[4:7], v[108:111]
	v_mfma_f32_16x16x32_bf16 v[80:83], v[206:209], v[186:189], v[104:107]
	v_mfma_f32_16x16x32_bf16 v[60:63], v[214:217], v[4:7], v[120:123]
	v_mfma_f32_16x16x32_bf16 v[56:59], v[214:217], v[186:189], v[124:127]
	s_setprio 0
	s_barrier
	ds_read_b128 v[218:221], v152
	ds_read_b128 v[222:225], v152 offset:1024
	ds_read_b128 v[226:229], v152 offset:2048
	ds_read_b128 v[230:233], v152 offset:3072
	s_waitcnt vmcnt(0)
	s_barrier
	s_waitcnt lgkmcnt(0)
	s_setprio 1
	v_mfma_f32_16x16x32_bf16 v[92:95], v[20:23], v[218:221], v[92:95]
	v_mfma_f32_16x16x32_bf16 v[20:23], v[20:23], v[226:229], v[88:91]
	v_mfma_f32_16x16x32_bf16 v[88:91], v[194:197], v[218:221], v[170:173]
	v_mfma_f32_16x16x32_bf16 v[104:107], v[194:197], v[226:229], v[174:177]
	v_mfma_f32_16x16x32_bf16 v[76:79], v[202:205], v[218:221], v[76:79]
	v_mfma_f32_16x16x32_bf16 v[72:75], v[202:205], v[226:229], v[72:75]
	v_mfma_f32_16x16x32_bf16 v[68:71], v[210:213], v[218:221], v[68:71]
	v_mfma_f32_16x16x32_bf16 v[64:67], v[210:213], v[226:229], v[64:67]
	v_mfma_f32_16x16x32_bf16 v[124:127], v[190:193], v[222:225], v[92:95]
	v_mfma_f32_16x16x32_bf16 v[120:123], v[190:193], v[230:233], v[20:23]
	v_mfma_f32_16x16x32_bf16 v[108:111], v[198:201], v[222:225], v[88:91]
	v_mfma_f32_16x16x32_bf16 v[104:107], v[198:201], v[230:233], v[104:107]
	v_mfma_f32_16x16x32_bf16 v[92:95], v[206:209], v[222:225], v[76:79]
	v_mfma_f32_16x16x32_bf16 v[88:91], v[206:209], v[230:233], v[72:75]
	v_mfma_f32_16x16x32_bf16 v[76:79], v[214:217], v[222:225], v[68:71]
	v_mfma_f32_16x16x32_bf16 v[72:75], v[214:217], v[230:233], v[64:67]
	s_setprio 0
	s_barrier
	s_nop 0
	ds_read_b128 v[64:67], v146 offset:49152
	ds_read_b128 v[170:173], v146 offset:50176
	ds_read_b128 v[68:71], v147 offset:49152
	ds_read_b128 v[174:177], v147 offset:50176
	ds_read_b128 v[190:193], v148 offset:49152
	ds_read_b128 v[194:197], v148 offset:50176
	ds_read_b128 v[198:201], v149 offset:49152
	ds_read_b128 v[202:205], v149 offset:50176
	s_barrier
	s_waitcnt lgkmcnt(0)
	s_setprio 1
	v_mfma_f32_16x16x32_bf16 v[20:23], v[64:67], v[0:3], v[154:157]
	v_mfma_f32_16x16x32_bf16 v[154:157], v[64:67], v[16:19], v[162:165]
	v_mfma_f32_16x16x32_bf16 v[162:165], v[68:71], v[0:3], v[52:55]
	v_mfma_f32_16x16x32_bf16 v[206:209], v[68:71], v[16:19], v[48:51]
	v_mfma_f32_16x16x32_bf16 v[44:47], v[190:193], v[0:3], v[44:47]
	v_mfma_f32_16x16x32_bf16 v[40:43], v[190:193], v[16:19], v[40:43]
	v_mfma_f32_16x16x32_bf16 v[0:3], v[198:201], v[0:3], v[36:39]
	v_mfma_f32_16x16x32_bf16 v[210:213], v[198:201], v[16:19], v[32:35]
	v_mfma_f32_16x16x32_bf16 v[52:55], v[170:173], v[4:7], v[20:23]
	v_mfma_f32_16x16x32_bf16 v[48:51], v[170:173], v[186:189], v[154:157]
	v_mfma_f32_16x16x32_bf16 v[36:39], v[174:177], v[4:7], v[162:165]
	v_mfma_f32_16x16x32_bf16 v[32:35], v[174:177], v[186:189], v[206:209]
	v_mfma_f32_16x16x32_bf16 v[20:23], v[194:197], v[4:7], v[44:47]
	v_mfma_f32_16x16x32_bf16 v[16:19], v[194:197], v[186:189], v[40:43]
	v_mfma_f32_16x16x32_bf16 v[4:7], v[202:205], v[4:7], v[0:3]
	v_mfma_f32_16x16x32_bf16 v[0:3], v[202:205], v[186:189], v[210:213]
	s_setprio 0
	s_setprio 1
	v_mfma_f32_16x16x32_bf16 v[28:31], v[64:67], v[218:221], v[28:31]
	v_mfma_f32_16x16x32_bf16 v[24:27], v[64:67], v[226:229], v[24:27]
	v_mfma_f32_16x16x32_bf16 v[40:43], v[68:71], v[218:221], v[158:161]
	v_mfma_f32_16x16x32_bf16 v[154:157], v[68:71], v[226:229], v[166:169]
	v_mfma_f32_16x16x32_bf16 v[12:15], v[190:193], v[218:221], v[12:15]
	v_mfma_f32_16x16x32_bf16 v[8:11], v[190:193], v[226:229], v[8:11]
	v_mfma_f32_16x16x32_bf16 v[158:161], v[198:201], v[218:221], v[178:181]
	v_mfma_f32_16x16x32_bf16 v[162:165], v[198:201], v[226:229], v[182:185]
	v_mfma_f32_16x16x32_bf16 v[68:71], v[170:173], v[222:225], v[28:31]
	v_mfma_f32_16x16x32_bf16 v[64:67], v[170:173], v[230:233], v[24:27]
	v_mfma_f32_16x16x32_bf16 v[44:47], v[174:177], v[222:225], v[40:43]
	v_mfma_f32_16x16x32_bf16 v[40:43], v[174:177], v[230:233], v[154:157]
	v_mfma_f32_16x16x32_bf16 v[28:31], v[194:197], v[222:225], v[12:15]
	v_mfma_f32_16x16x32_bf16 v[24:27], v[194:197], v[230:233], v[8:11]
	v_mfma_f32_16x16x32_bf16 v[12:15], v[202:205], v[222:225], v[158:161]
	v_mfma_f32_16x16x32_bf16 v[8:11], v[202:205], v[230:233], v[162:165]
	s_setprio 0
	s_barrier
	s_and_saveexec_b64 s[0:1], s[6:7]
	s_cbranch_execz .LBB0_136
	s_barrier

; #define STAGE_A(POFF, h, kt) STAGE_AX(POFF, h, kt, brow)
; #define STAGE_B(POFF, h, kt) STAGE_BX(POFF, h, kt, bcol)
; #define LDA(dst, b, h) _Pragma("unroll") for (int m = 0; m < 4; ++m) _Pragma("unroll") for (int k = 0; k < 2; ++k) \
;     dst[m][k] = *reinterpret_cast<const bf16x8*>((char*)SA(b, h) + lds_byte(wr * 64 + m * 16 + fr, k * 32 + fq * 8))
; #define LDB(dst, b, h) _Pragma("unroll") for (int n = 0; n < 2; ++n) _Pragma("unroll") for (int k = 0; k < 2; ++k) \
;     dst[n][k] = *reinterpret_cast<const bf16x8*>((char*)SB(b, h) + lds_byte(wc * 32 + n * 16 + fr, k * 32 + fq * 8))
; #define MMA(ai, bj, At_, Bt_) do { __builtin_amdgcn_s_setprio(1); \
;     _Pragma("unroll") for (int k = 0; k < 2; ++k) _Pragma("unroll") for (int m = 0; m < 4; ++m) _Pragma("unroll") for (int n = 0; n < 2; ++n) \
;       acc[ai][bj][m][n] = __builtin_amdgcn_mfma_f32_16x16x32_bf16(At_[m][k], Bt_[n][k], acc[ai][bj][m][n], 0, 0, 0); \
;     __builtin_amdgcn_s_setprio(0); } while (0)
; #define WAIT_V(n) asm volatile("s_waitcnt vmcnt(" #n ")" ::: "memory")
; #define BAR __builtin_amdgcn_s_barrier()
; #define SCHED __builtin_amdgcn_sched_barrier(0)
; template <int EPI, int N, int K>
; __device__ __forceinline__ void gemm_phase(const bf16_t* __restrict__ A, const bf16_t* __restrict__ Bt, const EpiArgs ea) {
;     ...
;     int brow, bcol; TILE_RC(w, brow, bcol);
;     f32x4 acc[2][2][4][2];
; #pragma unroll
;     for (int a = 0; a < 2; ++a)
; #pragma unroll
;       for (int b = 0; b < 2; ++b)
; #pragma unroll
;         for (int m = 0; m < 4; ++m)
; #pragma unroll
;           for (int n = 0; n < 2; ++n) acc[a][b][m][n] = (f32x4){0.f, 0.f, 0.f, 0.f};
;     bf16x8 At[4][2], B0[2][2], B1[2][2];
;     if (wr == 1) BAR;
;     if (w == (int)blockIdx.x) { WAIT_V(0); } else { WAIT_V(24); }
;     BAR;
;     BAR;
;     for (int t = 0; t < nt - 2; t += 2) {
;       LDB(B0, 0, 0); SCHED; LDA(At, 0, 0); STAGE_A(SA_OFF(1, 1), 1, t + 1);
;       WAIT_L(8); BAR; WAIT_L(0); MMA(0, 0, At, B0); BAR; SCHED;
;       LDB(B1, 0, 1); STAGE_B(SB_OFF(0, 0), 0, t + 2);
;       BAR; WAIT_L(0); MMA(0, 1, At, B1); BAR;
;       LDA(At, 0, 1); STAGE_A(SA_OFF(0, 0), 0, t + 2);
;       BAR; WAIT_L(0); MMA(1, 0, At, B0); BAR; SCHED;
;       STAGE_B(SB_OFF(0, 1), 1, t + 2);
;       WAIT_V(6); BAR; MMA(1, 1, At, B1); BAR;
.LBB0_269:
	s_and_b32 s0, s26, 7
	s_mulk_i32 s0, 0x50
	s_ashr_i32 s1, s26, 3
	s_add_i32 s1, s0, s1
	s_mul_hi_i32 s0, s1, 0x66666667
	s_lshr_b32 s2, s0, 31
	s_ashr_i32 s0, s0, 5
	s_add_i32 s0, s0, s2
	s_mul_i32 s2, s0, 0x50
	s_sub_i32 s27, s1, s2
	s_lshl_b32 s1, s27, 8
	s_lshl_b32 s2, s27, 5
	s_lshl_b32 s3, s27, 17
	s_and_b32 s27, s27, 7
	s_lshl_b32 s28, s0, 23
	s_lshl_b32 s27, s27, 20
	s_barrier
	s_barrier
	s_and_b32 s3, s3, 0xfff00000
	s_or_b32 s27, s28, s27
	s_mov_b32 s28, -2
	s_mov_b32 s29, 0
	ds_read_b128 v[154:157], v145
	ds_read_b128 v[158:161], v145 offset:1024
	ds_read_b128 v[162:165], v145 offset:2048
	ds_read_b128 v[166:169], v145 offset:3072
	ds_read_b128 v[170:173], v146
	ds_read_b128 v[174:177], v146 offset:1024
	ds_read_b128 v[178:181], v147
	ds_read_b128 v[182:185], v147 offset:1024
	ds_read_b128 v[186:189], v148
	ds_read_b128 v[190:193], v148 offset:1024
	ds_read_b128 v[194:197], v149
	ds_read_b128 v[198:201], v149 offset:1024
	ds_read_b128 v[218:221], v146 offset:16384
	ds_read_b128 v[222:225], v146 offset:17408
	ds_read_b128 v[226:229], v147 offset:16384
	ds_read_b128 v[230:233], v147 offset:17408
	ds_read_b128 v[238:241], v148 offset:16384
	ds_read_b128 v[242:245], v148 offset:17408
	s_add_i32 s30, s27, s29
	s_mov_b32 m0, s24
	s_or_b32 s31, s30, 0x80080
	buffer_load_dwordx4 v131, s[48:51], s31 offen lds
	s_mov_b32 m0, s25
	s_or_b32 s31, s30, 0xc0080
	buffer_load_dwordx4 v131, s[48:51], s31 offen lds
	s_setprio 1
	s_barrier
	s_waitcnt lgkmcnt(6)
	v_mfma_f32_16x16x32_bf16 v[124:127], v[170:173], v[154:157], 0
	v_mfma_f32_16x16x32_bf16 v[120:123], v[170:173], v[162:165], 0
	v_mfma_f32_16x16x32_bf16 v[116:119], v[178:181], v[154:157], 0
	v_mfma_f32_16x16x32_bf16 v[112:115], v[178:181], v[162:165], 0
	v_mfma_f32_16x16x32_bf16 v[108:111], v[186:189], v[154:157], 0
	v_mfma_f32_16x16x32_bf16 v[104:107], v[186:189], v[162:165], 0
	v_mfma_f32_16x16x32_bf16 v[100:103], v[194:197], v[154:157], 0
	v_mfma_f32_16x16x32_bf16 v[96:99], v[194:197], v[162:165], 0
	v_mfma_f32_16x16x32_bf16 v[124:127], v[174:177], v[158:161], v[124:127]
	v_mfma_f32_16x16x32_bf16 v[120:123], v[174:177], v[166:169], v[120:123]
	v_mfma_f32_16x16x32_bf16 v[116:119], v[182:185], v[158:161], v[116:119]
	v_mfma_f32_16x16x32_bf16 v[112:115], v[182:185], v[166:169], v[112:115]
	v_mfma_f32_16x16x32_bf16 v[108:111], v[190:193], v[158:161], v[108:111]
	v_mfma_f32_16x16x32_bf16 v[104:107], v[190:193], v[166:169], v[104:107]
	v_mfma_f32_16x16x32_bf16 v[100:103], v[198:201], v[158:161], v[100:103]
	v_mfma_f32_16x16x32_bf16 v[96:99], v[198:201], v[166:169], v[96:99]
	s_barrier
	s_setprio 0
	ds_read_b128 v[202:205], v150
	ds_read_b128 v[206:209], v150 offset:1024
	ds_read_b128 v[210:213], v150 offset:2048
	ds_read_b128 v[214:217], v150 offset:3072
	ds_read_b128 v[246:249], v149 offset:16384
	ds_read_b128 v[250:253], v149 offset:17408
	s_add_i32 s31, s3, s29
	s_mov_b32 m0, s11
	s_add_i32 s34, s31, 0x100
	buffer_load_dwordx4 v134, s[56:59], s34 offen lds
	s_mov_b32 m0, s12
	s_add_i32 s34, s31, 0x80100
	buffer_load_dwordx4 v134, s[56:59], s34 offen lds
	s_waitcnt vmcnt(6)
	s_setprio 1
	s_barrier
	s_waitcnt lgkmcnt(2)
	v_mfma_f32_16x16x32_bf16 v[92:95], v[170:173], v[202:205], 0
	v_mfma_f32_16x16x32_bf16 v[88:91], v[170:173], v[210:213], 0
	v_mfma_f32_16x16x32_bf16 v[84:87], v[178:181], v[202:205], 0
	v_mfma_f32_16x16x32_bf16 v[80:83], v[178:181], v[210:213], 0
	v_mfma_f32_16x16x32_bf16 v[76:79], v[186:189], v[202:205], 0
	v_mfma_f32_16x16x32_bf16 v[72:75], v[186:189], v[210:213], 0
	v_mfma_f32_16x16x32_bf16 v[68:71], v[194:197], v[202:205], 0
	v_mfma_f32_16x16x32_bf16 v[64:67], v[194:197], v[210:213], 0
	v_mfma_f32_16x16x32_bf16 v[92:95], v[174:177], v[206:209], v[92:95]
	v_mfma_f32_16x16x32_bf16 v[88:91], v[174:177], v[214:217], v[88:91]
	v_mfma_f32_16x16x32_bf16 v[84:87], v[182:185], v[206:209], v[84:87]
	v_mfma_f32_16x16x32_bf16 v[80:83], v[182:185], v[214:217], v[80:83]
	v_mfma_f32_16x16x32_bf16 v[76:79], v[190:193], v[206:209], v[76:79]
	v_mfma_f32_16x16x32_bf16 v[72:75], v[190:193], v[214:217], v[72:75]
	v_mfma_f32_16x16x32_bf16 v[68:71], v[198:201], v[206:209], v[68:71]
	v_mfma_f32_16x16x32_bf16 v[64:67], v[198:201], v[214:217], v[64:67]
	s_barrier
	s_setprio 0
	ds_read_b128 v[170:173], v146 offset:32768
	ds_read_b128 v[174:177], v146 offset:33792
	ds_read_b128 v[178:181], v147 offset:32768
	ds_read_b128 v[182:185], v147 offset:33792
	ds_read_b128 v[186:189], v148 offset:32768
	ds_read_b128 v[190:193], v148 offset:33792
	s_mov_b32 m0, s10
	s_add_i32 s34, s30, 0x100
	buffer_load_dwordx4 v131, s[48:51], s34 offen lds
	s_mov_b32 m0, s13
	s_add_i32 s35, s30, 0x40100
	buffer_load_dwordx4 v131, s[48:51], s35 offen lds
	s_waitcnt vmcnt(10)
	s_setprio 1
	s_barrier
	s_waitcnt lgkmcnt(6)
	v_mfma_f32_16x16x32_bf16 v[60:63], v[218:221], v[154:157], 0
	v_mfma_f32_16x16x32_bf16 v[56:59], v[218:221], v[162:165], 0
	v_mfma_f32_16x16x32_bf16 v[52:55], v[226:229], v[154:157], 0
	v_mfma_f32_16x16x32_bf16 v[48:51], v[226:229], v[162:165], 0
	v_mfma_f32_16x16x32_bf16 v[44:47], v[238:241], v[154:157], 0
	v_mfma_f32_16x16x32_bf16 v[40:43], v[238:241], v[162:165], 0
	v_mfma_f32_16x16x32_bf16 v[36:39], v[246:249], v[154:157], 0
	v_mfma_f32_16x16x32_bf16 v[32:35], v[246:249], v[162:165], 0
	v_mfma_f32_16x16x32_bf16 v[60:63], v[222:225], v[158:161], v[60:63]
	v_mfma_f32_16x16x32_bf16 v[56:59], v[222:225], v[166:169], v[56:59]
	v_mfma_f32_16x16x32_bf16 v[52:55], v[230:233], v[158:161], v[52:55]
	v_mfma_f32_16x16x32_bf16 v[48:51], v[230:233], v[166:169], v[48:51]
	v_mfma_f32_16x16x32_bf16 v[44:47], v[242:245], v[158:161], v[44:47]
	v_mfma_f32_16x16x32_bf16 v[40:43], v[242:245], v[166:169], v[40:43]
	v_mfma_f32_16x16x32_bf16 v[36:39], v[250:253], v[158:161], v[36:39]
	v_mfma_f32_16x16x32_bf16 v[32:35], v[250:253], v[166:169], v[32:35]
	s_barrier
; #define STAGE_A(POFF, h, kt) STAGE_AX(POFF, h, kt, brow)
; #define STAGE_B(POFF, h, kt) STAGE_BX(POFF, h, kt, bcol)
; #define LDA(dst, b, h) _Pragma("unroll") for (int m = 0; m < 4; ++m) _Pragma("unroll") for (int k = 0; k < 2; ++k) \
;     dst[m][k] = *reinterpret_cast<const bf16x8*>((char*)SA(b, h) + lds_byte(wr * 64 + m * 16 + fr, k * 32 + fq * 8))
; #define LDB(dst, b, h) _Pragma("unroll") for (int n = 0; n < 2; ++n) _Pragma("unroll") for (int k = 0; k < 2; ++k) \
;     dst[n][k] = *reinterpret_cast<const bf16x8*>((char*)SB(b, h) + lds_byte(wc * 32 + n * 16 + fr, k * 32 + fq * 8))
; #define MMA(ai, bj, At_, Bt_) do { __builtin_amdgcn_s_setprio(1); \
;     _Pragma("unroll") for (int k = 0; k < 2; ++k) _Pragma("unroll") for (int m = 0; m < 4; ++m) _Pragma("unroll") for (int n = 0; n < 2; ++n) \
;       acc[ai][bj][m][n] = __builtin_amdgcn_mfma_f32_16x16x32_bf16(At_[m][k], Bt_[n][k], acc[ai][bj][m][n], 0, 0, 0); \
;     __builtin_amdgcn_s_setprio(0); } while (0)
; #define WAIT_V(n) asm volatile("s_waitcnt vmcnt(" #n ")" ::: "memory")
; #define BAR __builtin_amdgcn_s_barrier()
; #define SCHED __builtin_amdgcn_sched_barrier(0)
; template <int EPI, int N, int K>
; __device__ __forceinline__ void gemm_phase(const bf16_t* __restrict__ A, const bf16_t* __restrict__ Bt, const EpiArgs ea) {
;     ...
;       BAR; WAIT_L(0); MMA(1, 0, At, B0); BAR; SCHED;
;       STAGE_B(SB_OFF(0, 1), 1, t + 2);
;       WAIT_V(6); BAR; MMA(1, 1, At, B1); BAR;
;       LDB(B0, 1, 0); SCHED; LDA(At, 1, 0); STAGE_A(SA_OFF(0, 1), 1, t + 2);
;       WAIT_L(8); BAR; WAIT_L(0); MMA(0, 0, At, B0); BAR; SCHED;
;       LDB(B1, 1, 1); STAGE_B(SB_OFF(1, 0), 0, t + 3);
;       BAR; WAIT_L(0); MMA(0, 1, At, B1); BAR;
;       LDA(At, 1, 1); STAGE_A(SA_OFF(1, 0), 0, t + 3);
;       BAR; WAIT_L(0); MMA(1, 0, At, B0); BAR; SCHED;
	s_setprio 0
	ds_read_b128 v[154:157], v151
	ds_read_b128 v[158:161], v151 offset:1024
	ds_read_b128 v[162:165], v151 offset:2048
	ds_read_b128 v[166:169], v151 offset:3072
	ds_read_b128 v[194:197], v149 offset:32768
	ds_read_b128 v[198:201], v149 offset:33792
	s_mov_b32 m0, s14
	s_add_i32 s35, s31, 0x2100
	buffer_load_dwordx4 v134, s[56:59], s35 offen lds
	s_mov_b32 m0, s15
	s_add_i32 s35, s31, 0x82100
	buffer_load_dwordx4 v134, s[56:59], s35 offen lds
	s_waitcnt vmcnt(6)
	s_setprio 1
	s_barrier
	v_mfma_f32_16x16x32_bf16 v[28:31], v[218:221], v[202:205], 0
	v_mfma_f32_16x16x32_bf16 v[24:27], v[218:221], v[210:213], 0
	v_mfma_f32_16x16x32_bf16 v[20:23], v[226:229], v[202:205], 0
	v_mfma_f32_16x16x32_bf16 v[16:19], v[226:229], v[210:213], 0
	v_mfma_f32_16x16x32_bf16 v[12:15], v[238:241], v[202:205], 0
	v_mfma_f32_16x16x32_bf16 v[8:11], v[238:241], v[210:213], 0
	v_mfma_f32_16x16x32_bf16 v[4:7], v[246:249], v[202:205], 0
	v_mfma_f32_16x16x32_bf16 v[0:3], v[246:249], v[210:213], 0
	v_mfma_f32_16x16x32_bf16 v[28:31], v[222:225], v[206:209], v[28:31]
	v_mfma_f32_16x16x32_bf16 v[24:27], v[222:225], v[214:217], v[24:27]
	v_mfma_f32_16x16x32_bf16 v[20:23], v[230:233], v[206:209], v[20:23]
	v_mfma_f32_16x16x32_bf16 v[16:19], v[230:233], v[214:217], v[16:19]
	v_mfma_f32_16x16x32_bf16 v[12:15], v[242:245], v[206:209], v[12:15]
	v_mfma_f32_16x16x32_bf16 v[8:11], v[242:245], v[214:217], v[8:11]
	v_mfma_f32_16x16x32_bf16 v[4:7], v[250:253], v[206:209], v[4:7]
	v_mfma_f32_16x16x32_bf16 v[0:3], v[250:253], v[214:217], v[0:3]
	s_barrier
	s_setprio 0
	ds_read_b128 v[218:221], v146 offset:49152
	ds_read_b128 v[222:225], v146 offset:50176
	ds_read_b128 v[226:229], v147 offset:49152
	ds_read_b128 v[230:233], v147 offset:50176
	ds_read_b128 v[238:241], v148 offset:49152
	ds_read_b128 v[242:245], v148 offset:50176
	s_mov_b32 m0, s16
	s_or_b32 s35, s34, 0x80000
	buffer_load_dwordx4 v131, s[48:51], s35 offen lds
	s_mov_b32 m0, s17
	s_or_b32 s34, s34, 0xc0000
	buffer_load_dwordx4 v131, s[48:51], s34 offen lds
	s_setprio 1
	s_barrier
	s_waitcnt lgkmcnt(6)
	v_mfma_f32_16x16x32_bf16 v[124:127], v[170:173], v[154:157], v[124:127]
	v_mfma_f32_16x16x32_bf16 v[120:123], v[170:173], v[162:165], v[120:123]
	v_mfma_f32_16x16x32_bf16 v[116:119], v[178:181], v[154:157], v[116:119]
	v_mfma_f32_16x16x32_bf16 v[112:115], v[178:181], v[162:165], v[112:115]
	v_mfma_f32_16x16x32_bf16 v[108:111], v[186:189], v[154:157], v[108:111]
	v_mfma_f32_16x16x32_bf16 v[104:107], v[186:189], v[162:165], v[104:107]
	v_mfma_f32_16x16x32_bf16 v[100:103], v[194:197], v[154:157], v[100:103]
	v_mfma_f32_16x16x32_bf16 v[96:99], v[194:197], v[162:165], v[96:99]
	v_mfma_f32_16x16x32_bf16 v[124:127], v[174:177], v[158:161], v[124:127]
	v_mfma_f32_16x16x32_bf16 v[120:123], v[174:177], v[166:169], v[120:123]
	v_mfma_f32_16x16x32_bf16 v[116:119], v[182:185], v[158:161], v[116:119]
	v_mfma_f32_16x16x32_bf16 v[112:115], v[182:185], v[166:169], v[112:115]
	v_mfma_f32_16x16x32_bf16 v[108:111], v[190:193], v[158:161], v[108:111]
	v_mfma_f32_16x16x32_bf16 v[104:107], v[190:193], v[166:169], v[104:107]
	v_mfma_f32_16x16x32_bf16 v[100:103], v[198:201], v[158:161], v[100:103]
	v_mfma_f32_16x16x32_bf16 v[96:99], v[198:201], v[166:169], v[96:99]
	s_barrier
	s_setprio 0
	ds_read_b128 v[202:205], v152
	ds_read_b128 v[206:209], v152 offset:1024
	ds_read_b128 v[210:213], v152 offset:2048
	ds_read_b128 v[214:217], v152 offset:3072
	ds_read_b128 v[246:249], v149 offset:49152
	ds_read_b128 v[250:253], v149 offset:50176
	s_mov_b32 m0, s18
	s_add_i32 s34, s31, 0x180
	buffer_load_dwordx4 v134, s[56:59], s34 offen lds
	s_mov_b32 m0, s19
	s_add_i32 s34, s31, 0x80180
	buffer_load_dwordx4 v134, s[56:59], s34 offen lds
	s_waitcnt vmcnt(6)
	s_setprio 1
	s_barrier
	s_waitcnt lgkmcnt(2)
	v_mfma_f32_16x16x32_bf16 v[92:95], v[170:173], v[202:205], v[92:95]
	v_mfma_f32_16x16x32_bf16 v[88:91], v[170:173], v[210:213], v[88:91]
	v_mfma_f32_16x16x32_bf16 v[84:87], v[178:181], v[202:205], v[84:87]
	v_mfma_f32_16x16x32_bf16 v[80:83], v[178:181], v[210:213], v[80:83]
	v_mfma_f32_16x16x32_bf16 v[76:79], v[186:189], v[202:205], v[76:79]
	v_mfma_f32_16x16x32_bf16 v[72:75], v[186:189], v[210:213], v[72:75]
	v_mfma_f32_16x16x32_bf16 v[68:71], v[194:197], v[202:205], v[68:71]
	v_mfma_f32_16x16x32_bf16 v[64:67], v[194:197], v[210:213], v[64:67]
	v_mfma_f32_16x16x32_bf16 v[92:95], v[174:177], v[206:209], v[92:95]
	v_mfma_f32_16x16x32_bf16 v[88:91], v[174:177], v[214:217], v[88:91]
	v_mfma_f32_16x16x32_bf16 v[84:87], v[182:185], v[206:209], v[84:87]
	v_mfma_f32_16x16x32_bf16 v[80:83], v[182:185], v[214:217], v[80:83]
	v_mfma_f32_16x16x32_bf16 v[76:79], v[190:193], v[206:209], v[76:79]
	v_mfma_f32_16x16x32_bf16 v[72:75], v[190:193], v[214:217], v[72:75]
	v_mfma_f32_16x16x32_bf16 v[68:71], v[198:201], v[206:209], v[68:71]
	v_mfma_f32_16x16x32_bf16 v[64:67], v[198:201], v[214:217], v[64:67]
	s_barrier
	s_setprio 0
	ds_read_b128 v[170:173], v146
	ds_read_b128 v[174:177], v146 offset:1024
	ds_read_b128 v[178:181], v147
	ds_read_b128 v[182:185], v147 offset:1024
	ds_read_b128 v[186:189], v148
	ds_read_b128 v[190:193], v148 offset:1024
	s_mov_b32 m0, s20
	s_add_i32 s34, s30, 0x180
	buffer_load_dwordx4 v131, s[48:51], s34 offen lds
	s_mov_b32 m0, s21
	s_add_i32 s30, s30, 0x40180
	buffer_load_dwordx4 v131, s[48:51], s30 offen lds
	s_waitcnt vmcnt(10)
	s_setprio 1
	s_barrier
; #define STAGE_A(POFF, h, kt) STAGE_AX(POFF, h, kt, brow)
; #define STAGE_B(POFF, h, kt) STAGE_BX(POFF, h, kt, bcol)
; #define LDA(dst, b, h) _Pragma("unroll") for (int m = 0; m < 4; ++m) _Pragma("unroll") for (int k = 0; k < 2; ++k) \
;     dst[m][k] = *reinterpret_cast<const bf16x8*>((char*)SA(b, h) + lds_byte(wr * 64 + m * 16 + fr, k * 32 + fq * 8))
; #define LDB(dst, b, h) _Pragma("unroll") for (int n = 0; n < 2; ++n) _Pragma("unroll") for (int k = 0; k < 2; ++k) \
;     dst[n][k] = *reinterpret_cast<const bf16x8*>((char*)SB(b, h) + lds_byte(wc * 32 + n * 16 + fr, k * 32 + fq * 8))
; #define MMA(ai, bj, At_, Bt_) do { __builtin_amdgcn_s_setprio(1); \
;     _Pragma("unroll") for (int k = 0; k < 2; ++k) _Pragma("unroll") for (int m = 0; m < 4; ++m) _Pragma("unroll") for (int n = 0; n < 2; ++n) \
;       acc[ai][bj][m][n] = __builtin_amdgcn_mfma_f32_16x16x32_bf16(At_[m][k], Bt_[n][k], acc[ai][bj][m][n], 0, 0, 0); \
;     __builtin_amdgcn_s_setprio(0); } while (0)
; #define WAIT_V(n) asm volatile("s_waitcnt vmcnt(" #n ")" ::: "memory")
; #define BAR __builtin_amdgcn_s_barrier()
; #define SCHED __builtin_amdgcn_sched_barrier(0)
; template <int EPI, int N, int K>
; __device__ __forceinline__ void gemm_phase(const bf16_t* __restrict__ A, const bf16_t* __restrict__ Bt, const EpiArgs ea) {
;     ...
;       LDB(B0, 0, 0); SCHED; LDA(At, 0, 0); STAGE_A(SA_OFF(1, 1), 1, t + 1);
;       WAIT_L(8); BAR; WAIT_L(0); MMA(0, 0, At, B0); BAR; SCHED;
;       LDB(B1, 0, 1); STAGE_B(SB_OFF(0, 0), 0, t + 2);
;       BAR; WAIT_L(0); MMA(0, 1, At, B1); BAR;
;       LDA(At, 0, 1); STAGE_A(SA_OFF(0, 0), 0, t + 2);
;       BAR; WAIT_L(0); MMA(1, 0, At, B0); BAR; SCHED;
;       STAGE_B(SB_OFF(0, 1), 1, t + 2);
;       WAIT_V(6); BAR; MMA(1, 1, At, B1); BAR;
;       LDB(B0, 1, 0); SCHED; LDA(At, 1, 0); STAGE_A(SA_OFF(0, 1), 1, t + 2);
;       WAIT_L(8); BAR; WAIT_L(0); MMA(0, 0, At, B0); BAR; SCHED;
;       LDB(B1, 1, 1); STAGE_B(SB_OFF(1, 0), 0, t + 3);
;       BAR; WAIT_L(0); MMA(0, 1, At, B1); BAR;
;       LDA(At, 1, 1); STAGE_A(SA_OFF(1, 0), 0, t + 3);
;       BAR; WAIT_L(0); MMA(1, 0, At, B0); BAR; SCHED;
;       STAGE_B(SB_OFF(1, 1), 1, t + 3);
;       WAIT_V(6); BAR; MMA(1, 1, At, B1); BAR;
	s_waitcnt lgkmcnt(6)
	v_mfma_f32_16x16x32_bf16 v[60:63], v[218:221], v[154:157], v[60:63]
	v_mfma_f32_16x16x32_bf16 v[56:59], v[218:221], v[162:165], v[56:59]
	v_mfma_f32_16x16x32_bf16 v[52:55], v[226:229], v[154:157], v[52:55]
	v_mfma_f32_16x16x32_bf16 v[48:51], v[226:229], v[162:165], v[48:51]
	v_mfma_f32_16x16x32_bf16 v[44:47], v[238:241], v[154:157], v[44:47]
	v_mfma_f32_16x16x32_bf16 v[40:43], v[238:241], v[162:165], v[40:43]
	v_mfma_f32_16x16x32_bf16 v[36:39], v[246:249], v[154:157], v[36:39]
	v_mfma_f32_16x16x32_bf16 v[32:35], v[246:249], v[162:165], v[32:35]
	v_mfma_f32_16x16x32_bf16 v[60:63], v[222:225], v[158:161], v[60:63]
	v_mfma_f32_16x16x32_bf16 v[56:59], v[222:225], v[166:169], v[56:59]
	v_mfma_f32_16x16x32_bf16 v[52:55], v[230:233], v[158:161], v[52:55]
	v_mfma_f32_16x16x32_bf16 v[48:51], v[230:233], v[166:169], v[48:51]
	v_mfma_f32_16x16x32_bf16 v[44:47], v[242:245], v[158:161], v[44:47]
	v_mfma_f32_16x16x32_bf16 v[40:43], v[242:245], v[166:169], v[40:43]
	v_mfma_f32_16x16x32_bf16 v[36:39], v[250:253], v[158:161], v[36:39]
	v_mfma_f32_16x16x32_bf16 v[32:35], v[250:253], v[166:169], v[32:35]
	s_barrier
	s_setprio 0
	ds_read_b128 v[154:157], v145
	ds_read_b128 v[158:161], v145 offset:1024
	ds_read_b128 v[162:165], v145 offset:2048
	ds_read_b128 v[166:169], v145 offset:3072
	ds_read_b128 v[194:197], v149
	ds_read_b128 v[198:201], v149 offset:1024
	s_mov_b32 m0, s22
	s_add_i32 s30, s31, 0x2180
	buffer_load_dwordx4 v134, s[56:59], s30 offen lds
	s_mov_b32 m0, s23
	s_add_i32 s31, s31, 0x82180
	buffer_load_dwordx4 v134, s[56:59], s31 offen lds
	s_waitcnt vmcnt(6)
	s_setprio 1
	s_barrier
	v_mfma_f32_16x16x32_bf16 v[28:31], v[218:221], v[202:205], v[28:31]
	v_mfma_f32_16x16x32_bf16 v[24:27], v[218:221], v[210:213], v[24:27]
	v_mfma_f32_16x16x32_bf16 v[20:23], v[226:229], v[202:205], v[20:23]
	v_mfma_f32_16x16x32_bf16 v[16:19], v[226:229], v[210:213], v[16:19]
	v_mfma_f32_16x16x32_bf16 v[12:15], v[238:241], v[202:205], v[12:15]
	v_mfma_f32_16x16x32_bf16 v[8:11], v[238:241], v[210:213], v[8:11]
	v_mfma_f32_16x16x32_bf16 v[4:7], v[246:249], v[202:205], v[4:7]
	v_mfma_f32_16x16x32_bf16 v[0:3], v[246:249], v[210:213], v[0:3]
	v_mfma_f32_16x16x32_bf16 v[28:31], v[222:225], v[206:209], v[28:31]
	v_mfma_f32_16x16x32_bf16 v[24:27], v[222:225], v[214:217], v[24:27]
	v_mfma_f32_16x16x32_bf16 v[20:23], v[230:233], v[206:209], v[20:23]
	v_mfma_f32_16x16x32_bf16 v[16:19], v[230:233], v[214:217], v[16:19]
	v_mfma_f32_16x16x32_bf16 v[12:15], v[242:245], v[206:209], v[12:15]
	v_mfma_f32_16x16x32_bf16 v[8:11], v[242:245], v[214:217], v[8:11]
	v_mfma_f32_16x16x32_bf16 v[4:7], v[250:253], v[206:209], v[4:7]
	v_mfma_f32_16x16x32_bf16 v[0:3], v[250:253], v[214:217], v[0:3]
	s_barrier
	s_setprio 0
	s_add_i32 s28, s28, 2
	s_addk_i32 s29, 0x100
	s_cmp_lt_u32 s28, 28
.LBB0_270:
	ds_read_b128 v[218:221], v146 offset:16384
	ds_read_b128 v[222:225], v146 offset:17408
	ds_read_b128 v[226:229], v147 offset:16384
	ds_read_b128 v[230:233], v147 offset:17408
	ds_read_b128 v[238:241], v148 offset:16384
	ds_read_b128 v[242:245], v148 offset:17408
	s_add_i32 s30, s27, s29
	s_mov_b32 m0, s24
	s_or_b32 s31, s30, 0x80080
	buffer_load_dwordx4 v131, s[48:51], s31 offen lds
	s_mov_b32 m0, s25
	s_or_b32 s31, s30, 0xc0080
	buffer_load_dwordx4 v131, s[48:51], s31 offen lds
	s_setprio 1
	s_barrier
	s_waitcnt lgkmcnt(6)
	v_mfma_f32_16x16x32_bf16 v[124:127], v[170:173], v[154:157], v[124:127]
	v_mfma_f32_16x16x32_bf16 v[120:123], v[170:173], v[162:165], v[120:123]
	v_mfma_f32_16x16x32_bf16 v[116:119], v[178:181], v[154:157], v[116:119]
	v_mfma_f32_16x16x32_bf16 v[112:115], v[178:181], v[162:165], v[112:115]
	v_mfma_f32_16x16x32_bf16 v[108:111], v[186:189], v[154:157], v[108:111]
	v_mfma_f32_16x16x32_bf16 v[104:107], v[186:189], v[162:165], v[104:107]
	v_mfma_f32_16x16x32_bf16 v[100:103], v[194:197], v[154:157], v[100:103]
	v_mfma_f32_16x16x32_bf16 v[96:99], v[194:197], v[162:165], v[96:99]
	v_mfma_f32_16x16x32_bf16 v[124:127], v[174:177], v[158:161], v[124:127]
	v_mfma_f32_16x16x32_bf16 v[120:123], v[174:177], v[166:169], v[120:123]
	v_mfma_f32_16x16x32_bf16 v[116:119], v[182:185], v[158:161], v[116:119]
	v_mfma_f32_16x16x32_bf16 v[112:115], v[182:185], v[166:169], v[112:115]
	v_mfma_f32_16x16x32_bf16 v[108:111], v[190:193], v[158:161], v[108:111]
	v_mfma_f32_16x16x32_bf16 v[104:107], v[190:193], v[166:169], v[104:107]
	v_mfma_f32_16x16x32_bf16 v[100:103], v[198:201], v[158:161], v[100:103]
	v_mfma_f32_16x16x32_bf16 v[96:99], v[198:201], v[166:169], v[96:99]
	s_barrier
	s_setprio 0
	ds_read_b128 v[202:205], v150
	ds_read_b128 v[206:209], v150 offset:1024
	ds_read_b128 v[210:213], v150 offset:2048
	ds_read_b128 v[214:217], v150 offset:3072
	ds_read_b128 v[246:249], v149 offset:16384
	ds_read_b128 v[250:253], v149 offset:17408
	s_add_i32 s31, s3, s29
	s_mov_b32 m0, s11
	s_add_i32 s34, s31, 0x100
	buffer_load_dwordx4 v134, s[56:59], s34 offen lds
	s_mov_b32 m0, s12
	s_add_i32 s34, s31, 0x80100
	buffer_load_dwordx4 v134, s[56:59], s34 offen lds
	s_waitcnt vmcnt(6)
	s_setprio 1
	s_barrier
	s_waitcnt lgkmcnt(2)
	v_mfma_f32_16x16x32_bf16 v[92:95], v[170:173], v[202:205], v[92:95]
	v_mfma_f32_16x16x32_bf16 v[88:91], v[170:173], v[210:213], v[88:91]
	v_mfma_f32_16x16x32_bf16 v[84:87], v[178:181], v[202:205], v[84:87]
	v_mfma_f32_16x16x32_bf16 v[80:83], v[178:181], v[210:213], v[80:83]
	v_mfma_f32_16x16x32_bf16 v[76:79], v[186:189], v[202:205], v[76:79]
	v_mfma_f32_16x16x32_bf16 v[72:75], v[186:189], v[210:213], v[72:75]
	v_mfma_f32_16x16x32_bf16 v[68:71], v[194:197], v[202:205], v[68:71]
	v_mfma_f32_16x16x32_bf16 v[64:67], v[194:197], v[210:213], v[64:67]
	v_mfma_f32_16x16x32_bf16 v[92:95], v[174:177], v[206:209], v[92:95]
	v_mfma_f32_16x16x32_bf16 v[88:91], v[174:177], v[214:217], v[88:91]
	v_mfma_f32_16x16x32_bf16 v[84:87], v[182:185], v[206:209], v[84:87]
	v_mfma_f32_16x16x32_bf16 v[80:83], v[182:185], v[214:217], v[80:83]
	v_mfma_f32_16x16x32_bf16 v[76:79], v[190:193], v[206:209], v[76:79]
	v_mfma_f32_16x16x32_bf16 v[72:75], v[190:193], v[214:217], v[72:75]
	v_mfma_f32_16x16x32_bf16 v[68:71], v[198:201], v[206:209], v[68:71]
	v_mfma_f32_16x16x32_bf16 v[64:67], v[198:201], v[214:217], v[64:67]
	s_barrier
; #define STAGE_A(POFF, h, kt) STAGE_AX(POFF, h, kt, brow)
; #define STAGE_B(POFF, h, kt) STAGE_BX(POFF, h, kt, bcol)
; #define LDA(dst, b, h) _Pragma("unroll") for (int m = 0; m < 4; ++m) _Pragma("unroll") for (int k = 0; k < 2; ++k) \
;     dst[m][k] = *reinterpret_cast<const bf16x8*>((char*)SA(b, h) + lds_byte(wr * 64 + m * 16 + fr, k * 32 + fq * 8))
; #define LDB(dst, b, h) _Pragma("unroll") for (int n = 0; n < 2; ++n) _Pragma("unroll") for (int k = 0; k < 2; ++k) \
;     dst[n][k] = *reinterpret_cast<const bf16x8*>((char*)SB(b, h) + lds_byte(wc * 32 + n * 16 + fr, k * 32 + fq * 8))
; #define MMA(ai, bj, At_, Bt_) do { __builtin_amdgcn_s_setprio(1); \
;     _Pragma("unroll") for (int k = 0; k < 2; ++k) _Pragma("unroll") for (int m = 0; m < 4; ++m) _Pragma("unroll") for (int n = 0; n < 2; ++n) \
;       acc[ai][bj][m][n] = __builtin_amdgcn_mfma_f32_16x16x32_bf16(At_[m][k], Bt_[n][k], acc[ai][bj][m][n], 0, 0, 0); \
;     __builtin_amdgcn_s_setprio(0); } while (0)
; #define WAIT_V(n) asm volatile("s_waitcnt vmcnt(" #n ")" ::: "memory")
; #define BAR __builtin_amdgcn_s_barrier()
; #define SCHED __builtin_amdgcn_sched_barrier(0)
; template <int EPI, int N, int K>
; __device__ __forceinline__ void gemm_phase(const bf16_t* __restrict__ A, const bf16_t* __restrict__ Bt, const EpiArgs ea) {
;     ...
;       LDA(At, 0, 1); STAGE_A(SA_OFF(0, 0), 0, t + 2);
;       BAR; WAIT_L(0); MMA(1, 0, At, B0); BAR; SCHED;
;       STAGE_B(SB_OFF(0, 1), 1, t + 2);
;       WAIT_V(6); BAR; MMA(1, 1, At, B1); BAR;
;       LDB(B0, 1, 0); SCHED; LDA(At, 1, 0); STAGE_A(SA_OFF(0, 1), 1, t + 2);
;       WAIT_L(8); BAR; WAIT_L(0); MMA(0, 0, At, B0); BAR; SCHED;
;       LDB(B1, 1, 1); STAGE_B(SB_OFF(1, 0), 0, t + 3);
;       BAR; WAIT_L(0); MMA(0, 1, At, B1); BAR;
	s_setprio 0
	ds_read_b128 v[170:173], v146 offset:32768
	ds_read_b128 v[174:177], v146 offset:33792
	ds_read_b128 v[178:181], v147 offset:32768
	ds_read_b128 v[182:185], v147 offset:33792
	ds_read_b128 v[186:189], v148 offset:32768
	ds_read_b128 v[190:193], v148 offset:33792
	s_mov_b32 m0, s10
	s_add_i32 s34, s30, 0x100
	buffer_load_dwordx4 v131, s[48:51], s34 offen lds
	s_mov_b32 m0, s13
	s_add_i32 s35, s30, 0x40100
	buffer_load_dwordx4 v131, s[48:51], s35 offen lds
	s_waitcnt vmcnt(10)
	s_setprio 1
	s_barrier
	s_waitcnt lgkmcnt(6)
	v_mfma_f32_16x16x32_bf16 v[60:63], v[218:221], v[154:157], v[60:63]
	v_mfma_f32_16x16x32_bf16 v[56:59], v[218:221], v[162:165], v[56:59]
	v_mfma_f32_16x16x32_bf16 v[52:55], v[226:229], v[154:157], v[52:55]
	v_mfma_f32_16x16x32_bf16 v[48:51], v[226:229], v[162:165], v[48:51]
	v_mfma_f32_16x16x32_bf16 v[44:47], v[238:241], v[154:157], v[44:47]
	v_mfma_f32_16x16x32_bf16 v[40:43], v[238:241], v[162:165], v[40:43]
	v_mfma_f32_16x16x32_bf16 v[36:39], v[246:249], v[154:157], v[36:39]
	v_mfma_f32_16x16x32_bf16 v[32:35], v[246:249], v[162:165], v[32:35]
	v_mfma_f32_16x16x32_bf16 v[60:63], v[222:225], v[158:161], v[60:63]
	v_mfma_f32_16x16x32_bf16 v[56:59], v[222:225], v[166:169], v[56:59]
	v_mfma_f32_16x16x32_bf16 v[52:55], v[230:233], v[158:161], v[52:55]
	v_mfma_f32_16x16x32_bf16 v[48:51], v[230:233], v[166:169], v[48:51]
	v_mfma_f32_16x16x32_bf16 v[44:47], v[242:245], v[158:161], v[44:47]
	v_mfma_f32_16x16x32_bf16 v[40:43], v[242:245], v[166:169], v[40:43]
	v_mfma_f32_16x16x32_bf16 v[36:39], v[250:253], v[158:161], v[36:39]
	v_mfma_f32_16x16x32_bf16 v[32:35], v[250:253], v[166:169], v[32:35]
	s_barrier
	s_setprio 0
	ds_read_b128 v[154:157], v151
	ds_read_b128 v[158:161], v151 offset:1024
	ds_read_b128 v[162:165], v151 offset:2048
	ds_read_b128 v[166:169], v151 offset:3072
	ds_read_b128 v[194:197], v149 offset:32768
	ds_read_b128 v[198:201], v149 offset:33792
	s_mov_b32 m0, s14
	s_add_i32 s35, s31, 0x2100
	buffer_load_dwordx4 v134, s[56:59], s35 offen lds
	s_mov_b32 m0, s15
	s_add_i32 s35, s31, 0x82100
	buffer_load_dwordx4 v134, s[56:59], s35 offen lds
	s_waitcnt vmcnt(6)
	s_setprio 1
	s_barrier
	v_mfma_f32_16x16x32_bf16 v[28:31], v[218:221], v[202:205], v[28:31]
	v_mfma_f32_16x16x32_bf16 v[24:27], v[218:221], v[210:213], v[24:27]
	v_mfma_f32_16x16x32_bf16 v[20:23], v[226:229], v[202:205], v[20:23]
	v_mfma_f32_16x16x32_bf16 v[16:19], v[226:229], v[210:213], v[16:19]
	v_mfma_f32_16x16x32_bf16 v[12:15], v[238:241], v[202:205], v[12:15]
	v_mfma_f32_16x16x32_bf16 v[8:11], v[238:241], v[210:213], v[8:11]
	v_mfma_f32_16x16x32_bf16 v[4:7], v[246:249], v[202:205], v[4:7]
	v_mfma_f32_16x16x32_bf16 v[0:3], v[246:249], v[210:213], v[0:3]
	v_mfma_f32_16x16x32_bf16 v[28:31], v[222:225], v[206:209], v[28:31]
	v_mfma_f32_16x16x32_bf16 v[24:27], v[222:225], v[214:217], v[24:27]
	v_mfma_f32_16x16x32_bf16 v[20:23], v[230:233], v[206:209], v[20:23]
	v_mfma_f32_16x16x32_bf16 v[16:19], v[230:233], v[214:217], v[16:19]
	v_mfma_f32_16x16x32_bf16 v[12:15], v[242:245], v[206:209], v[12:15]
	v_mfma_f32_16x16x32_bf16 v[8:11], v[242:245], v[214:217], v[8:11]
	v_mfma_f32_16x16x32_bf16 v[4:7], v[250:253], v[206:209], v[4:7]
	v_mfma_f32_16x16x32_bf16 v[0:3], v[250:253], v[214:217], v[0:3]
	s_barrier
	s_setprio 0
	ds_read_b128 v[218:221], v146 offset:49152
	ds_read_b128 v[222:225], v146 offset:50176
	ds_read_b128 v[226:229], v147 offset:49152
	ds_read_b128 v[230:233], v147 offset:50176
	ds_read_b128 v[238:241], v148 offset:49152
	ds_read_b128 v[242:245], v148 offset:50176
	s_mov_b32 m0, s16
	s_or_b32 s35, s34, 0x80000
	buffer_load_dwordx4 v131, s[48:51], s35 offen lds
	s_mov_b32 m0, s17
	s_or_b32 s34, s34, 0xc0000
	buffer_load_dwordx4 v131, s[48:51], s34 offen lds
	s_setprio 1
	s_barrier
	s_waitcnt lgkmcnt(6)
	v_mfma_f32_16x16x32_bf16 v[124:127], v[170:173], v[154:157], v[124:127]
	v_mfma_f32_16x16x32_bf16 v[120:123], v[170:173], v[162:165], v[120:123]
	v_mfma_f32_16x16x32_bf16 v[116:119], v[178:181], v[154:157], v[116:119]
	v_mfma_f32_16x16x32_bf16 v[112:115], v[178:181], v[162:165], v[112:115]
	v_mfma_f32_16x16x32_bf16 v[108:111], v[186:189], v[154:157], v[108:111]
	v_mfma_f32_16x16x32_bf16 v[104:107], v[186:189], v[162:165], v[104:107]
	v_mfma_f32_16x16x32_bf16 v[100:103], v[194:197], v[154:157], v[100:103]
	v_mfma_f32_16x16x32_bf16 v[96:99], v[194:197], v[162:165], v[96:99]
	v_mfma_f32_16x16x32_bf16 v[124:127], v[174:177], v[158:161], v[124:127]
	v_mfma_f32_16x16x32_bf16 v[120:123], v[174:177], v[166:169], v[120:123]
	v_mfma_f32_16x16x32_bf16 v[116:119], v[182:185], v[158:161], v[116:119]
	v_mfma_f32_16x16x32_bf16 v[112:115], v[182:185], v[166:169], v[112:115]
	v_mfma_f32_16x16x32_bf16 v[108:111], v[190:193], v[158:161], v[108:111]
	v_mfma_f32_16x16x32_bf16 v[104:107], v[190:193], v[166:169], v[104:107]
	v_mfma_f32_16x16x32_bf16 v[100:103], v[198:201], v[158:161], v[100:103]
	v_mfma_f32_16x16x32_bf16 v[96:99], v[198:201], v[166:169], v[96:99]
	s_barrier
	s_setprio 0
	ds_read_b128 v[202:205], v152
	ds_read_b128 v[206:209], v152 offset:1024
	ds_read_b128 v[210:213], v152 offset:2048
	ds_read_b128 v[214:217], v152 offset:3072
	ds_read_b128 v[246:249], v149 offset:49152
	ds_read_b128 v[250:253], v149 offset:50176
	s_mov_b32 m0, s18
	s_add_i32 s34, s31, 0x180
	buffer_load_dwordx4 v134, s[56:59], s34 offen lds
	s_mov_b32 m0, s19
	s_add_i32 s34, s31, 0x80180
	buffer_load_dwordx4 v134, s[56:59], s34 offen lds
	s_waitcnt vmcnt(6)
	s_setprio 1
	s_barrier
; #define STAGE_A(POFF, h, kt) STAGE_AX(POFF, h, kt, brow)
; #define STAGE_B(POFF, h, kt) STAGE_BX(POFF, h, kt, bcol)
; #define LDA(dst, b, h) _Pragma("unroll") for (int m = 0; m < 4; ++m) _Pragma("unroll") for (int k = 0; k < 2; ++k) \
;     dst[m][k] = *reinterpret_cast<const bf16x8*>((char*)SA(b, h) + lds_byte(wr * 64 + m * 16 + fr, k * 32 + fq * 8))
; #define LDB(dst, b, h) _Pragma("unroll") for (int n = 0; n < 2; ++n) _Pragma("unroll") for (int k = 0; k < 2; ++k) \
;     dst[n][k] = *reinterpret_cast<const bf16x8*>((char*)SB(b, h) + lds_byte(wc * 32 + n * 16 + fr, k * 32 + fq * 8))
; #define MMA(ai, bj, At_, Bt_) do { __builtin_amdgcn_s_setprio(1); \
;     _Pragma("unroll") for (int k = 0; k < 2; ++k) _Pragma("unroll") for (int m = 0; m < 4; ++m) _Pragma("unroll") for (int n = 0; n < 2; ++n) \
;       acc[ai][bj][m][n] = __builtin_amdgcn_mfma_f32_16x16x32_bf16(At_[m][k], Bt_[n][k], acc[ai][bj][m][n], 0, 0, 0); \
;     __builtin_amdgcn_s_setprio(0); } while (0)
; #define WAIT_V(n) asm volatile("s_waitcnt vmcnt(" #n ")" ::: "memory")
; #define BAR __builtin_amdgcn_s_barrier()
; #define SCHED __builtin_amdgcn_sched_barrier(0)
; template <int EPI, int N, int K>
; __device__ __forceinline__ void gemm_phase(const bf16_t* __restrict__ A, const bf16_t* __restrict__ Bt, const EpiArgs ea) {
;     ...
;       LDA(At, 1, 1); STAGE_A(SA_OFF(1, 0), 0, t + 3);
;       BAR; WAIT_L(0); MMA(1, 0, At, B0); BAR; SCHED;
;       STAGE_B(SB_OFF(1, 1), 1, t + 3);
;       WAIT_V(6); BAR; MMA(1, 1, At, B1); BAR;
;     }
;     { LDB(B0, 0, 0); LDA(At, 0, 0); STAGE_A(SA_OFF(1, 1), 1, nt - 1);
;       BAR; WAIT_L(0); MMA(0, 0, At, B0); BAR;
;       LDB(B1, 0, 1); BAR; WAIT_L(0); MMA(0, 1, At, B1); BAR;
;       LDA(At, 0, 1); WAIT_V(4); BAR; WAIT_L(0); MMA(1, 0, At, B0); MMA(1, 1, At, B1); BAR; }
	s_waitcnt lgkmcnt(2)
	v_mfma_f32_16x16x32_bf16 v[92:95], v[170:173], v[202:205], v[92:95]
	v_mfma_f32_16x16x32_bf16 v[88:91], v[170:173], v[210:213], v[88:91]
	v_mfma_f32_16x16x32_bf16 v[84:87], v[178:181], v[202:205], v[84:87]
	v_mfma_f32_16x16x32_bf16 v[80:83], v[178:181], v[210:213], v[80:83]
	v_mfma_f32_16x16x32_bf16 v[76:79], v[186:189], v[202:205], v[76:79]
	v_mfma_f32_16x16x32_bf16 v[72:75], v[186:189], v[210:213], v[72:75]
	v_mfma_f32_16x16x32_bf16 v[68:71], v[194:197], v[202:205], v[68:71]
	v_mfma_f32_16x16x32_bf16 v[64:67], v[194:197], v[210:213], v[64:67]
	v_mfma_f32_16x16x32_bf16 v[92:95], v[174:177], v[206:209], v[92:95]
	v_mfma_f32_16x16x32_bf16 v[88:91], v[174:177], v[214:217], v[88:91]
	v_mfma_f32_16x16x32_bf16 v[84:87], v[182:185], v[206:209], v[84:87]
	v_mfma_f32_16x16x32_bf16 v[80:83], v[182:185], v[214:217], v[80:83]
	v_mfma_f32_16x16x32_bf16 v[76:79], v[190:193], v[206:209], v[76:79]
	v_mfma_f32_16x16x32_bf16 v[72:75], v[190:193], v[214:217], v[72:75]
	v_mfma_f32_16x16x32_bf16 v[68:71], v[198:201], v[206:209], v[68:71]
	v_mfma_f32_16x16x32_bf16 v[64:67], v[198:201], v[214:217], v[64:67]
	s_barrier
	s_setprio 0
	ds_read_b128 v[170:173], v146
	ds_read_b128 v[174:177], v146 offset:1024
	ds_read_b128 v[178:181], v147
	ds_read_b128 v[182:185], v147 offset:1024
	ds_read_b128 v[186:189], v148
	ds_read_b128 v[190:193], v148 offset:1024
	s_mov_b32 m0, s20
	s_add_i32 s34, s30, 0x180
	buffer_load_dwordx4 v131, s[48:51], s34 offen lds
	s_mov_b32 m0, s21
	s_add_i32 s30, s30, 0x40180
	buffer_load_dwordx4 v131, s[48:51], s30 offen lds
	s_waitcnt vmcnt(10)
	s_setprio 1
	s_barrier
	s_waitcnt lgkmcnt(6)
	v_mfma_f32_16x16x32_bf16 v[60:63], v[218:221], v[154:157], v[60:63]
	v_mfma_f32_16x16x32_bf16 v[56:59], v[218:221], v[162:165], v[56:59]
	v_mfma_f32_16x16x32_bf16 v[52:55], v[226:229], v[154:157], v[52:55]
	v_mfma_f32_16x16x32_bf16 v[48:51], v[226:229], v[162:165], v[48:51]
	v_mfma_f32_16x16x32_bf16 v[44:47], v[238:241], v[154:157], v[44:47]
	v_mfma_f32_16x16x32_bf16 v[40:43], v[238:241], v[162:165], v[40:43]
	v_mfma_f32_16x16x32_bf16 v[36:39], v[246:249], v[154:157], v[36:39]
	v_mfma_f32_16x16x32_bf16 v[32:35], v[246:249], v[162:165], v[32:35]
	v_mfma_f32_16x16x32_bf16 v[60:63], v[222:225], v[158:161], v[60:63]
	v_mfma_f32_16x16x32_bf16 v[56:59], v[222:225], v[166:169], v[56:59]
	v_mfma_f32_16x16x32_bf16 v[52:55], v[230:233], v[158:161], v[52:55]
	v_mfma_f32_16x16x32_bf16 v[48:51], v[230:233], v[166:169], v[48:51]
	v_mfma_f32_16x16x32_bf16 v[44:47], v[242:245], v[158:161], v[44:47]
	v_mfma_f32_16x16x32_bf16 v[40:43], v[242:245], v[166:169], v[40:43]
	v_mfma_f32_16x16x32_bf16 v[36:39], v[250:253], v[158:161], v[36:39]
	v_mfma_f32_16x16x32_bf16 v[32:35], v[250:253], v[166:169], v[32:35]
	s_barrier
	s_setprio 0
	ds_read_b128 v[154:157], v145
	ds_read_b128 v[158:161], v145 offset:1024
	ds_read_b128 v[162:165], v145 offset:2048
	ds_read_b128 v[166:169], v145 offset:3072
	ds_read_b128 v[194:197], v149
	ds_read_b128 v[198:201], v149 offset:1024
	s_mov_b32 m0, s22
	s_add_i32 s30, s31, 0x2180
	buffer_load_dwordx4 v134, s[56:59], s30 offen lds
	s_mov_b32 m0, s23
	s_add_i32 s31, s31, 0x82180
	buffer_load_dwordx4 v134, s[56:59], s31 offen lds
	s_waitcnt vmcnt(6)
	s_setprio 1
	s_barrier
	v_mfma_f32_16x16x32_bf16 v[28:31], v[218:221], v[202:205], v[28:31]
	v_mfma_f32_16x16x32_bf16 v[24:27], v[218:221], v[210:213], v[24:27]
	v_mfma_f32_16x16x32_bf16 v[20:23], v[226:229], v[202:205], v[20:23]
	v_mfma_f32_16x16x32_bf16 v[16:19], v[226:229], v[210:213], v[16:19]
	v_mfma_f32_16x16x32_bf16 v[12:15], v[238:241], v[202:205], v[12:15]
	v_mfma_f32_16x16x32_bf16 v[8:11], v[238:241], v[210:213], v[8:11]
	v_mfma_f32_16x16x32_bf16 v[4:7], v[246:249], v[202:205], v[4:7]
	v_mfma_f32_16x16x32_bf16 v[0:3], v[246:249], v[210:213], v[0:3]
	v_mfma_f32_16x16x32_bf16 v[28:31], v[222:225], v[206:209], v[28:31]
	v_mfma_f32_16x16x32_bf16 v[24:27], v[222:225], v[214:217], v[24:27]
	v_mfma_f32_16x16x32_bf16 v[20:23], v[230:233], v[206:209], v[20:23]
	v_mfma_f32_16x16x32_bf16 v[16:19], v[230:233], v[214:217], v[16:19]
	v_mfma_f32_16x16x32_bf16 v[12:15], v[242:245], v[206:209], v[12:15]
	v_mfma_f32_16x16x32_bf16 v[8:11], v[242:245], v[214:217], v[8:11]
	v_mfma_f32_16x16x32_bf16 v[4:7], v[250:253], v[206:209], v[4:7]
	v_mfma_f32_16x16x32_bf16 v[0:3], v[250:253], v[214:217], v[0:3]
	s_barrier
	s_setprio 0
	s_add_i32 s28, s28, 2
	s_addk_i32 s29, 0x100
	s_cmp_lt_u32 s28, 28
	s_cbranch_scc1 .LBB0_270
	s_and_b32 s1, s1, 0x700
	s_lshl_b32 s0, s0, 11
	s_or_b32 s27, s1, s0
	s_lshl_b32 s0, s27, 12
	s_or_b32 s1, s0, 0x80f80
	s_mov_b32 m0, s24
	s_nop 0
	buffer_load_dwordx4 v131, s[48:51], s1 offen lds
	s_or_b32 s0, s0, 0xc0f80
	s_mov_b32 m0, s25
	s_nop 0
	buffer_load_dwordx4 v131, s[48:51], s0 offen lds
	s_barrier
	s_waitcnt lgkmcnt(0)
	s_setprio 1
	v_mfma_f32_16x16x32_bf16 v[124:127], v[170:173], v[154:157], v[124:127]
	v_mfma_f32_16x16x32_bf16 v[120:123], v[170:173], v[162:165], v[120:123]
	v_mfma_f32_16x16x32_bf16 v[116:119], v[178:181], v[154:157], v[116:119]
	v_mfma_f32_16x16x32_bf16 v[112:115], v[178:181], v[162:165], v[112:115]
	v_mfma_f32_16x16x32_bf16 v[108:111], v[186:189], v[154:157], v[108:111]
	v_mfma_f32_16x16x32_bf16 v[104:107], v[186:189], v[162:165], v[104:107]
	v_mfma_f32_16x16x32_bf16 v[100:103], v[194:197], v[154:157], v[100:103]
	v_mfma_f32_16x16x32_bf16 v[96:99], v[194:197], v[162:165], v[96:99]
	v_mfma_f32_16x16x32_bf16 v[124:127], v[174:177], v[158:161], v[124:127]
	v_mfma_f32_16x16x32_bf16 v[120:123], v[174:177], v[166:169], v[120:123]
	v_mfma_f32_16x16x32_bf16 v[116:119], v[182:185], v[158:161], v[116:119]
	v_mfma_f32_16x16x32_bf16 v[112:115], v[182:185], v[166:169], v[112:115]
	v_mfma_f32_16x16x32_bf16 v[108:111], v[190:193], v[158:161], v[108:111]
	v_mfma_f32_16x16x32_bf16 v[104:107], v[190:193], v[166:169], v[104:107]
	v_mfma_f32_16x16x32_bf16 v[100:103], v[198:201], v[158:161], v[100:103]
	v_mfma_f32_16x16x32_bf16 v[96:99], v[198:201], v[166:169], v[96:99]
	s_setprio 0
	s_barrier
; #define STAGE_A(POFF, h, kt) STAGE_AX(POFF, h, kt, brow)
; #define LDA(dst, b, h) _Pragma("unroll") for (int m = 0; m < 4; ++m) _Pragma("unroll") for (int k = 0; k < 2; ++k) \
;     dst[m][k] = *reinterpret_cast<const bf16x8*>((char*)SA(b, h) + lds_byte(wr * 64 + m * 16 + fr, k * 32 + fq * 8))
; #define LDB(dst, b, h) _Pragma("unroll") for (int n = 0; n < 2; ++n) _Pragma("unroll") for (int k = 0; k < 2; ++k) \
;     dst[n][k] = *reinterpret_cast<const bf16x8*>((char*)SB(b, h) + lds_byte(wc * 32 + n * 16 + fr, k * 32 + fq * 8))
; #define MMA(ai, bj, At_, Bt_) do { __builtin_amdgcn_s_setprio(1); \
;     _Pragma("unroll") for (int k = 0; k < 2; ++k) _Pragma("unroll") for (int m = 0; m < 4; ++m) _Pragma("unroll") for (int n = 0; n < 2; ++n) \
;       acc[ai][bj][m][n] = __builtin_amdgcn_mfma_f32_16x16x32_bf16(At_[m][k], Bt_[n][k], acc[ai][bj][m][n], 0, 0, 0); \
;     __builtin_amdgcn_s_setprio(0); } while (0)
; #define WAIT_V(n) asm volatile("s_waitcnt vmcnt(" #n ")" ::: "memory")
; #define BAR __builtin_amdgcn_s_barrier()
; template <int EPI, int N, int K>
; __device__ __forceinline__ void gemm_phase(const bf16_t* __restrict__ A, const bf16_t* __restrict__ Bt, const EpiArgs ea) {
;     ...
;     { LDB(B0, 0, 0); LDA(At, 0, 0); STAGE_A(SA_OFF(1, 1), 1, nt - 1);
;       BAR; WAIT_L(0); MMA(0, 0, At, B0); BAR;
;       LDB(B1, 0, 1); BAR; WAIT_L(0); MMA(0, 1, At, B1); BAR;
;       LDA(At, 0, 1); WAIT_V(4); BAR; WAIT_L(0); MMA(1, 0, At, B0); MMA(1, 1, At, B1); BAR; }
;     { LDB(B0, 1, 0); LDA(At, 1, 0); WAIT_V(2); BAR; WAIT_L(0); MMA(0, 0, At, B0); BAR;
	ds_read_b128 v[202:205], v150
	ds_read_b128 v[206:209], v150 offset:1024
	ds_read_b128 v[210:213], v150 offset:2048
	ds_read_b128 v[214:217], v150 offset:3072
	s_barrier
	s_waitcnt lgkmcnt(0)
	s_setprio 1
	v_mfma_f32_16x16x32_bf16 v[92:95], v[170:173], v[202:205], v[92:95]
	v_mfma_f32_16x16x32_bf16 v[88:91], v[170:173], v[210:213], v[88:91]
	v_mfma_f32_16x16x32_bf16 v[76:79], v[186:189], v[202:205], v[76:79]
	v_mfma_f32_16x16x32_bf16 v[72:75], v[186:189], v[210:213], v[72:75]
	v_mfma_f32_16x16x32_bf16 v[68:71], v[194:197], v[202:205], v[68:71]
	v_mfma_f32_16x16x32_bf16 v[64:67], v[194:197], v[210:213], v[64:67]
	v_mfma_f32_16x16x32_bf16 v[84:87], v[178:181], v[202:205], v[84:87]
	v_mfma_f32_16x16x32_bf16 v[80:83], v[178:181], v[210:213], v[80:83]
	v_mfma_f32_16x16x32_bf16 v[92:95], v[174:177], v[206:209], v[92:95]
	v_mfma_f32_16x16x32_bf16 v[88:91], v[174:177], v[214:217], v[88:91]
	v_mfma_f32_16x16x32_bf16 v[76:79], v[190:193], v[206:209], v[76:79]
	v_mfma_f32_16x16x32_bf16 v[72:75], v[190:193], v[214:217], v[72:75]
	v_mfma_f32_16x16x32_bf16 v[68:71], v[198:201], v[206:209], v[68:71]
	v_mfma_f32_16x16x32_bf16 v[64:67], v[198:201], v[214:217], v[64:67]
	v_mfma_f32_16x16x32_bf16 v[170:173], v[182:185], v[206:209], v[84:87]
	v_mfma_f32_16x16x32_bf16 v[174:177], v[182:185], v[214:217], v[80:83]
	s_setprio 0
	s_barrier
	s_nop 0
	ds_read_b128 v[80:83], v146 offset:16384
	ds_read_b128 v[84:87], v146 offset:17408
	ds_read_b128 v[178:181], v147 offset:16384
	ds_read_b128 v[182:185], v147 offset:17408
	ds_read_b128 v[186:189], v148 offset:16384
	ds_read_b128 v[190:193], v148 offset:17408
	ds_read_b128 v[194:197], v149 offset:16384
	ds_read_b128 v[198:201], v149 offset:17408
	s_waitcnt vmcnt(4)
	s_barrier
	s_waitcnt lgkmcnt(0)
	s_setprio 1
	v_mfma_f32_16x16x32_bf16 v[52:55], v[178:181], v[154:157], v[52:55]
	v_mfma_f32_16x16x32_bf16 v[48:51], v[178:181], v[162:165], v[48:51]
	v_mfma_f32_16x16x32_bf16 v[44:47], v[186:189], v[154:157], v[44:47]
	v_mfma_f32_16x16x32_bf16 v[40:43], v[186:189], v[162:165], v[40:43]
	v_mfma_f32_16x16x32_bf16 v[36:39], v[194:197], v[154:157], v[36:39]
	v_mfma_f32_16x16x32_bf16 v[32:35], v[194:197], v[162:165], v[32:35]
	v_mfma_f32_16x16x32_bf16 v[60:63], v[80:83], v[154:157], v[60:63]
	v_mfma_f32_16x16x32_bf16 v[56:59], v[80:83], v[162:165], v[56:59]
	v_mfma_f32_16x16x32_bf16 v[52:55], v[182:185], v[158:161], v[52:55]
	v_mfma_f32_16x16x32_bf16 v[48:51], v[182:185], v[166:169], v[48:51]
	v_mfma_f32_16x16x32_bf16 v[44:47], v[190:193], v[158:161], v[44:47]
	v_mfma_f32_16x16x32_bf16 v[40:43], v[190:193], v[166:169], v[40:43]
	v_mfma_f32_16x16x32_bf16 v[36:39], v[198:201], v[158:161], v[36:39]
	v_mfma_f32_16x16x32_bf16 v[32:35], v[198:201], v[166:169], v[32:35]
	v_mfma_f32_16x16x32_bf16 v[154:157], v[84:87], v[158:161], v[60:63]
	v_mfma_f32_16x16x32_bf16 v[162:165], v[84:87], v[166:169], v[56:59]
	s_setprio 0
	s_setprio 1
	v_mfma_f32_16x16x32_bf16 v[28:31], v[80:83], v[202:205], v[28:31]
	v_mfma_f32_16x16x32_bf16 v[24:27], v[80:83], v[210:213], v[24:27]
	v_mfma_f32_16x16x32_bf16 v[12:15], v[186:189], v[202:205], v[12:15]
	v_mfma_f32_16x16x32_bf16 v[8:11], v[186:189], v[210:213], v[8:11]
	v_mfma_f32_16x16x32_bf16 v[20:23], v[178:181], v[202:205], v[20:23]
	v_mfma_f32_16x16x32_bf16 v[16:19], v[178:181], v[210:213], v[16:19]
	v_mfma_f32_16x16x32_bf16 v[4:7], v[194:197], v[202:205], v[4:7]
	v_mfma_f32_16x16x32_bf16 v[0:3], v[194:197], v[210:213], v[0:3]
	v_mfma_f32_16x16x32_bf16 v[28:31], v[84:87], v[206:209], v[28:31]
	v_mfma_f32_16x16x32_bf16 v[24:27], v[84:87], v[214:217], v[24:27]
	v_mfma_f32_16x16x32_bf16 v[12:15], v[190:193], v[206:209], v[12:15]
	v_mfma_f32_16x16x32_bf16 v[8:11], v[190:193], v[214:217], v[8:11]
	v_mfma_f32_16x16x32_bf16 v[158:161], v[182:185], v[206:209], v[20:23]
	v_mfma_f32_16x16x32_bf16 v[166:169], v[182:185], v[214:217], v[16:19]
	v_mfma_f32_16x16x32_bf16 v[178:181], v[198:201], v[206:209], v[4:7]
	v_mfma_f32_16x16x32_bf16 v[182:185], v[198:201], v[214:217], v[0:3]
	s_setprio 0
	s_barrier
	s_nop 0
	ds_read_b128 v[0:3], v151
	ds_read_b128 v[4:7], v151 offset:1024
	ds_read_b128 v[16:19], v151 offset:2048
	ds_read_b128 v[186:189], v151 offset:3072
	ds_read_b128 v[20:23], v146 offset:32768
	ds_read_b128 v[190:193], v146 offset:33792
	ds_read_b128 v[194:197], v147 offset:32768
	ds_read_b128 v[198:201], v147 offset:33792
	ds_read_b128 v[202:205], v148 offset:32768
	ds_read_b128 v[206:209], v148 offset:33792
	ds_read_b128 v[210:213], v149 offset:32768
	ds_read_b128 v[214:217], v149 offset:33792
	s_waitcnt vmcnt(2)
	s_barrier
; #define LDA(dst, b, h) _Pragma("unroll") for (int m = 0; m < 4; ++m) _Pragma("unroll") for (int k = 0; k < 2; ++k) \
;     dst[m][k] = *reinterpret_cast<const bf16x8*>((char*)SA(b, h) + lds_byte(wr * 64 + m * 16 + fr, k * 32 + fq * 8))
; #define LDB(dst, b, h) _Pragma("unroll") for (int n = 0; n < 2; ++n) _Pragma("unroll") for (int k = 0; k < 2; ++k) \
;     dst[n][k] = *reinterpret_cast<const bf16x8*>((char*)SB(b, h) + lds_byte(wc * 32 + n * 16 + fr, k * 32 + fq * 8))
; #define MMA(ai, bj, At_, Bt_) do { __builtin_amdgcn_s_setprio(1); \
;     _Pragma("unroll") for (int k = 0; k < 2; ++k) _Pragma("unroll") for (int m = 0; m < 4; ++m) _Pragma("unroll") for (int n = 0; n < 2; ++n) \
;       acc[ai][bj][m][n] = __builtin_amdgcn_mfma_f32_16x16x32_bf16(At_[m][k], Bt_[n][k], acc[ai][bj][m][n], 0, 0, 0); \
;     __builtin_amdgcn_s_setprio(0); } while (0)
; #define WAIT_V(n) asm volatile("s_waitcnt vmcnt(" #n ")" ::: "memory")
; #define BAR __builtin_amdgcn_s_barrier()
; template <int EPI, int N, int K>
; __device__ __forceinline__ void gemm_phase(const bf16_t* __restrict__ A, const bf16_t* __restrict__ Bt, const EpiArgs ea) {
;     ...
;     { LDB(B0, 1, 0); LDA(At, 1, 0); WAIT_V(2); BAR; WAIT_L(0); MMA(0, 0, At, B0); BAR;
;       LDB(B1, 1, 1); WAIT_V(0); BAR; WAIT_L(0); MMA(0, 1, At, B1); BAR;
;       LDA(At, 1, 1); BAR; WAIT_L(0); MMA(1, 0, At, B0); MMA(1, 1, At, B1); BAR; }
;     if (wr == 0) BAR;
	s_waitcnt lgkmcnt(0)
	s_setprio 1
	v_mfma_f32_16x16x32_bf16 v[56:59], v[20:23], v[0:3], v[124:127]
	v_mfma_f32_16x16x32_bf16 v[60:63], v[20:23], v[16:19], v[120:123]
	v_mfma_f32_16x16x32_bf16 v[80:83], v[194:197], v[0:3], v[116:119]
	v_mfma_f32_16x16x32_bf16 v[84:87], v[194:197], v[16:19], v[112:115]
	v_mfma_f32_16x16x32_bf16 v[108:111], v[202:205], v[0:3], v[108:111]
	v_mfma_f32_16x16x32_bf16 v[104:107], v[202:205], v[16:19], v[104:107]
	v_mfma_f32_16x16x32_bf16 v[120:123], v[210:213], v[0:3], v[100:103]
	v_mfma_f32_16x16x32_bf16 v[124:127], v[210:213], v[16:19], v[96:99]
	v_mfma_f32_16x16x32_bf16 v[116:119], v[190:193], v[4:7], v[56:59]
	v_mfma_f32_16x16x32_bf16 v[112:115], v[190:193], v[186:189], v[60:63]
	v_mfma_f32_16x16x32_bf16 v[100:103], v[198:201], v[4:7], v[80:83]
	v_mfma_f32_16x16x32_bf16 v[96:99], v[198:201], v[186:189], v[84:87]
	v_mfma_f32_16x16x32_bf16 v[84:87], v[206:209], v[4:7], v[108:111]
	v_mfma_f32_16x16x32_bf16 v[80:83], v[206:209], v[186:189], v[104:107]
	v_mfma_f32_16x16x32_bf16 v[60:63], v[214:217], v[4:7], v[120:123]
	v_mfma_f32_16x16x32_bf16 v[56:59], v[214:217], v[186:189], v[124:127]
	s_setprio 0
	s_barrier
	ds_read_b128 v[218:221], v152
	ds_read_b128 v[222:225], v152 offset:1024
	ds_read_b128 v[226:229], v152 offset:2048
	ds_read_b128 v[230:233], v152 offset:3072
	s_waitcnt vmcnt(0)
	s_barrier
	s_waitcnt lgkmcnt(0)
	s_setprio 1
	v_mfma_f32_16x16x32_bf16 v[92:95], v[20:23], v[218:221], v[92:95]
	v_mfma_f32_16x16x32_bf16 v[20:23], v[20:23], v[226:229], v[88:91]
	v_mfma_f32_16x16x32_bf16 v[88:91], v[194:197], v[218:221], v[170:173]
	v_mfma_f32_16x16x32_bf16 v[104:107], v[194:197], v[226:229], v[174:177]
	v_mfma_f32_16x16x32_bf16 v[76:79], v[202:205], v[218:221], v[76:79]
	v_mfma_f32_16x16x32_bf16 v[72:75], v[202:205], v[226:229], v[72:75]
	v_mfma_f32_16x16x32_bf16 v[68:71], v[210:213], v[218:221], v[68:71]
	v_mfma_f32_16x16x32_bf16 v[64:67], v[210:213], v[226:229], v[64:67]
	v_mfma_f32_16x16x32_bf16 v[124:127], v[190:193], v[222:225], v[92:95]
	v_mfma_f32_16x16x32_bf16 v[120:123], v[190:193], v[230:233], v[20:23]
	v_mfma_f32_16x16x32_bf16 v[108:111], v[198:201], v[222:225], v[88:91]
	v_mfma_f32_16x16x32_bf16 v[104:107], v[198:201], v[230:233], v[104:107]
	v_mfma_f32_16x16x32_bf16 v[92:95], v[206:209], v[222:225], v[76:79]
	v_mfma_f32_16x16x32_bf16 v[88:91], v[206:209], v[230:233], v[72:75]
	v_mfma_f32_16x16x32_bf16 v[76:79], v[214:217], v[222:225], v[68:71]
	v_mfma_f32_16x16x32_bf16 v[72:75], v[214:217], v[230:233], v[64:67]
	s_setprio 0
	s_barrier
	s_nop 0
	ds_read_b128 v[64:67], v146 offset:49152
	ds_read_b128 v[170:173], v146 offset:50176
	ds_read_b128 v[68:71], v147 offset:49152
	ds_read_b128 v[174:177], v147 offset:50176
	ds_read_b128 v[190:193], v148 offset:49152
	ds_read_b128 v[194:197], v148 offset:50176
	ds_read_b128 v[198:201], v149 offset:49152
	ds_read_b128 v[202:205], v149 offset:50176
	s_barrier
	s_waitcnt lgkmcnt(0)
	s_setprio 1
	v_mfma_f32_16x16x32_bf16 v[20:23], v[64:67], v[0:3], v[154:157]
	v_mfma_f32_16x16x32_bf16 v[154:157], v[64:67], v[16:19], v[162:165]
	v_mfma_f32_16x16x32_bf16 v[162:165], v[68:71], v[0:3], v[52:55]
	v_mfma_f32_16x16x32_bf16 v[206:209], v[68:71], v[16:19], v[48:51]
	v_mfma_f32_16x16x32_bf16 v[44:47], v[190:193], v[0:3], v[44:47]
	v_mfma_f32_16x16x32_bf16 v[40:43], v[190:193], v[16:19], v[40:43]
	v_mfma_f32_16x16x32_bf16 v[0:3], v[198:201], v[0:3], v[36:39]
	v_mfma_f32_16x16x32_bf16 v[210:213], v[198:201], v[16:19], v[32:35]
	v_mfma_f32_16x16x32_bf16 v[52:55], v[170:173], v[4:7], v[20:23]
	v_mfma_f32_16x16x32_bf16 v[48:51], v[170:173], v[186:189], v[154:157]
	v_mfma_f32_16x16x32_bf16 v[36:39], v[174:177], v[4:7], v[162:165]
	v_mfma_f32_16x16x32_bf16 v[32:35], v[174:177], v[186:189], v[206:209]
	v_mfma_f32_16x16x32_bf16 v[20:23], v[194:197], v[4:7], v[44:47]
	v_mfma_f32_16x16x32_bf16 v[16:19], v[194:197], v[186:189], v[40:43]
	v_mfma_f32_16x16x32_bf16 v[4:7], v[202:205], v[4:7], v[0:3]
	v_mfma_f32_16x16x32_bf16 v[0:3], v[202:205], v[186:189], v[210:213]
	s_setprio 0
	s_setprio 1
	v_mfma_f32_16x16x32_bf16 v[28:31], v[64:67], v[218:221], v[28:31]
	v_mfma_f32_16x16x32_bf16 v[24:27], v[64:67], v[226:229], v[24:27]
	v_mfma_f32_16x16x32_bf16 v[40:43], v[68:71], v[218:221], v[158:161]
	v_mfma_f32_16x16x32_bf16 v[154:157], v[68:71], v[226:229], v[166:169]
	v_mfma_f32_16x16x32_bf16 v[12:15], v[190:193], v[218:221], v[12:15]
	v_mfma_f32_16x16x32_bf16 v[8:11], v[190:193], v[226:229], v[8:11]
	v_mfma_f32_16x16x32_bf16 v[158:161], v[198:201], v[218:221], v[178:181]
	v_mfma_f32_16x16x32_bf16 v[162:165], v[198:201], v[226:229], v[182:185]
	v_mfma_f32_16x16x32_bf16 v[68:71], v[170:173], v[222:225], v[28:31]
	v_mfma_f32_16x16x32_bf16 v[64:67], v[170:173], v[230:233], v[24:27]
	v_mfma_f32_16x16x32_bf16 v[44:47], v[174:177], v[222:225], v[40:43]
	v_mfma_f32_16x16x32_bf16 v[40:43], v[174:177], v[230:233], v[154:157]
	v_mfma_f32_16x16x32_bf16 v[28:31], v[194:197], v[222:225], v[12:15]
	v_mfma_f32_16x16x32_bf16 v[24:27], v[194:197], v[230:233], v[8:11]
	v_mfma_f32_16x16x32_bf16 v[12:15], v[202:205], v[222:225], v[158:161]
	v_mfma_f32_16x16x32_bf16 v[8:11], v[202:205], v[230:233], v[162:165]
	s_setprio 0
	s_barrier
	s_and_saveexec_b64 s[0:1], s[6:7]
	s_cbranch_execz .LBB0_273
	s_barrier

; #define STAGE_A(POFF, h, kt) STAGE_AX(POFF, h, kt, brow)
; #define STAGE_B(POFF, h, kt) STAGE_BX(POFF, h, kt, bcol)
; #define LDA(dst, b, h) _Pragma("unroll") for (int m = 0; m < 4; ++m) _Pragma("unroll") for (int k = 0; k < 2; ++k) \
;     dst[m][k] = *reinterpret_cast<const bf16x8*>((char*)SA(b, h) + lds_byte(wr * 64 + m * 16 + fr, k * 32 + fq * 8))
; #define LDB(dst, b, h) _Pragma("unroll") for (int n = 0; n < 2; ++n) _Pragma("unroll") for (int k = 0; k < 2; ++k) \
;     dst[n][k] = *reinterpret_cast<const bf16x8*>((char*)SB(b, h) + lds_byte(wc * 32 + n * 16 + fr, k * 32 + fq * 8))
; #define MMA(ai, bj, At_, Bt_) do { __builtin_amdgcn_s_setprio(1); \
;     _Pragma("unroll") for (int k = 0; k < 2; ++k) _Pragma("unroll") for (int m = 0; m < 4; ++m) _Pragma("unroll") for (int n = 0; n < 2; ++n) \
;       acc[ai][bj][m][n] = __builtin_amdgcn_mfma_f32_16x16x32_bf16(At_[m][k], Bt_[n][k], acc[ai][bj][m][n], 0, 0, 0); \
;     __builtin_amdgcn_s_setprio(0); } while (0)
; #define WAIT_V(n) asm volatile("s_waitcnt vmcnt(" #n ")" ::: "memory")
; #define BAR __builtin_amdgcn_s_barrier()
; #define SCHED __builtin_amdgcn_sched_barrier(0)
; template <int EPI, int N, int K>
; __device__ __forceinline__ void gemm_phase(const bf16_t* __restrict__ A, const bf16_t* __restrict__ Bt, const EpiArgs ea) {
;     ...
;     int brow, bcol; TILE_RC(w, brow, bcol);
;     f32x4 acc[2][2][4][2];
; #pragma unroll
;     for (int a = 0; a < 2; ++a)
; #pragma unroll
;       for (int b = 0; b < 2; ++b)
; #pragma unroll
;         for (int m = 0; m < 4; ++m)
; #pragma unroll
;           for (int n = 0; n < 2; ++n) acc[a][b][m][n] = (f32x4){0.f, 0.f, 0.f, 0.f};
;     bf16x8 At[4][2], B0[2][2], B1[2][2];
;     if (wr == 1) BAR;
;     if (w == (int)blockIdx.x) { WAIT_V(0); } else { WAIT_V(24); }
;     BAR;
;     BAR;
;     for (int t = 0; t < nt - 2; t += 2) {
;       LDB(B0, 0, 0); SCHED; LDA(At, 0, 0); STAGE_A(SA_OFF(1, 1), 1, t + 1);
;       WAIT_L(8); BAR; WAIT_L(0); MMA(0, 0, At, B0); BAR; SCHED;
;       LDB(B1, 0, 1); STAGE_B(SB_OFF(0, 0), 0, t + 2);
;       BAR; WAIT_L(0); MMA(0, 1, At, B1); BAR;
;       LDA(At, 0, 1); STAGE_A(SA_OFF(0, 0), 0, t + 2);
;       BAR; WAIT_L(0); MMA(1, 0, At, B0); BAR; SCHED;
;       STAGE_B(SB_OFF(0, 1), 1, t + 2);
;       WAIT_V(6); BAR; MMA(1, 1, At, B1); BAR;
.LBB0_389:
	s_lshl_b32 s2, s30, 6
	s_and_b32 s2, s2, 0x1c0
	s_ashr_i32 s3, s30, 3
	s_add_i32 s3, s2, s3
	s_ashr_i32 s2, s3, 31
	s_lshr_b32 s2, s2, 26
	s_add_i32 s12, s3, s2
	s_ashr_i32 s2, s12, 6
	s_andn2_b32 s12, s12, 63
	s_sub_i32 s31, s3, s12
	s_lshl_b32 s3, s31, 8
	s_lshl_b32 s12, s31, 5
	s_lshl_b32 s13, s31, 17
	s_and_b32 s31, s31, 7
	s_lshl_b32 s34, s2, 23
	s_lshl_b32 s31, s31, 20
	s_and_b32 s13, s13, 0xfff00000
	s_or_b32 s31, s34, s31
	s_mov_b32 s34, -2
	s_mov_b32 s35, 0
	s_barrier
	s_barrier
	ds_read_b128 v[132:135], v147
	ds_read_b128 v[156:159], v147 offset:1024
	ds_read_b128 v[160:163], v147 offset:2048
	ds_read_b128 v[164:167], v147 offset:3072
	ds_read_b128 v[168:171], v148
	ds_read_b128 v[172:175], v148 offset:1024
	ds_read_b128 v[176:179], v149
	ds_read_b128 v[180:183], v149 offset:1024
	ds_read_b128 v[184:187], v150
	ds_read_b128 v[188:191], v150 offset:1024
	ds_read_b128 v[192:195], v151
	ds_read_b128 v[196:199], v151 offset:1024
	ds_read_b128 v[218:221], v148 offset:16384
	ds_read_b128 v[222:225], v148 offset:17408
	ds_read_b128 v[226:229], v149 offset:16384
	ds_read_b128 v[230:233], v149 offset:17408
	ds_read_b128 v[238:241], v150 offset:16384
	ds_read_b128 v[242:245], v150 offset:17408
	s_add_i32 s36, s31, s35
	s_or_b32 s37, s36, 0x80080
	s_mov_b32 s62, s50
	s_mov_b32 m0, s28
	s_mov_b32 s63, s51
	buffer_load_dwordx4 v131, s[60:63], s37 offen lds
	s_mov_b32 m0, s29
	s_or_b32 s37, s36, 0xc0080
	buffer_load_dwordx4 v131, s[60:63], s37 offen lds
	s_setprio 1
	s_barrier
	s_waitcnt lgkmcnt(6)
	v_mfma_f32_16x16x32_bf16 v[124:127], v[168:171], v[132:135], 0
	v_mfma_f32_16x16x32_bf16 v[120:123], v[168:171], v[160:163], 0
	v_mfma_f32_16x16x32_bf16 v[116:119], v[176:179], v[132:135], 0
	v_mfma_f32_16x16x32_bf16 v[112:115], v[176:179], v[160:163], 0
	v_mfma_f32_16x16x32_bf16 v[108:111], v[184:187], v[132:135], 0
	v_mfma_f32_16x16x32_bf16 v[104:107], v[184:187], v[160:163], 0
	v_mfma_f32_16x16x32_bf16 v[100:103], v[192:195], v[132:135], 0
	v_mfma_f32_16x16x32_bf16 v[96:99], v[192:195], v[160:163], 0
	v_mfma_f32_16x16x32_bf16 v[124:127], v[172:175], v[156:159], v[124:127]
	v_mfma_f32_16x16x32_bf16 v[120:123], v[172:175], v[164:167], v[120:123]
	v_mfma_f32_16x16x32_bf16 v[116:119], v[180:183], v[156:159], v[116:119]
	v_mfma_f32_16x16x32_bf16 v[112:115], v[180:183], v[164:167], v[112:115]
	v_mfma_f32_16x16x32_bf16 v[108:111], v[188:191], v[156:159], v[108:111]
	v_mfma_f32_16x16x32_bf16 v[104:107], v[188:191], v[164:167], v[104:107]
	v_mfma_f32_16x16x32_bf16 v[100:103], v[196:199], v[156:159], v[100:103]
	v_mfma_f32_16x16x32_bf16 v[96:99], v[196:199], v[164:167], v[96:99]
	s_barrier
	s_setprio 0
	ds_read_b128 v[200:203], v152
	ds_read_b128 v[204:207], v152 offset:1024
	ds_read_b128 v[208:211], v152 offset:2048
	ds_read_b128 v[212:215], v152 offset:3072
	ds_read_b128 v[246:249], v151 offset:16384
	ds_read_b128 v[250:253], v151 offset:17408
	s_add_i32 s37, s13, s35
	s_mov_b32 m0, s15
	s_add_i32 s38, s37, 0x100
	buffer_load_dwordx4 v144, s[76:79], s38 offen lds
	s_mov_b32 m0, s16
	s_add_i32 s38, s37, 0x80100
	buffer_load_dwordx4 v144, s[76:79], s38 offen lds
	s_waitcnt vmcnt(6)
	s_setprio 1
	s_barrier
	s_waitcnt lgkmcnt(2)
	v_mfma_f32_16x16x32_bf16 v[92:95], v[168:171], v[200:203], 0
	v_mfma_f32_16x16x32_bf16 v[88:91], v[168:171], v[208:211], 0
	v_mfma_f32_16x16x32_bf16 v[84:87], v[176:179], v[200:203], 0
	v_mfma_f32_16x16x32_bf16 v[80:83], v[176:179], v[208:211], 0
	v_mfma_f32_16x16x32_bf16 v[76:79], v[184:187], v[200:203], 0
	v_mfma_f32_16x16x32_bf16 v[72:75], v[184:187], v[208:211], 0
	v_mfma_f32_16x16x32_bf16 v[68:71], v[192:195], v[200:203], 0
	v_mfma_f32_16x16x32_bf16 v[64:67], v[192:195], v[208:211], 0
	v_mfma_f32_16x16x32_bf16 v[92:95], v[172:175], v[204:207], v[92:95]
	v_mfma_f32_16x16x32_bf16 v[88:91], v[172:175], v[212:215], v[88:91]
	v_mfma_f32_16x16x32_bf16 v[84:87], v[180:183], v[204:207], v[84:87]
	v_mfma_f32_16x16x32_bf16 v[80:83], v[180:183], v[212:215], v[80:83]
	v_mfma_f32_16x16x32_bf16 v[76:79], v[188:191], v[204:207], v[76:79]
	v_mfma_f32_16x16x32_bf16 v[72:75], v[188:191], v[212:215], v[72:75]
	v_mfma_f32_16x16x32_bf16 v[68:71], v[196:199], v[204:207], v[68:71]
	v_mfma_f32_16x16x32_bf16 v[64:67], v[196:199], v[212:215], v[64:67]
	s_barrier
	s_setprio 0
	ds_read_b128 v[168:171], v148 offset:32768
	ds_read_b128 v[172:175], v148 offset:33792
	ds_read_b128 v[176:179], v149 offset:32768
	ds_read_b128 v[180:183], v149 offset:33792
	ds_read_b128 v[184:187], v150 offset:32768
	ds_read_b128 v[188:191], v150 offset:33792
	s_mov_b32 m0, s14
	s_add_i32 s38, s36, 0x100
	buffer_load_dwordx4 v131, s[60:63], s38 offen lds
	s_mov_b32 m0, s17
	s_add_i32 s39, s36, 0x40100
	buffer_load_dwordx4 v131, s[60:63], s39 offen lds
	s_waitcnt vmcnt(10)
	s_setprio 1
	s_barrier
	s_waitcnt lgkmcnt(6)
	v_mfma_f32_16x16x32_bf16 v[60:63], v[218:221], v[132:135], 0
	v_mfma_f32_16x16x32_bf16 v[56:59], v[218:221], v[160:163], 0
	v_mfma_f32_16x16x32_bf16 v[52:55], v[226:229], v[132:135], 0
	v_mfma_f32_16x16x32_bf16 v[48:51], v[226:229], v[160:163], 0
	v_mfma_f32_16x16x32_bf16 v[44:47], v[238:241], v[132:135], 0
	v_mfma_f32_16x16x32_bf16 v[40:43], v[238:241], v[160:163], 0
	v_mfma_f32_16x16x32_bf16 v[36:39], v[246:249], v[132:135], 0
	v_mfma_f32_16x16x32_bf16 v[32:35], v[246:249], v[160:163], 0
	v_mfma_f32_16x16x32_bf16 v[60:63], v[222:225], v[156:159], v[60:63]
	v_mfma_f32_16x16x32_bf16 v[56:59], v[222:225], v[164:167], v[56:59]
	v_mfma_f32_16x16x32_bf16 v[52:55], v[230:233], v[156:159], v[52:55]
	v_mfma_f32_16x16x32_bf16 v[48:51], v[230:233], v[164:167], v[48:51]
	v_mfma_f32_16x16x32_bf16 v[44:47], v[242:245], v[156:159], v[44:47]
	v_mfma_f32_16x16x32_bf16 v[40:43], v[242:245], v[164:167], v[40:43]
	v_mfma_f32_16x16x32_bf16 v[36:39], v[250:253], v[156:159], v[36:39]
	v_mfma_f32_16x16x32_bf16 v[32:35], v[250:253], v[164:167], v[32:35]
	s_barrier
; #define STAGE_A(POFF, h, kt) STAGE_AX(POFF, h, kt, brow)
; #define STAGE_B(POFF, h, kt) STAGE_BX(POFF, h, kt, bcol)
; #define LDA(dst, b, h) _Pragma("unroll") for (int m = 0; m < 4; ++m) _Pragma("unroll") for (int k = 0; k < 2; ++k) \
;     dst[m][k] = *reinterpret_cast<const bf16x8*>((char*)SA(b, h) + lds_byte(wr * 64 + m * 16 + fr, k * 32 + fq * 8))
; #define LDB(dst, b, h) _Pragma("unroll") for (int n = 0; n < 2; ++n) _Pragma("unroll") for (int k = 0; k < 2; ++k) \
;     dst[n][k] = *reinterpret_cast<const bf16x8*>((char*)SB(b, h) + lds_byte(wc * 32 + n * 16 + fr, k * 32 + fq * 8))
; #define MMA(ai, bj, At_, Bt_) do { __builtin_amdgcn_s_setprio(1); \
;     _Pragma("unroll") for (int k = 0; k < 2; ++k) _Pragma("unroll") for (int m = 0; m < 4; ++m) _Pragma("unroll") for (int n = 0; n < 2; ++n) \
;       acc[ai][bj][m][n] = __builtin_amdgcn_mfma_f32_16x16x32_bf16(At_[m][k], Bt_[n][k], acc[ai][bj][m][n], 0, 0, 0); \
;     __builtin_amdgcn_s_setprio(0); } while (0)
; #define WAIT_V(n) asm volatile("s_waitcnt vmcnt(" #n ")" ::: "memory")
; #define BAR __builtin_amdgcn_s_barrier()
; #define SCHED __builtin_amdgcn_sched_barrier(0)
; template <int EPI, int N, int K>
; __device__ __forceinline__ void gemm_phase(const bf16_t* __restrict__ A, const bf16_t* __restrict__ Bt, const EpiArgs ea) {
;     ...
;       BAR; WAIT_L(0); MMA(1, 0, At, B0); BAR; SCHED;
;       STAGE_B(SB_OFF(0, 1), 1, t + 2);
;       WAIT_V(6); BAR; MMA(1, 1, At, B1); BAR;
;       LDB(B0, 1, 0); SCHED; LDA(At, 1, 0); STAGE_A(SA_OFF(0, 1), 1, t + 2);
;       WAIT_L(8); BAR; WAIT_L(0); MMA(0, 0, At, B0); BAR; SCHED;
;       LDB(B1, 1, 1); STAGE_B(SB_OFF(1, 0), 0, t + 3);
;       BAR; WAIT_L(0); MMA(0, 1, At, B1); BAR;
;       LDA(At, 1, 1); STAGE_A(SA_OFF(1, 0), 0, t + 3);
;       BAR; WAIT_L(0); MMA(1, 0, At, B0); BAR; SCHED;
	s_setprio 0
	ds_read_b128 v[132:135], v153
	ds_read_b128 v[156:159], v153 offset:1024
	ds_read_b128 v[160:163], v153 offset:2048
	ds_read_b128 v[164:167], v153 offset:3072
	ds_read_b128 v[192:195], v151 offset:32768
	ds_read_b128 v[196:199], v151 offset:33792
	s_mov_b32 m0, s18
	s_add_i32 s39, s37, 0x2100
	buffer_load_dwordx4 v144, s[76:79], s39 offen lds
	s_mov_b32 m0, s19
	s_add_i32 s39, s37, 0x82100
	buffer_load_dwordx4 v144, s[76:79], s39 offen lds
	s_waitcnt vmcnt(6)
	s_setprio 1
	s_barrier
	v_mfma_f32_16x16x32_bf16 v[28:31], v[218:221], v[200:203], 0
	v_mfma_f32_16x16x32_bf16 v[24:27], v[218:221], v[208:211], 0
	v_mfma_f32_16x16x32_bf16 v[20:23], v[226:229], v[200:203], 0
	v_mfma_f32_16x16x32_bf16 v[16:19], v[226:229], v[208:211], 0
	v_mfma_f32_16x16x32_bf16 v[12:15], v[238:241], v[200:203], 0
	v_mfma_f32_16x16x32_bf16 v[8:11], v[238:241], v[208:211], 0
	v_mfma_f32_16x16x32_bf16 v[4:7], v[246:249], v[200:203], 0
	v_mfma_f32_16x16x32_bf16 v[0:3], v[246:249], v[208:211], 0
	v_mfma_f32_16x16x32_bf16 v[28:31], v[222:225], v[204:207], v[28:31]
	v_mfma_f32_16x16x32_bf16 v[24:27], v[222:225], v[212:215], v[24:27]
	v_mfma_f32_16x16x32_bf16 v[20:23], v[230:233], v[204:207], v[20:23]
	v_mfma_f32_16x16x32_bf16 v[16:19], v[230:233], v[212:215], v[16:19]
	v_mfma_f32_16x16x32_bf16 v[12:15], v[242:245], v[204:207], v[12:15]
	v_mfma_f32_16x16x32_bf16 v[8:11], v[242:245], v[212:215], v[8:11]
	v_mfma_f32_16x16x32_bf16 v[4:7], v[250:253], v[204:207], v[4:7]
	v_mfma_f32_16x16x32_bf16 v[0:3], v[250:253], v[212:215], v[0:3]
	s_barrier
	s_setprio 0
	ds_read_b128 v[218:221], v148 offset:49152
	ds_read_b128 v[222:225], v148 offset:50176
	ds_read_b128 v[226:229], v149 offset:49152
	ds_read_b128 v[230:233], v149 offset:50176
	ds_read_b128 v[238:241], v150 offset:49152
	ds_read_b128 v[242:245], v150 offset:50176
	s_mov_b32 m0, s20
	s_or_b32 s39, s38, 0x80000
	buffer_load_dwordx4 v131, s[60:63], s39 offen lds
	s_mov_b32 m0, s21
	s_or_b32 s38, s38, 0xc0000
	buffer_load_dwordx4 v131, s[60:63], s38 offen lds
	s_setprio 1
	s_barrier
	s_waitcnt lgkmcnt(6)
	v_mfma_f32_16x16x32_bf16 v[124:127], v[168:171], v[132:135], v[124:127]
	v_mfma_f32_16x16x32_bf16 v[120:123], v[168:171], v[160:163], v[120:123]
	v_mfma_f32_16x16x32_bf16 v[116:119], v[176:179], v[132:135], v[116:119]
	v_mfma_f32_16x16x32_bf16 v[112:115], v[176:179], v[160:163], v[112:115]
	v_mfma_f32_16x16x32_bf16 v[108:111], v[184:187], v[132:135], v[108:111]
	v_mfma_f32_16x16x32_bf16 v[104:107], v[184:187], v[160:163], v[104:107]
	v_mfma_f32_16x16x32_bf16 v[100:103], v[192:195], v[132:135], v[100:103]
	v_mfma_f32_16x16x32_bf16 v[96:99], v[192:195], v[160:163], v[96:99]
	v_mfma_f32_16x16x32_bf16 v[124:127], v[172:175], v[156:159], v[124:127]
	v_mfma_f32_16x16x32_bf16 v[120:123], v[172:175], v[164:167], v[120:123]
	v_mfma_f32_16x16x32_bf16 v[116:119], v[180:183], v[156:159], v[116:119]
	v_mfma_f32_16x16x32_bf16 v[112:115], v[180:183], v[164:167], v[112:115]
	v_mfma_f32_16x16x32_bf16 v[108:111], v[188:191], v[156:159], v[108:111]
	v_mfma_f32_16x16x32_bf16 v[104:107], v[188:191], v[164:167], v[104:107]
	v_mfma_f32_16x16x32_bf16 v[100:103], v[196:199], v[156:159], v[100:103]
	v_mfma_f32_16x16x32_bf16 v[96:99], v[196:199], v[164:167], v[96:99]
	s_barrier
	s_setprio 0
	ds_read_b128 v[200:203], v154
	ds_read_b128 v[204:207], v154 offset:1024
	ds_read_b128 v[208:211], v154 offset:2048
	ds_read_b128 v[212:215], v154 offset:3072
	ds_read_b128 v[246:249], v151 offset:49152
	ds_read_b128 v[250:253], v151 offset:50176
	s_mov_b32 m0, s22
	s_add_i32 s38, s37, 0x180
	buffer_load_dwordx4 v144, s[76:79], s38 offen lds
	s_mov_b32 m0, s23
	s_add_i32 s38, s37, 0x80180
	buffer_load_dwordx4 v144, s[76:79], s38 offen lds
	s_waitcnt vmcnt(6)
	s_setprio 1
	s_barrier
	s_waitcnt lgkmcnt(2)
	v_mfma_f32_16x16x32_bf16 v[92:95], v[168:171], v[200:203], v[92:95]
	v_mfma_f32_16x16x32_bf16 v[88:91], v[168:171], v[208:211], v[88:91]
	v_mfma_f32_16x16x32_bf16 v[84:87], v[176:179], v[200:203], v[84:87]
	v_mfma_f32_16x16x32_bf16 v[80:83], v[176:179], v[208:211], v[80:83]
	v_mfma_f32_16x16x32_bf16 v[76:79], v[184:187], v[200:203], v[76:79]
	v_mfma_f32_16x16x32_bf16 v[72:75], v[184:187], v[208:211], v[72:75]
	v_mfma_f32_16x16x32_bf16 v[68:71], v[192:195], v[200:203], v[68:71]
	v_mfma_f32_16x16x32_bf16 v[64:67], v[192:195], v[208:211], v[64:67]
	v_mfma_f32_16x16x32_bf16 v[92:95], v[172:175], v[204:207], v[92:95]
	v_mfma_f32_16x16x32_bf16 v[88:91], v[172:175], v[212:215], v[88:91]
	v_mfma_f32_16x16x32_bf16 v[84:87], v[180:183], v[204:207], v[84:87]
	v_mfma_f32_16x16x32_bf16 v[80:83], v[180:183], v[212:215], v[80:83]
	v_mfma_f32_16x16x32_bf16 v[76:79], v[188:191], v[204:207], v[76:79]
	v_mfma_f32_16x16x32_bf16 v[72:75], v[188:191], v[212:215], v[72:75]
	v_mfma_f32_16x16x32_bf16 v[68:71], v[196:199], v[204:207], v[68:71]
	v_mfma_f32_16x16x32_bf16 v[64:67], v[196:199], v[212:215], v[64:67]
	s_barrier
	s_setprio 0
	ds_read_b128 v[168:171], v148
	ds_read_b128 v[172:175], v148 offset:1024
	ds_read_b128 v[176:179], v149
	ds_read_b128 v[180:183], v149 offset:1024
	ds_read_b128 v[184:187], v150
	ds_read_b128 v[188:191], v150 offset:1024
	s_mov_b32 m0, s24
	s_add_i32 s38, s36, 0x180
	buffer_load_dwordx4 v131, s[60:63], s38 offen lds
	s_mov_b32 m0, s25
	s_add_i32 s36, s36, 0x40180
	buffer_load_dwordx4 v131, s[60:63], s36 offen lds
	s_waitcnt vmcnt(10)
	s_setprio 1
	s_barrier
; #define STAGE_A(POFF, h, kt) STAGE_AX(POFF, h, kt, brow)
; #define STAGE_B(POFF, h, kt) STAGE_BX(POFF, h, kt, bcol)
; #define LDA(dst, b, h) _Pragma("unroll") for (int m = 0; m < 4; ++m) _Pragma("unroll") for (int k = 0; k < 2; ++k) \
;     dst[m][k] = *reinterpret_cast<const bf16x8*>((char*)SA(b, h) + lds_byte(wr * 64 + m * 16 + fr, k * 32 + fq * 8))
; #define LDB(dst, b, h) _Pragma("unroll") for (int n = 0; n < 2; ++n) _Pragma("unroll") for (int k = 0; k < 2; ++k) \
;     dst[n][k] = *reinterpret_cast<const bf16x8*>((char*)SB(b, h) + lds_byte(wc * 32 + n * 16 + fr, k * 32 + fq * 8))
; #define MMA(ai, bj, At_, Bt_) do { __builtin_amdgcn_s_setprio(1); \
;     _Pragma("unroll") for (int k = 0; k < 2; ++k) _Pragma("unroll") for (int m = 0; m < 4; ++m) _Pragma("unroll") for (int n = 0; n < 2; ++n) \
;       acc[ai][bj][m][n] = __builtin_amdgcn_mfma_f32_16x16x32_bf16(At_[m][k], Bt_[n][k], acc[ai][bj][m][n], 0, 0, 0); \
;     __builtin_amdgcn_s_setprio(0); } while (0)
; #define WAIT_V(n) asm volatile("s_waitcnt vmcnt(" #n ")" ::: "memory")
; #define BAR __builtin_amdgcn_s_barrier()
; #define SCHED __builtin_amdgcn_sched_barrier(0)
; template <int EPI, int N, int K>
; __device__ __forceinline__ void gemm_phase(const bf16_t* __restrict__ A, const bf16_t* __restrict__ Bt, const EpiArgs ea) {
;     ...
;       LDB(B0, 0, 0); SCHED; LDA(At, 0, 0); STAGE_A(SA_OFF(1, 1), 1, t + 1);
;       WAIT_L(8); BAR; WAIT_L(0); MMA(0, 0, At, B0); BAR; SCHED;
;       LDB(B1, 0, 1); STAGE_B(SB_OFF(0, 0), 0, t + 2);
;       BAR; WAIT_L(0); MMA(0, 1, At, B1); BAR;
;       LDA(At, 0, 1); STAGE_A(SA_OFF(0, 0), 0, t + 2);
;       BAR; WAIT_L(0); MMA(1, 0, At, B0); BAR; SCHED;
;       STAGE_B(SB_OFF(0, 1), 1, t + 2);
;       WAIT_V(6); BAR; MMA(1, 1, At, B1); BAR;
;       LDB(B0, 1, 0); SCHED; LDA(At, 1, 0); STAGE_A(SA_OFF(0, 1), 1, t + 2);
;       WAIT_L(8); BAR; WAIT_L(0); MMA(0, 0, At, B0); BAR; SCHED;
;       LDB(B1, 1, 1); STAGE_B(SB_OFF(1, 0), 0, t + 3);
;       BAR; WAIT_L(0); MMA(0, 1, At, B1); BAR;
;       LDA(At, 1, 1); STAGE_A(SA_OFF(1, 0), 0, t + 3);
;       BAR; WAIT_L(0); MMA(1, 0, At, B0); BAR; SCHED;
;       STAGE_B(SB_OFF(1, 1), 1, t + 3);
;       WAIT_V(6); BAR; MMA(1, 1, At, B1); BAR;
	s_waitcnt lgkmcnt(6)
	v_mfma_f32_16x16x32_bf16 v[60:63], v[218:221], v[132:135], v[60:63]
	v_mfma_f32_16x16x32_bf16 v[56:59], v[218:221], v[160:163], v[56:59]
	v_mfma_f32_16x16x32_bf16 v[52:55], v[226:229], v[132:135], v[52:55]
	v_mfma_f32_16x16x32_bf16 v[48:51], v[226:229], v[160:163], v[48:51]
	v_mfma_f32_16x16x32_bf16 v[44:47], v[238:241], v[132:135], v[44:47]
	v_mfma_f32_16x16x32_bf16 v[40:43], v[238:241], v[160:163], v[40:43]
	v_mfma_f32_16x16x32_bf16 v[36:39], v[246:249], v[132:135], v[36:39]
	v_mfma_f32_16x16x32_bf16 v[32:35], v[246:249], v[160:163], v[32:35]
	v_mfma_f32_16x16x32_bf16 v[60:63], v[222:225], v[156:159], v[60:63]
	v_mfma_f32_16x16x32_bf16 v[56:59], v[222:225], v[164:167], v[56:59]
	v_mfma_f32_16x16x32_bf16 v[52:55], v[230:233], v[156:159], v[52:55]
	v_mfma_f32_16x16x32_bf16 v[48:51], v[230:233], v[164:167], v[48:51]
	v_mfma_f32_16x16x32_bf16 v[44:47], v[242:245], v[156:159], v[44:47]
	v_mfma_f32_16x16x32_bf16 v[40:43], v[242:245], v[164:167], v[40:43]
	v_mfma_f32_16x16x32_bf16 v[36:39], v[250:253], v[156:159], v[36:39]
	v_mfma_f32_16x16x32_bf16 v[32:35], v[250:253], v[164:167], v[32:35]
	s_barrier
	s_setprio 0
	ds_read_b128 v[132:135], v147
	ds_read_b128 v[156:159], v147 offset:1024
	ds_read_b128 v[160:163], v147 offset:2048
	ds_read_b128 v[164:167], v147 offset:3072
	ds_read_b128 v[192:195], v151
	ds_read_b128 v[196:199], v151 offset:1024
	s_mov_b32 m0, s26
	s_add_i32 s36, s37, 0x2180
	buffer_load_dwordx4 v144, s[76:79], s36 offen lds
	s_mov_b32 m0, s27
	s_add_i32 s37, s37, 0x82180
	buffer_load_dwordx4 v144, s[76:79], s37 offen lds
	s_waitcnt vmcnt(6)
	s_setprio 1
	s_barrier
	v_mfma_f32_16x16x32_bf16 v[28:31], v[218:221], v[200:203], v[28:31]
	v_mfma_f32_16x16x32_bf16 v[24:27], v[218:221], v[208:211], v[24:27]
	v_mfma_f32_16x16x32_bf16 v[20:23], v[226:229], v[200:203], v[20:23]
	v_mfma_f32_16x16x32_bf16 v[16:19], v[226:229], v[208:211], v[16:19]
	v_mfma_f32_16x16x32_bf16 v[12:15], v[238:241], v[200:203], v[12:15]
	v_mfma_f32_16x16x32_bf16 v[8:11], v[238:241], v[208:211], v[8:11]
	v_mfma_f32_16x16x32_bf16 v[4:7], v[246:249], v[200:203], v[4:7]
	v_mfma_f32_16x16x32_bf16 v[0:3], v[246:249], v[208:211], v[0:3]
	v_mfma_f32_16x16x32_bf16 v[28:31], v[222:225], v[204:207], v[28:31]
	v_mfma_f32_16x16x32_bf16 v[24:27], v[222:225], v[212:215], v[24:27]
	v_mfma_f32_16x16x32_bf16 v[20:23], v[230:233], v[204:207], v[20:23]
	v_mfma_f32_16x16x32_bf16 v[16:19], v[230:233], v[212:215], v[16:19]
	v_mfma_f32_16x16x32_bf16 v[12:15], v[242:245], v[204:207], v[12:15]
	v_mfma_f32_16x16x32_bf16 v[8:11], v[242:245], v[212:215], v[8:11]
	v_mfma_f32_16x16x32_bf16 v[4:7], v[250:253], v[204:207], v[4:7]
	v_mfma_f32_16x16x32_bf16 v[0:3], v[250:253], v[212:215], v[0:3]
	s_barrier
	s_setprio 0
	s_add_i32 s34, s34, 2
	s_addk_i32 s35, 0x100
	s_cmp_lt_u32 s34, 28
.LBB0_390:
	ds_read_b128 v[218:221], v148 offset:16384
	ds_read_b128 v[222:225], v148 offset:17408
	ds_read_b128 v[226:229], v149 offset:16384
	ds_read_b128 v[230:233], v149 offset:17408
	ds_read_b128 v[238:241], v150 offset:16384
	ds_read_b128 v[242:245], v150 offset:17408
	s_add_i32 s36, s31, s35
	s_or_b32 s37, s36, 0x80080
	s_mov_b32 s62, s50
	s_mov_b32 m0, s28
	s_mov_b32 s63, s51
	buffer_load_dwordx4 v131, s[60:63], s37 offen lds
	s_mov_b32 m0, s29
	s_or_b32 s37, s36, 0xc0080
	buffer_load_dwordx4 v131, s[60:63], s37 offen lds
	s_setprio 1
	s_barrier
	s_waitcnt lgkmcnt(6)
	v_mfma_f32_16x16x32_bf16 v[124:127], v[168:171], v[132:135], v[124:127]
	v_mfma_f32_16x16x32_bf16 v[120:123], v[168:171], v[160:163], v[120:123]
	v_mfma_f32_16x16x32_bf16 v[116:119], v[176:179], v[132:135], v[116:119]
	v_mfma_f32_16x16x32_bf16 v[112:115], v[176:179], v[160:163], v[112:115]
	v_mfma_f32_16x16x32_bf16 v[108:111], v[184:187], v[132:135], v[108:111]
	v_mfma_f32_16x16x32_bf16 v[104:107], v[184:187], v[160:163], v[104:107]
	v_mfma_f32_16x16x32_bf16 v[100:103], v[192:195], v[132:135], v[100:103]
	v_mfma_f32_16x16x32_bf16 v[96:99], v[192:195], v[160:163], v[96:99]
	v_mfma_f32_16x16x32_bf16 v[124:127], v[172:175], v[156:159], v[124:127]
	v_mfma_f32_16x16x32_bf16 v[120:123], v[172:175], v[164:167], v[120:123]
	v_mfma_f32_16x16x32_bf16 v[116:119], v[180:183], v[156:159], v[116:119]
	v_mfma_f32_16x16x32_bf16 v[112:115], v[180:183], v[164:167], v[112:115]
	v_mfma_f32_16x16x32_bf16 v[108:111], v[188:191], v[156:159], v[108:111]
	v_mfma_f32_16x16x32_bf16 v[104:107], v[188:191], v[164:167], v[104:107]
	v_mfma_f32_16x16x32_bf16 v[100:103], v[196:199], v[156:159], v[100:103]
	v_mfma_f32_16x16x32_bf16 v[96:99], v[196:199], v[164:167], v[96:99]
	s_barrier
	s_setprio 0
	ds_read_b128 v[200:203], v152
	ds_read_b128 v[204:207], v152 offset:1024
	ds_read_b128 v[208:211], v152 offset:2048
	ds_read_b128 v[212:215], v152 offset:3072
	ds_read_b128 v[246:249], v151 offset:16384
	ds_read_b128 v[250:253], v151 offset:17408
	s_add_i32 s37, s13, s35
	s_mov_b32 m0, s15
	s_add_i32 s38, s37, 0x100
	buffer_load_dwordx4 v144, s[76:79], s38 offen lds
	s_mov_b32 m0, s16
	s_add_i32 s38, s37, 0x80100
	buffer_load_dwordx4 v144, s[76:79], s38 offen lds
	s_waitcnt vmcnt(6)
	s_setprio 1
	s_barrier
; #define STAGE_A(POFF, h, kt) STAGE_AX(POFF, h, kt, brow)
; #define STAGE_B(POFF, h, kt) STAGE_BX(POFF, h, kt, bcol)
; #define LDA(dst, b, h) _Pragma("unroll") for (int m = 0; m < 4; ++m) _Pragma("unroll") for (int k = 0; k < 2; ++k) \
;     dst[m][k] = *reinterpret_cast<const bf16x8*>((char*)SA(b, h) + lds_byte(wr * 64 + m * 16 + fr, k * 32 + fq * 8))
; #define LDB(dst, b, h) _Pragma("unroll") for (int n = 0; n < 2; ++n) _Pragma("unroll") for (int k = 0; k < 2; ++k) \
;     dst[n][k] = *reinterpret_cast<const bf16x8*>((char*)SB(b, h) + lds_byte(wc * 32 + n * 16 + fr, k * 32 + fq * 8))
; #define MMA(ai, bj, At_, Bt_) do { __builtin_amdgcn_s_setprio(1); \
;     _Pragma("unroll") for (int k = 0; k < 2; ++k) _Pragma("unroll") for (int m = 0; m < 4; ++m) _Pragma("unroll") for (int n = 0; n < 2; ++n) \
;       acc[ai][bj][m][n] = __builtin_amdgcn_mfma_f32_16x16x32_bf16(At_[m][k], Bt_[n][k], acc[ai][bj][m][n], 0, 0, 0); \
;     __builtin_amdgcn_s_setprio(0); } while (0)
; #define WAIT_V(n) asm volatile("s_waitcnt vmcnt(" #n ")" ::: "memory")
; #define BAR __builtin_amdgcn_s_barrier()
; #define SCHED __builtin_amdgcn_sched_barrier(0)
; template <int EPI, int N, int K>
; __device__ __forceinline__ void gemm_phase(const bf16_t* __restrict__ A, const bf16_t* __restrict__ Bt, const EpiArgs ea) {
;     ...
;       LDA(At, 0, 1); STAGE_A(SA_OFF(0, 0), 0, t + 2);
;       BAR; WAIT_L(0); MMA(1, 0, At, B0); BAR; SCHED;
;       STAGE_B(SB_OFF(0, 1), 1, t + 2);
;       WAIT_V(6); BAR; MMA(1, 1, At, B1); BAR;
;       LDB(B0, 1, 0); SCHED; LDA(At, 1, 0); STAGE_A(SA_OFF(0, 1), 1, t + 2);
;       WAIT_L(8); BAR; WAIT_L(0); MMA(0, 0, At, B0); BAR; SCHED;
;       LDB(B1, 1, 1); STAGE_B(SB_OFF(1, 0), 0, t + 3);
;       BAR; WAIT_L(0); MMA(0, 1, At, B1); BAR;
	s_waitcnt lgkmcnt(2)
	v_mfma_f32_16x16x32_bf16 v[92:95], v[168:171], v[200:203], v[92:95]
	v_mfma_f32_16x16x32_bf16 v[88:91], v[168:171], v[208:211], v[88:91]
	v_mfma_f32_16x16x32_bf16 v[84:87], v[176:179], v[200:203], v[84:87]
	v_mfma_f32_16x16x32_bf16 v[80:83], v[176:179], v[208:211], v[80:83]
	v_mfma_f32_16x16x32_bf16 v[76:79], v[184:187], v[200:203], v[76:79]
	v_mfma_f32_16x16x32_bf16 v[72:75], v[184:187], v[208:211], v[72:75]
	v_mfma_f32_16x16x32_bf16 v[68:71], v[192:195], v[200:203], v[68:71]
	v_mfma_f32_16x16x32_bf16 v[64:67], v[192:195], v[208:211], v[64:67]
	v_mfma_f32_16x16x32_bf16 v[92:95], v[172:175], v[204:207], v[92:95]
	v_mfma_f32_16x16x32_bf16 v[88:91], v[172:175], v[212:215], v[88:91]
	v_mfma_f32_16x16x32_bf16 v[84:87], v[180:183], v[204:207], v[84:87]
	v_mfma_f32_16x16x32_bf16 v[80:83], v[180:183], v[212:215], v[80:83]
	v_mfma_f32_16x16x32_bf16 v[76:79], v[188:191], v[204:207], v[76:79]
	v_mfma_f32_16x16x32_bf16 v[72:75], v[188:191], v[212:215], v[72:75]
	v_mfma_f32_16x16x32_bf16 v[68:71], v[196:199], v[204:207], v[68:71]
	v_mfma_f32_16x16x32_bf16 v[64:67], v[196:199], v[212:215], v[64:67]
	s_barrier
	s_setprio 0
	ds_read_b128 v[168:171], v148 offset:32768
	ds_read_b128 v[172:175], v148 offset:33792
	ds_read_b128 v[176:179], v149 offset:32768
	ds_read_b128 v[180:183], v149 offset:33792
	ds_read_b128 v[184:187], v150 offset:32768
	ds_read_b128 v[188:191], v150 offset:33792
	s_mov_b32 m0, s14
	s_add_i32 s38, s36, 0x100
	buffer_load_dwordx4 v131, s[60:63], s38 offen lds
	s_mov_b32 m0, s17
	s_add_i32 s39, s36, 0x40100
	buffer_load_dwordx4 v131, s[60:63], s39 offen lds
	s_waitcnt vmcnt(10)
	s_setprio 1
	s_barrier
	s_waitcnt lgkmcnt(6)
	v_mfma_f32_16x16x32_bf16 v[60:63], v[218:221], v[132:135], v[60:63]
	v_mfma_f32_16x16x32_bf16 v[56:59], v[218:221], v[160:163], v[56:59]
	v_mfma_f32_16x16x32_bf16 v[52:55], v[226:229], v[132:135], v[52:55]
	v_mfma_f32_16x16x32_bf16 v[48:51], v[226:229], v[160:163], v[48:51]
	v_mfma_f32_16x16x32_bf16 v[44:47], v[238:241], v[132:135], v[44:47]
	v_mfma_f32_16x16x32_bf16 v[40:43], v[238:241], v[160:163], v[40:43]
	v_mfma_f32_16x16x32_bf16 v[36:39], v[246:249], v[132:135], v[36:39]
	v_mfma_f32_16x16x32_bf16 v[32:35], v[246:249], v[160:163], v[32:35]
	v_mfma_f32_16x16x32_bf16 v[60:63], v[222:225], v[156:159], v[60:63]
	v_mfma_f32_16x16x32_bf16 v[56:59], v[222:225], v[164:167], v[56:59]
	v_mfma_f32_16x16x32_bf16 v[52:55], v[230:233], v[156:159], v[52:55]
	v_mfma_f32_16x16x32_bf16 v[48:51], v[230:233], v[164:167], v[48:51]
	v_mfma_f32_16x16x32_bf16 v[44:47], v[242:245], v[156:159], v[44:47]
	v_mfma_f32_16x16x32_bf16 v[40:43], v[242:245], v[164:167], v[40:43]
	v_mfma_f32_16x16x32_bf16 v[36:39], v[250:253], v[156:159], v[36:39]
	v_mfma_f32_16x16x32_bf16 v[32:35], v[250:253], v[164:167], v[32:35]
	s_barrier
	s_setprio 0
	ds_read_b128 v[132:135], v153
	ds_read_b128 v[156:159], v153 offset:1024
	ds_read_b128 v[160:163], v153 offset:2048
	ds_read_b128 v[164:167], v153 offset:3072
	ds_read_b128 v[192:195], v151 offset:32768
	ds_read_b128 v[196:199], v151 offset:33792
	s_mov_b32 m0, s18
	s_add_i32 s39, s37, 0x2100
	buffer_load_dwordx4 v144, s[76:79], s39 offen lds
	s_mov_b32 m0, s19
	s_add_i32 s39, s37, 0x82100
	buffer_load_dwordx4 v144, s[76:79], s39 offen lds
	s_waitcnt vmcnt(6)
	s_setprio 1
	s_barrier
	v_mfma_f32_16x16x32_bf16 v[28:31], v[218:221], v[200:203], v[28:31]
	v_mfma_f32_16x16x32_bf16 v[24:27], v[218:221], v[208:211], v[24:27]
	v_mfma_f32_16x16x32_bf16 v[20:23], v[226:229], v[200:203], v[20:23]
	v_mfma_f32_16x16x32_bf16 v[16:19], v[226:229], v[208:211], v[16:19]
	v_mfma_f32_16x16x32_bf16 v[12:15], v[238:241], v[200:203], v[12:15]
	v_mfma_f32_16x16x32_bf16 v[8:11], v[238:241], v[208:211], v[8:11]
	v_mfma_f32_16x16x32_bf16 v[4:7], v[246:249], v[200:203], v[4:7]
	v_mfma_f32_16x16x32_bf16 v[0:3], v[246:249], v[208:211], v[0:3]
	v_mfma_f32_16x16x32_bf16 v[28:31], v[222:225], v[204:207], v[28:31]
	v_mfma_f32_16x16x32_bf16 v[24:27], v[222:225], v[212:215], v[24:27]
	v_mfma_f32_16x16x32_bf16 v[20:23], v[230:233], v[204:207], v[20:23]
	v_mfma_f32_16x16x32_bf16 v[16:19], v[230:233], v[212:215], v[16:19]
	v_mfma_f32_16x16x32_bf16 v[12:15], v[242:245], v[204:207], v[12:15]
	v_mfma_f32_16x16x32_bf16 v[8:11], v[242:245], v[212:215], v[8:11]
	v_mfma_f32_16x16x32_bf16 v[4:7], v[250:253], v[204:207], v[4:7]
	v_mfma_f32_16x16x32_bf16 v[0:3], v[250:253], v[212:215], v[0:3]
	s_barrier
	s_setprio 0
	ds_read_b128 v[218:221], v148 offset:49152
	ds_read_b128 v[222:225], v148 offset:50176
	ds_read_b128 v[226:229], v149 offset:49152
	ds_read_b128 v[230:233], v149 offset:50176
	ds_read_b128 v[238:241], v150 offset:49152
	ds_read_b128 v[242:245], v150 offset:50176
	s_mov_b32 m0, s20
	s_or_b32 s39, s38, 0x80000
	buffer_load_dwordx4 v131, s[60:63], s39 offen lds
	s_mov_b32 m0, s21
	s_or_b32 s38, s38, 0xc0000
	buffer_load_dwordx4 v131, s[60:63], s38 offen lds
	s_setprio 1
	s_barrier
	s_waitcnt lgkmcnt(6)
	v_mfma_f32_16x16x32_bf16 v[124:127], v[168:171], v[132:135], v[124:127]
	v_mfma_f32_16x16x32_bf16 v[120:123], v[168:171], v[160:163], v[120:123]
	v_mfma_f32_16x16x32_bf16 v[116:119], v[176:179], v[132:135], v[116:119]
	v_mfma_f32_16x16x32_bf16 v[112:115], v[176:179], v[160:163], v[112:115]
	v_mfma_f32_16x16x32_bf16 v[108:111], v[184:187], v[132:135], v[108:111]
	v_mfma_f32_16x16x32_bf16 v[104:107], v[184:187], v[160:163], v[104:107]
	v_mfma_f32_16x16x32_bf16 v[100:103], v[192:195], v[132:135], v[100:103]
	v_mfma_f32_16x16x32_bf16 v[96:99], v[192:195], v[160:163], v[96:99]
	v_mfma_f32_16x16x32_bf16 v[124:127], v[172:175], v[156:159], v[124:127]
	v_mfma_f32_16x16x32_bf16 v[120:123], v[172:175], v[164:167], v[120:123]
	v_mfma_f32_16x16x32_bf16 v[116:119], v[180:183], v[156:159], v[116:119]
	v_mfma_f32_16x16x32_bf16 v[112:115], v[180:183], v[164:167], v[112:115]
	v_mfma_f32_16x16x32_bf16 v[108:111], v[188:191], v[156:159], v[108:111]
	v_mfma_f32_16x16x32_bf16 v[104:107], v[188:191], v[164:167], v[104:107]
	v_mfma_f32_16x16x32_bf16 v[100:103], v[196:199], v[156:159], v[100:103]
	v_mfma_f32_16x16x32_bf16 v[96:99], v[196:199], v[164:167], v[96:99]
	s_barrier
; #define STAGE_A(POFF, h, kt) STAGE_AX(POFF, h, kt, brow)
; #define STAGE_B(POFF, h, kt) STAGE_BX(POFF, h, kt, bcol)
; #define LDA(dst, b, h) _Pragma("unroll") for (int m = 0; m < 4; ++m) _Pragma("unroll") for (int k = 0; k < 2; ++k) \
;     dst[m][k] = *reinterpret_cast<const bf16x8*>((char*)SA(b, h) + lds_byte(wr * 64 + m * 16 + fr, k * 32 + fq * 8))
; #define LDB(dst, b, h) _Pragma("unroll") for (int n = 0; n < 2; ++n) _Pragma("unroll") for (int k = 0; k < 2; ++k) \
;     dst[n][k] = *reinterpret_cast<const bf16x8*>((char*)SB(b, h) + lds_byte(wc * 32 + n * 16 + fr, k * 32 + fq * 8))
; #define MMA(ai, bj, At_, Bt_) do { __builtin_amdgcn_s_setprio(1); \
;     _Pragma("unroll") for (int k = 0; k < 2; ++k) _Pragma("unroll") for (int m = 0; m < 4; ++m) _Pragma("unroll") for (int n = 0; n < 2; ++n) \
;       acc[ai][bj][m][n] = __builtin_amdgcn_mfma_f32_16x16x32_bf16(At_[m][k], Bt_[n][k], acc[ai][bj][m][n], 0, 0, 0); \
;     __builtin_amdgcn_s_setprio(0); } while (0)
; #define WAIT_V(n) asm volatile("s_waitcnt vmcnt(" #n ")" ::: "memory")
; #define BAR __builtin_amdgcn_s_barrier()
; #define SCHED __builtin_amdgcn_sched_barrier(0)
; template <int EPI, int N, int K>
; __device__ __forceinline__ void gemm_phase(const bf16_t* __restrict__ A, const bf16_t* __restrict__ Bt, const EpiArgs ea) {
;     ...
;       LDA(At, 1, 1); STAGE_A(SA_OFF(1, 0), 0, t + 3);
;       BAR; WAIT_L(0); MMA(1, 0, At, B0); BAR; SCHED;
;       STAGE_B(SB_OFF(1, 1), 1, t + 3);
;       WAIT_V(6); BAR; MMA(1, 1, At, B1); BAR;
;     }
;     { LDB(B0, 0, 0); LDA(At, 0, 0); STAGE_A(SA_OFF(1, 1), 1, nt - 1);
	s_setprio 0
	ds_read_b128 v[200:203], v154
	ds_read_b128 v[204:207], v154 offset:1024
	ds_read_b128 v[208:211], v154 offset:2048
	ds_read_b128 v[212:215], v154 offset:3072
	ds_read_b128 v[246:249], v151 offset:49152
	ds_read_b128 v[250:253], v151 offset:50176
	s_mov_b32 m0, s22
	s_add_i32 s38, s37, 0x180
	buffer_load_dwordx4 v144, s[76:79], s38 offen lds
	s_mov_b32 m0, s23
	s_add_i32 s38, s37, 0x80180
	buffer_load_dwordx4 v144, s[76:79], s38 offen lds
	s_waitcnt vmcnt(6)
	s_setprio 1
	s_barrier
	s_waitcnt lgkmcnt(2)
	v_mfma_f32_16x16x32_bf16 v[92:95], v[168:171], v[200:203], v[92:95]
	v_mfma_f32_16x16x32_bf16 v[88:91], v[168:171], v[208:211], v[88:91]
	v_mfma_f32_16x16x32_bf16 v[84:87], v[176:179], v[200:203], v[84:87]
	v_mfma_f32_16x16x32_bf16 v[80:83], v[176:179], v[208:211], v[80:83]
	v_mfma_f32_16x16x32_bf16 v[76:79], v[184:187], v[200:203], v[76:79]
	v_mfma_f32_16x16x32_bf16 v[72:75], v[184:187], v[208:211], v[72:75]
	v_mfma_f32_16x16x32_bf16 v[68:71], v[192:195], v[200:203], v[68:71]
	v_mfma_f32_16x16x32_bf16 v[64:67], v[192:195], v[208:211], v[64:67]
	v_mfma_f32_16x16x32_bf16 v[92:95], v[172:175], v[204:207], v[92:95]
	v_mfma_f32_16x16x32_bf16 v[88:91], v[172:175], v[212:215], v[88:91]
	v_mfma_f32_16x16x32_bf16 v[84:87], v[180:183], v[204:207], v[84:87]
	v_mfma_f32_16x16x32_bf16 v[80:83], v[180:183], v[212:215], v[80:83]
	v_mfma_f32_16x16x32_bf16 v[76:79], v[188:191], v[204:207], v[76:79]
	v_mfma_f32_16x16x32_bf16 v[72:75], v[188:191], v[212:215], v[72:75]
	v_mfma_f32_16x16x32_bf16 v[68:71], v[196:199], v[204:207], v[68:71]
	v_mfma_f32_16x16x32_bf16 v[64:67], v[196:199], v[212:215], v[64:67]
	s_barrier
	s_setprio 0
	ds_read_b128 v[168:171], v148
	ds_read_b128 v[172:175], v148 offset:1024
	ds_read_b128 v[176:179], v149
	ds_read_b128 v[180:183], v149 offset:1024
	ds_read_b128 v[184:187], v150
	ds_read_b128 v[188:191], v150 offset:1024
	s_mov_b32 m0, s24
	s_add_i32 s38, s36, 0x180
	buffer_load_dwordx4 v131, s[60:63], s38 offen lds
	s_mov_b32 m0, s25
	s_add_i32 s36, s36, 0x40180
	buffer_load_dwordx4 v131, s[60:63], s36 offen lds
	s_waitcnt vmcnt(10)
	s_setprio 1
	s_barrier
	s_waitcnt lgkmcnt(6)
	v_mfma_f32_16x16x32_bf16 v[60:63], v[218:221], v[132:135], v[60:63]
	v_mfma_f32_16x16x32_bf16 v[56:59], v[218:221], v[160:163], v[56:59]
	v_mfma_f32_16x16x32_bf16 v[52:55], v[226:229], v[132:135], v[52:55]
	v_mfma_f32_16x16x32_bf16 v[48:51], v[226:229], v[160:163], v[48:51]
	v_mfma_f32_16x16x32_bf16 v[44:47], v[238:241], v[132:135], v[44:47]
	v_mfma_f32_16x16x32_bf16 v[40:43], v[238:241], v[160:163], v[40:43]
	v_mfma_f32_16x16x32_bf16 v[36:39], v[246:249], v[132:135], v[36:39]
	v_mfma_f32_16x16x32_bf16 v[32:35], v[246:249], v[160:163], v[32:35]
	v_mfma_f32_16x16x32_bf16 v[60:63], v[222:225], v[156:159], v[60:63]
	v_mfma_f32_16x16x32_bf16 v[56:59], v[222:225], v[164:167], v[56:59]
	v_mfma_f32_16x16x32_bf16 v[52:55], v[230:233], v[156:159], v[52:55]
	v_mfma_f32_16x16x32_bf16 v[48:51], v[230:233], v[164:167], v[48:51]
	v_mfma_f32_16x16x32_bf16 v[44:47], v[242:245], v[156:159], v[44:47]
	v_mfma_f32_16x16x32_bf16 v[40:43], v[242:245], v[164:167], v[40:43]
	v_mfma_f32_16x16x32_bf16 v[36:39], v[250:253], v[156:159], v[36:39]
	v_mfma_f32_16x16x32_bf16 v[32:35], v[250:253], v[164:167], v[32:35]
	s_barrier
	s_setprio 0
	ds_read_b128 v[132:135], v147
	ds_read_b128 v[156:159], v147 offset:1024
	ds_read_b128 v[160:163], v147 offset:2048
	ds_read_b128 v[164:167], v147 offset:3072
	ds_read_b128 v[192:195], v151
	ds_read_b128 v[196:199], v151 offset:1024
	s_mov_b32 m0, s26
	s_add_i32 s36, s37, 0x2180
	buffer_load_dwordx4 v144, s[76:79], s36 offen lds
	s_mov_b32 m0, s27
	s_add_i32 s37, s37, 0x82180
	buffer_load_dwordx4 v144, s[76:79], s37 offen lds
	s_waitcnt vmcnt(6)
	s_setprio 1
	s_barrier
	v_mfma_f32_16x16x32_bf16 v[28:31], v[218:221], v[200:203], v[28:31]
	v_mfma_f32_16x16x32_bf16 v[24:27], v[218:221], v[208:211], v[24:27]
	v_mfma_f32_16x16x32_bf16 v[20:23], v[226:229], v[200:203], v[20:23]
	v_mfma_f32_16x16x32_bf16 v[16:19], v[226:229], v[208:211], v[16:19]
	v_mfma_f32_16x16x32_bf16 v[12:15], v[238:241], v[200:203], v[12:15]
	v_mfma_f32_16x16x32_bf16 v[8:11], v[238:241], v[208:211], v[8:11]
	v_mfma_f32_16x16x32_bf16 v[4:7], v[246:249], v[200:203], v[4:7]
	v_mfma_f32_16x16x32_bf16 v[0:3], v[246:249], v[208:211], v[0:3]
	v_mfma_f32_16x16x32_bf16 v[28:31], v[222:225], v[204:207], v[28:31]
	v_mfma_f32_16x16x32_bf16 v[24:27], v[222:225], v[212:215], v[24:27]
	v_mfma_f32_16x16x32_bf16 v[20:23], v[230:233], v[204:207], v[20:23]
	v_mfma_f32_16x16x32_bf16 v[16:19], v[230:233], v[212:215], v[16:19]
	v_mfma_f32_16x16x32_bf16 v[12:15], v[242:245], v[204:207], v[12:15]
	v_mfma_f32_16x16x32_bf16 v[8:11], v[242:245], v[212:215], v[8:11]
	v_mfma_f32_16x16x32_bf16 v[4:7], v[250:253], v[204:207], v[4:7]
	v_mfma_f32_16x16x32_bf16 v[0:3], v[250:253], v[212:215], v[0:3]
	s_barrier
	s_setprio 0
	s_add_i32 s34, s34, 2
	s_addk_i32 s35, 0x100
	s_cmp_lt_u32 s34, 28
	s_cbranch_scc1 .LBB0_390
	s_and_b32 s3, s3, 0x700
	s_lshl_b32 s2, s2, 11
	s_or_b32 s31, s3, s2
	s_lshl_b32 s2, s31, 12
	s_or_b32 s3, s2, 0x80f80
	s_mov_b32 m0, s28
	s_nop 0
	buffer_load_dwordx4 v131, s[60:63], s3 offen lds
	s_or_b32 s2, s2, 0xc0f80
	s_mov_b32 m0, s29
	s_nop 0
	buffer_load_dwordx4 v131, s[60:63], s2 offen lds
	s_barrier
; #define STAGE_A(POFF, h, kt) STAGE_AX(POFF, h, kt, brow)
; #define LDA(dst, b, h) _Pragma("unroll") for (int m = 0; m < 4; ++m) _Pragma("unroll") for (int k = 0; k < 2; ++k) \
;     dst[m][k] = *reinterpret_cast<const bf16x8*>((char*)SA(b, h) + lds_byte(wr * 64 + m * 16 + fr, k * 32 + fq * 8))
; #define LDB(dst, b, h) _Pragma("unroll") for (int n = 0; n < 2; ++n) _Pragma("unroll") for (int k = 0; k < 2; ++k) \
;     dst[n][k] = *reinterpret_cast<const bf16x8*>((char*)SB(b, h) + lds_byte(wc * 32 + n * 16 + fr, k * 32 + fq * 8))
; #define MMA(ai, bj, At_, Bt_) do { __builtin_amdgcn_s_setprio(1); \
;     _Pragma("unroll") for (int k = 0; k < 2; ++k) _Pragma("unroll") for (int m = 0; m < 4; ++m) _Pragma("unroll") for (int n = 0; n < 2; ++n) \
;       acc[ai][bj][m][n] = __builtin_amdgcn_mfma_f32_16x16x32_bf16(At_[m][k], Bt_[n][k], acc[ai][bj][m][n], 0, 0, 0); \
;     __builtin_amdgcn_s_setprio(0); } while (0)
; #define WAIT_V(n) asm volatile("s_waitcnt vmcnt(" #n ")" ::: "memory")
; #define BAR __builtin_amdgcn_s_barrier()
; template <int EPI, int N, int K>
; __device__ __forceinline__ void gemm_phase(const bf16_t* __restrict__ A, const bf16_t* __restrict__ Bt, const EpiArgs ea) {
;     ...
;     { LDB(B0, 0, 0); LDA(At, 0, 0); STAGE_A(SA_OFF(1, 1), 1, nt - 1);
;       BAR; WAIT_L(0); MMA(0, 0, At, B0); BAR;
;       LDB(B1, 0, 1); BAR; WAIT_L(0); MMA(0, 1, At, B1); BAR;
;       LDA(At, 0, 1); WAIT_V(4); BAR; WAIT_L(0); MMA(1, 0, At, B0); MMA(1, 1, At, B1); BAR; }
;     { LDB(B0, 1, 0); LDA(At, 1, 0); WAIT_V(2); BAR; WAIT_L(0); MMA(0, 0, At, B0); BAR;
	s_waitcnt lgkmcnt(0)
	s_setprio 1
	v_mfma_f32_16x16x32_bf16 v[124:127], v[168:171], v[132:135], v[124:127]
	v_mfma_f32_16x16x32_bf16 v[120:123], v[168:171], v[160:163], v[120:123]
	v_mfma_f32_16x16x32_bf16 v[116:119], v[176:179], v[132:135], v[116:119]
	v_mfma_f32_16x16x32_bf16 v[112:115], v[176:179], v[160:163], v[112:115]
	v_mfma_f32_16x16x32_bf16 v[108:111], v[184:187], v[132:135], v[108:111]
	v_mfma_f32_16x16x32_bf16 v[104:107], v[184:187], v[160:163], v[104:107]
	v_mfma_f32_16x16x32_bf16 v[100:103], v[192:195], v[132:135], v[100:103]
	v_mfma_f32_16x16x32_bf16 v[96:99], v[192:195], v[160:163], v[96:99]
	v_mfma_f32_16x16x32_bf16 v[124:127], v[172:175], v[156:159], v[124:127]
	v_mfma_f32_16x16x32_bf16 v[120:123], v[172:175], v[164:167], v[120:123]
	v_mfma_f32_16x16x32_bf16 v[116:119], v[180:183], v[156:159], v[116:119]
	v_mfma_f32_16x16x32_bf16 v[112:115], v[180:183], v[164:167], v[112:115]
	v_mfma_f32_16x16x32_bf16 v[108:111], v[188:191], v[156:159], v[108:111]
	v_mfma_f32_16x16x32_bf16 v[104:107], v[188:191], v[164:167], v[104:107]
	v_mfma_f32_16x16x32_bf16 v[100:103], v[196:199], v[156:159], v[100:103]
	v_mfma_f32_16x16x32_bf16 v[96:99], v[196:199], v[164:167], v[96:99]
	s_setprio 0
	s_barrier
	ds_read_b128 v[200:203], v152
	ds_read_b128 v[204:207], v152 offset:1024
	ds_read_b128 v[208:211], v152 offset:2048
	ds_read_b128 v[212:215], v152 offset:3072
	s_barrier
	s_waitcnt lgkmcnt(0)
	s_setprio 1
	v_mfma_f32_16x16x32_bf16 v[92:95], v[168:171], v[200:203], v[92:95]
	v_mfma_f32_16x16x32_bf16 v[88:91], v[168:171], v[208:211], v[88:91]
	v_mfma_f32_16x16x32_bf16 v[76:79], v[184:187], v[200:203], v[76:79]
	v_mfma_f32_16x16x32_bf16 v[72:75], v[184:187], v[208:211], v[72:75]
	v_mfma_f32_16x16x32_bf16 v[84:87], v[176:179], v[200:203], v[84:87]
	v_mfma_f32_16x16x32_bf16 v[80:83], v[176:179], v[208:211], v[80:83]
	v_mfma_f32_16x16x32_bf16 v[68:71], v[192:195], v[200:203], v[68:71]
	v_mfma_f32_16x16x32_bf16 v[64:67], v[192:195], v[208:211], v[64:67]
	v_mfma_f32_16x16x32_bf16 v[92:95], v[172:175], v[204:207], v[92:95]
	v_mfma_f32_16x16x32_bf16 v[88:91], v[172:175], v[212:215], v[88:91]
	v_mfma_f32_16x16x32_bf16 v[76:79], v[188:191], v[204:207], v[76:79]
	v_mfma_f32_16x16x32_bf16 v[72:75], v[188:191], v[212:215], v[72:75]
	v_mfma_f32_16x16x32_bf16 v[168:171], v[180:183], v[204:207], v[84:87]
	v_mfma_f32_16x16x32_bf16 v[172:175], v[180:183], v[212:215], v[80:83]
	v_mfma_f32_16x16x32_bf16 v[176:179], v[196:199], v[204:207], v[68:71]
	v_mfma_f32_16x16x32_bf16 v[180:183], v[196:199], v[212:215], v[64:67]
	s_setprio 0
	s_barrier
	s_nop 0
	ds_read_b128 v[64:67], v148 offset:16384
	ds_read_b128 v[68:71], v148 offset:17408
	ds_read_b128 v[80:83], v149 offset:16384
	ds_read_b128 v[84:87], v149 offset:17408
	ds_read_b128 v[184:187], v150 offset:16384
	ds_read_b128 v[188:191], v150 offset:17408
	ds_read_b128 v[192:195], v151 offset:16384
	ds_read_b128 v[196:199], v151 offset:17408
	s_waitcnt vmcnt(4)
	s_barrier
	s_waitcnt lgkmcnt(0)
	s_setprio 1
	v_mfma_f32_16x16x32_bf16 v[60:63], v[64:67], v[132:135], v[60:63]
	v_mfma_f32_16x16x32_bf16 v[56:59], v[64:67], v[160:163], v[56:59]
	v_mfma_f32_16x16x32_bf16 v[52:55], v[80:83], v[132:135], v[52:55]
	v_mfma_f32_16x16x32_bf16 v[48:51], v[80:83], v[160:163], v[48:51]
	v_mfma_f32_16x16x32_bf16 v[44:47], v[184:187], v[132:135], v[44:47]
	v_mfma_f32_16x16x32_bf16 v[40:43], v[184:187], v[160:163], v[40:43]
	v_mfma_f32_16x16x32_bf16 v[36:39], v[192:195], v[132:135], v[36:39]
	v_mfma_f32_16x16x32_bf16 v[32:35], v[192:195], v[160:163], v[32:35]
	v_mfma_f32_16x16x32_bf16 v[60:63], v[68:71], v[156:159], v[60:63]
	v_mfma_f32_16x16x32_bf16 v[56:59], v[68:71], v[164:167], v[56:59]
	v_mfma_f32_16x16x32_bf16 v[52:55], v[84:87], v[156:159], v[52:55]
	v_mfma_f32_16x16x32_bf16 v[48:51], v[84:87], v[164:167], v[48:51]
	v_mfma_f32_16x16x32_bf16 v[44:47], v[188:191], v[156:159], v[44:47]
	v_mfma_f32_16x16x32_bf16 v[40:43], v[188:191], v[164:167], v[40:43]
	v_mfma_f32_16x16x32_bf16 v[36:39], v[196:199], v[156:159], v[36:39]
	v_mfma_f32_16x16x32_bf16 v[32:35], v[196:199], v[164:167], v[32:35]
	s_setprio 0
	s_setprio 1
	v_mfma_f32_16x16x32_bf16 v[28:31], v[64:67], v[200:203], v[28:31]
	v_mfma_f32_16x16x32_bf16 v[24:27], v[64:67], v[208:211], v[24:27]
	v_mfma_f32_16x16x32_bf16 v[4:7], v[192:195], v[200:203], v[4:7]
	v_mfma_f32_16x16x32_bf16 v[0:3], v[192:195], v[208:211], v[0:3]
	v_mfma_f32_16x16x32_bf16 v[20:23], v[80:83], v[200:203], v[20:23]
	v_mfma_f32_16x16x32_bf16 v[16:19], v[80:83], v[208:211], v[16:19]
	v_mfma_f32_16x16x32_bf16 v[12:15], v[184:187], v[200:203], v[12:15]
	v_mfma_f32_16x16x32_bf16 v[8:11], v[184:187], v[208:211], v[8:11]
	v_mfma_f32_16x16x32_bf16 v[28:31], v[68:71], v[204:207], v[28:31]
	v_mfma_f32_16x16x32_bf16 v[24:27], v[68:71], v[212:215], v[24:27]
	v_mfma_f32_16x16x32_bf16 v[4:7], v[196:199], v[204:207], v[4:7]
	v_mfma_f32_16x16x32_bf16 v[0:3], v[196:199], v[212:215], v[0:3]
	v_mfma_f32_16x16x32_bf16 v[132:135], v[84:87], v[204:207], v[20:23]
	v_mfma_f32_16x16x32_bf16 v[156:159], v[84:87], v[212:215], v[16:19]
	v_mfma_f32_16x16x32_bf16 v[160:163], v[188:191], v[204:207], v[12:15]
	v_mfma_f32_16x16x32_bf16 v[164:167], v[188:191], v[212:215], v[8:11]
	s_setprio 0
	s_barrier
	s_nop 0
	ds_read_b128 v[8:11], v153
	ds_read_b128 v[12:15], v153 offset:1024
	ds_read_b128 v[16:19], v153 offset:2048
	ds_read_b128 v[184:187], v153 offset:3072
	ds_read_b128 v[20:23], v148 offset:32768
	ds_read_b128 v[188:191], v148 offset:33792
	ds_read_b128 v[192:195], v149 offset:32768
	ds_read_b128 v[196:199], v149 offset:33792
	ds_read_b128 v[200:203], v150 offset:32768
	ds_read_b128 v[204:207], v150 offset:33792
	ds_read_b128 v[208:211], v151 offset:32768
	ds_read_b128 v[212:215], v151 offset:33792
	s_waitcnt vmcnt(2)
	s_barrier
; #define LDA(dst, b, h) _Pragma("unroll") for (int m = 0; m < 4; ++m) _Pragma("unroll") for (int k = 0; k < 2; ++k) \
;     dst[m][k] = *reinterpret_cast<const bf16x8*>((char*)SA(b, h) + lds_byte(wr * 64 + m * 16 + fr, k * 32 + fq * 8))
; #define LDB(dst, b, h) _Pragma("unroll") for (int n = 0; n < 2; ++n) _Pragma("unroll") for (int k = 0; k < 2; ++k) \
;     dst[n][k] = *reinterpret_cast<const bf16x8*>((char*)SB(b, h) + lds_byte(wc * 32 + n * 16 + fr, k * 32 + fq * 8))
; #define MMA(ai, bj, At_, Bt_) do { __builtin_amdgcn_s_setprio(1); \
;     _Pragma("unroll") for (int k = 0; k < 2; ++k) _Pragma("unroll") for (int m = 0; m < 4; ++m) _Pragma("unroll") for (int n = 0; n < 2; ++n) \
;       acc[ai][bj][m][n] = __builtin_amdgcn_mfma_f32_16x16x32_bf16(At_[m][k], Bt_[n][k], acc[ai][bj][m][n], 0, 0, 0); \
;     __builtin_amdgcn_s_setprio(0); } while (0)
; #define WAIT_V(n) asm volatile("s_waitcnt vmcnt(" #n ")" ::: "memory")
; #define BAR __builtin_amdgcn_s_barrier()
; template <int EPI, int N, int K>
; __device__ __forceinline__ void gemm_phase(const bf16_t* __restrict__ A, const bf16_t* __restrict__ Bt, const EpiArgs ea) {
;     ...
;     { LDB(B0, 1, 0); LDA(At, 1, 0); WAIT_V(2); BAR; WAIT_L(0); MMA(0, 0, At, B0); BAR;
;       LDB(B1, 1, 1); WAIT_V(0); BAR; WAIT_L(0); MMA(0, 1, At, B1); BAR;
;       LDA(At, 1, 1); BAR; WAIT_L(0); MMA(1, 0, At, B0); MMA(1, 1, At, B1); BAR; }
;     if (wr == 0) BAR;
	s_waitcnt lgkmcnt(0)
	s_setprio 1
	v_mfma_f32_16x16x32_bf16 v[64:67], v[20:23], v[8:11], v[124:127]
	v_mfma_f32_16x16x32_bf16 v[68:71], v[20:23], v[16:19], v[120:123]
	v_mfma_f32_16x16x32_bf16 v[80:83], v[192:195], v[8:11], v[116:119]
	v_mfma_f32_16x16x32_bf16 v[84:87], v[192:195], v[16:19], v[112:115]
	v_mfma_f32_16x16x32_bf16 v[108:111], v[200:203], v[8:11], v[108:111]
	v_mfma_f32_16x16x32_bf16 v[104:107], v[200:203], v[16:19], v[104:107]
	v_mfma_f32_16x16x32_bf16 v[120:123], v[208:211], v[8:11], v[100:103]
	v_mfma_f32_16x16x32_bf16 v[124:127], v[208:211], v[16:19], v[96:99]
	v_mfma_f32_16x16x32_bf16 v[116:119], v[188:191], v[12:15], v[64:67]
	v_mfma_f32_16x16x32_bf16 v[112:115], v[188:191], v[184:187], v[68:71]
	v_mfma_f32_16x16x32_bf16 v[100:103], v[196:199], v[12:15], v[80:83]
	v_mfma_f32_16x16x32_bf16 v[96:99], v[196:199], v[184:187], v[84:87]
	v_mfma_f32_16x16x32_bf16 v[84:87], v[204:207], v[12:15], v[108:111]
	v_mfma_f32_16x16x32_bf16 v[80:83], v[204:207], v[184:187], v[104:107]
	v_mfma_f32_16x16x32_bf16 v[68:71], v[212:215], v[12:15], v[120:123]
	v_mfma_f32_16x16x32_bf16 v[64:67], v[212:215], v[184:187], v[124:127]
	s_setprio 0
	s_barrier
	ds_read_b128 v[216:219], v154
	ds_read_b128 v[220:223], v154 offset:1024
	ds_read_b128 v[224:227], v154 offset:2048
	ds_read_b128 v[228:231], v154 offset:3072
	s_waitcnt vmcnt(0)
	s_barrier
	s_waitcnt lgkmcnt(0)
	s_setprio 1
	v_mfma_f32_16x16x32_bf16 v[92:95], v[20:23], v[216:219], v[92:95]
	v_mfma_f32_16x16x32_bf16 v[20:23], v[20:23], v[224:227], v[88:91]
	v_mfma_f32_16x16x32_bf16 v[88:91], v[192:195], v[216:219], v[168:171]
	v_mfma_f32_16x16x32_bf16 v[104:107], v[192:195], v[224:227], v[172:175]
	v_mfma_f32_16x16x32_bf16 v[76:79], v[200:203], v[216:219], v[76:79]
	v_mfma_f32_16x16x32_bf16 v[72:75], v[200:203], v[224:227], v[72:75]
	v_mfma_f32_16x16x32_bf16 v[168:171], v[208:211], v[216:219], v[176:179]
	v_mfma_f32_16x16x32_bf16 v[172:175], v[208:211], v[224:227], v[180:183]
	v_mfma_f32_16x16x32_bf16 v[124:127], v[188:191], v[220:223], v[92:95]
	v_mfma_f32_16x16x32_bf16 v[120:123], v[188:191], v[228:231], v[20:23]
	v_mfma_f32_16x16x32_bf16 v[108:111], v[196:199], v[220:223], v[88:91]
	v_mfma_f32_16x16x32_bf16 v[104:107], v[196:199], v[228:231], v[104:107]
	v_mfma_f32_16x16x32_bf16 v[92:95], v[204:207], v[220:223], v[76:79]
	v_mfma_f32_16x16x32_bf16 v[88:91], v[204:207], v[228:231], v[72:75]
	v_mfma_f32_16x16x32_bf16 v[76:79], v[212:215], v[220:223], v[168:171]
	v_mfma_f32_16x16x32_bf16 v[72:75], v[212:215], v[228:231], v[172:175]
	s_setprio 0
	s_barrier
	ds_read_b128 v[168:171], v148 offset:49152
	ds_read_b128 v[172:175], v148 offset:50176
	ds_read_b128 v[176:179], v149 offset:49152
	ds_read_b128 v[180:183], v149 offset:50176
	ds_read_b128 v[188:191], v150 offset:49152
	ds_read_b128 v[192:195], v150 offset:50176
	ds_read_b128 v[196:199], v151 offset:49152
	ds_read_b128 v[200:203], v151 offset:50176
	s_barrier
	s_waitcnt lgkmcnt(0)
	s_setprio 1
	v_mfma_f32_16x16x32_bf16 v[20:23], v[168:171], v[8:11], v[60:63]
	v_mfma_f32_16x16x32_bf16 v[56:59], v[168:171], v[16:19], v[56:59]
	v_mfma_f32_16x16x32_bf16 v[60:63], v[176:179], v[8:11], v[52:55]
	v_mfma_f32_16x16x32_bf16 v[204:207], v[176:179], v[16:19], v[48:51]
	v_mfma_f32_16x16x32_bf16 v[44:47], v[188:191], v[8:11], v[44:47]
	v_mfma_f32_16x16x32_bf16 v[40:43], v[188:191], v[16:19], v[40:43]
	v_mfma_f32_16x16x32_bf16 v[8:11], v[196:199], v[8:11], v[36:39]
	v_mfma_f32_16x16x32_bf16 v[208:211], v[196:199], v[16:19], v[32:35]
	v_mfma_f32_16x16x32_bf16 v[52:55], v[172:175], v[12:15], v[20:23]
	v_mfma_f32_16x16x32_bf16 v[48:51], v[172:175], v[184:187], v[56:59]
	v_mfma_f32_16x16x32_bf16 v[36:39], v[180:183], v[12:15], v[60:63]
	v_mfma_f32_16x16x32_bf16 v[32:35], v[180:183], v[184:187], v[204:207]
	v_mfma_f32_16x16x32_bf16 v[20:23], v[192:195], v[12:15], v[44:47]
	v_mfma_f32_16x16x32_bf16 v[16:19], v[192:195], v[184:187], v[40:43]
	v_mfma_f32_16x16x32_bf16 v[8:11], v[200:203], v[12:15], v[8:11]
	v_mfma_f32_16x16x32_bf16 v[12:15], v[200:203], v[184:187], v[208:211]
	s_setprio 0
	s_setprio 1
	v_mfma_f32_16x16x32_bf16 v[28:31], v[168:171], v[216:219], v[28:31]
	v_mfma_f32_16x16x32_bf16 v[24:27], v[168:171], v[224:227], v[24:27]
	v_mfma_f32_16x16x32_bf16 v[40:43], v[176:179], v[216:219], v[132:135]
	v_mfma_f32_16x16x32_bf16 v[132:135], v[176:179], v[224:227], v[156:159]
	v_mfma_f32_16x16x32_bf16 v[156:159], v[188:191], v[216:219], v[160:163]
	v_mfma_f32_16x16x32_bf16 v[160:163], v[188:191], v[224:227], v[164:167]
	v_mfma_f32_16x16x32_bf16 v[4:7], v[196:199], v[216:219], v[4:7]
	v_mfma_f32_16x16x32_bf16 v[0:3], v[196:199], v[224:227], v[0:3]
	v_mfma_f32_16x16x32_bf16 v[60:63], v[172:175], v[220:223], v[28:31]
	v_mfma_f32_16x16x32_bf16 v[56:59], v[172:175], v[228:231], v[24:27]
	v_mfma_f32_16x16x32_bf16 v[44:47], v[180:183], v[220:223], v[40:43]
	v_mfma_f32_16x16x32_bf16 v[40:43], v[180:183], v[228:231], v[132:135]
	v_mfma_f32_16x16x32_bf16 v[28:31], v[192:195], v[220:223], v[156:159]
	v_mfma_f32_16x16x32_bf16 v[24:27], v[192:195], v[228:231], v[160:163]
	v_mfma_f32_16x16x32_bf16 v[4:7], v[200:203], v[220:223], v[4:7]
	v_mfma_f32_16x16x32_bf16 v[0:3], v[200:203], v[228:231], v[0:3]
	s_setprio 0
	s_barrier
	s_and_saveexec_b64 s[2:3], s[8:9]
	s_cbranch_execz .LBB0_393
	s_barrier

; #define STAGE_A(POFF, h, kt) STAGE_AX(POFF, h, kt, brow)
; #define STAGE_B(POFF, h, kt) STAGE_BX(POFF, h, kt, bcol)
; #define LDA(dst, b, h) _Pragma("unroll") for (int m = 0; m < 4; ++m) _Pragma("unroll") for (int k = 0; k < 2; ++k) \
;     dst[m][k] = *reinterpret_cast<const bf16x8*>((char*)SA(b, h) + lds_byte(wr * 64 + m * 16 + fr, k * 32 + fq * 8))
; #define LDB(dst, b, h) _Pragma("unroll") for (int n = 0; n < 2; ++n) _Pragma("unroll") for (int k = 0; k < 2; ++k) \
;     dst[n][k] = *reinterpret_cast<const bf16x8*>((char*)SB(b, h) + lds_byte(wc * 32 + n * 16 + fr, k * 32 + fq * 8))
; #define MMA(ai, bj, At_, Bt_) do { __builtin_amdgcn_s_setprio(1); \
;     _Pragma("unroll") for (int k = 0; k < 2; ++k) _Pragma("unroll") for (int m = 0; m < 4; ++m) _Pragma("unroll") for (int n = 0; n < 2; ++n) \
;       acc[ai][bj][m][n] = __builtin_amdgcn_mfma_f32_16x16x32_bf16(At_[m][k], Bt_[n][k], acc[ai][bj][m][n], 0, 0, 0); \
;     __builtin_amdgcn_s_setprio(0); } while (0)
; #define WAIT_V(n) asm volatile("s_waitcnt vmcnt(" #n ")" ::: "memory")
; #define BAR __builtin_amdgcn_s_barrier()
; #define SCHED __builtin_amdgcn_sched_barrier(0)
; template <int EPI, int N, int K>
; __device__ __forceinline__ void gemm_phase(const bf16_t* __restrict__ A, const bf16_t* __restrict__ Bt, const EpiArgs ea) {
;     ...
;     int brow, bcol; TILE_RC(w, brow, bcol);
;     f32x4 acc[2][2][4][2];
; #pragma unroll
;     for (int a = 0; a < 2; ++a)
; #pragma unroll
;       for (int b = 0; b < 2; ++b)
; #pragma unroll
;         for (int m = 0; m < 4; ++m)
; #pragma unroll
;           for (int n = 0; n < 2; ++n) acc[a][b][m][n] = (f32x4){0.f, 0.f, 0.f, 0.f};
;     bf16x8 At[4][2], B0[2][2], B1[2][2];
;     if (wr == 1) BAR;
;     if (w == (int)blockIdx.x) { WAIT_V(0); } else { WAIT_V(24); }
;     BAR;
;     BAR;
;     for (int t = 0; t < nt - 2; t += 2) {
;       LDB(B0, 0, 0); SCHED; LDA(At, 0, 0); STAGE_A(SA_OFF(1, 1), 1, t + 1);
;       WAIT_L(8); BAR; WAIT_L(0); MMA(0, 0, At, B0); BAR; SCHED;
;       LDB(B1, 0, 1); STAGE_B(SB_OFF(0, 0), 0, t + 2);
;       BAR; WAIT_L(0); MMA(0, 1, At, B1); BAR;
;       LDA(At, 0, 1); STAGE_A(SA_OFF(0, 0), 0, t + 2);
;       BAR; WAIT_L(0); MMA(1, 0, At, B0); BAR; SCHED;
;       STAGE_B(SB_OFF(0, 1), 1, t + 2);
;       WAIT_V(6); BAR; MMA(1, 1, At, B1); BAR;
.LBB0_508:
	s_lshl_b32 s2, s31, 8
	s_and_b32 s2, s2, 0x700
	s_ashr_i32 s3, s31, 3
	s_add_i32 s3, s2, s3
	s_ashr_i32 s2, s3, 31
	s_lshr_b32 s2, s2, 24
	s_add_i32 s12, s3, s2
	s_ashr_i32 s2, s12, 8
	s_and_b32 s12, s12, 0xffffff00
	s_sub_i32 s34, s3, s12
	s_lshl_b32 s3, s34, 8
	s_lshl_b32 s12, s34, 5
	s_lshl_b32 s13, s34, 17
	s_and_b32 s34, s34, 7
	s_lshl_b32 s35, s2, 23
	s_lshl_b32 s34, s34, 20
	s_and_b32 s13, s13, 0xfff00000
	s_or_b32 s34, s35, s34
	s_mov_b32 s35, -2
	s_mov_b32 s36, 0
	s_barrier
	s_barrier
	ds_read_b128 v[132:135], v148
	ds_read_b128 v[156:159], v148 offset:1024
	ds_read_b128 v[160:163], v148 offset:2048
	ds_read_b128 v[164:167], v148 offset:3072
	ds_read_b128 v[168:171], v149
	ds_read_b128 v[172:175], v149 offset:1024
	ds_read_b128 v[176:179], v150
	ds_read_b128 v[180:183], v150 offset:1024
	ds_read_b128 v[184:187], v151
	ds_read_b128 v[188:191], v151 offset:1024
	ds_read_b128 v[192:195], v152
	ds_read_b128 v[196:199], v152 offset:1024
	ds_read_b128 v[218:221], v149 offset:16384
	ds_read_b128 v[222:225], v149 offset:17408
	ds_read_b128 v[226:229], v150 offset:16384
	ds_read_b128 v[230:233], v150 offset:17408
	ds_read_b128 v[238:241], v151 offset:16384
	ds_read_b128 v[242:245], v151 offset:17408
	s_add_i32 s37, s34, s36
	s_mov_b32 m0, s29
	s_or_b32 s38, s37, 0x80080
	buffer_load_dwordx4 v136, s[48:51], s38 offen lds
	s_mov_b32 m0, s30
	s_or_b32 s38, s37, 0xc0080
	buffer_load_dwordx4 v136, s[48:51], s38 offen lds
	s_setprio 1
	s_barrier
	s_waitcnt lgkmcnt(6)
	v_mfma_f32_16x16x32_bf16 v[124:127], v[168:171], v[132:135], 0
	v_mfma_f32_16x16x32_bf16 v[120:123], v[168:171], v[160:163], 0
	v_mfma_f32_16x16x32_bf16 v[116:119], v[176:179], v[132:135], 0
	v_mfma_f32_16x16x32_bf16 v[112:115], v[176:179], v[160:163], 0
	v_mfma_f32_16x16x32_bf16 v[108:111], v[184:187], v[132:135], 0
	v_mfma_f32_16x16x32_bf16 v[104:107], v[184:187], v[160:163], 0
	v_mfma_f32_16x16x32_bf16 v[100:103], v[192:195], v[132:135], 0
	v_mfma_f32_16x16x32_bf16 v[96:99], v[192:195], v[160:163], 0
	v_mfma_f32_16x16x32_bf16 v[124:127], v[172:175], v[156:159], v[124:127]
	v_mfma_f32_16x16x32_bf16 v[120:123], v[172:175], v[164:167], v[120:123]
	v_mfma_f32_16x16x32_bf16 v[116:119], v[180:183], v[156:159], v[116:119]
	v_mfma_f32_16x16x32_bf16 v[112:115], v[180:183], v[164:167], v[112:115]
	v_mfma_f32_16x16x32_bf16 v[108:111], v[188:191], v[156:159], v[108:111]
	v_mfma_f32_16x16x32_bf16 v[104:107], v[188:191], v[164:167], v[104:107]
	v_mfma_f32_16x16x32_bf16 v[100:103], v[196:199], v[156:159], v[100:103]
	v_mfma_f32_16x16x32_bf16 v[96:99], v[196:199], v[164:167], v[96:99]
	s_barrier
	s_setprio 0
	ds_read_b128 v[200:203], v153
	ds_read_b128 v[204:207], v153 offset:1024
	ds_read_b128 v[208:211], v153 offset:2048
	ds_read_b128 v[212:215], v153 offset:3072
	ds_read_b128 v[246:249], v152 offset:16384
	ds_read_b128 v[250:253], v152 offset:17408
	s_add_i32 s38, s13, s36
	s_mov_b32 m0, s15
	s_add_i32 s39, s38, 0x100
	buffer_load_dwordx4 v137, s[80:83], s39 offen lds
	s_mov_b32 m0, s16
	s_add_i32 s39, s38, 0x80100
	buffer_load_dwordx4 v137, s[80:83], s39 offen lds
	s_waitcnt vmcnt(6)
	s_setprio 1
	s_barrier
	s_waitcnt lgkmcnt(2)
	v_mfma_f32_16x16x32_bf16 v[92:95], v[168:171], v[200:203], 0
	v_mfma_f32_16x16x32_bf16 v[88:91], v[168:171], v[208:211], 0
	v_mfma_f32_16x16x32_bf16 v[84:87], v[176:179], v[200:203], 0
	v_mfma_f32_16x16x32_bf16 v[80:83], v[176:179], v[208:211], 0
	v_mfma_f32_16x16x32_bf16 v[76:79], v[184:187], v[200:203], 0
	v_mfma_f32_16x16x32_bf16 v[72:75], v[184:187], v[208:211], 0
	v_mfma_f32_16x16x32_bf16 v[68:71], v[192:195], v[200:203], 0
	v_mfma_f32_16x16x32_bf16 v[64:67], v[192:195], v[208:211], 0
	v_mfma_f32_16x16x32_bf16 v[92:95], v[172:175], v[204:207], v[92:95]
	v_mfma_f32_16x16x32_bf16 v[88:91], v[172:175], v[212:215], v[88:91]
	v_mfma_f32_16x16x32_bf16 v[84:87], v[180:183], v[204:207], v[84:87]
	v_mfma_f32_16x16x32_bf16 v[80:83], v[180:183], v[212:215], v[80:83]
	v_mfma_f32_16x16x32_bf16 v[76:79], v[188:191], v[204:207], v[76:79]
	v_mfma_f32_16x16x32_bf16 v[72:75], v[188:191], v[212:215], v[72:75]
	v_mfma_f32_16x16x32_bf16 v[68:71], v[196:199], v[204:207], v[68:71]
	v_mfma_f32_16x16x32_bf16 v[64:67], v[196:199], v[212:215], v[64:67]
	s_barrier
	s_setprio 0
	ds_read_b128 v[168:171], v149 offset:32768
	ds_read_b128 v[172:175], v149 offset:33792
	ds_read_b128 v[176:179], v150 offset:32768
	ds_read_b128 v[180:183], v150 offset:33792
	ds_read_b128 v[184:187], v151 offset:32768
	ds_read_b128 v[188:191], v151 offset:33792
	s_mov_b32 m0, s14
	s_add_i32 s39, s37, 0x100
	buffer_load_dwordx4 v136, s[48:51], s39 offen lds
	s_mov_b32 m0, s17
	s_add_i32 s40, s37, 0x40100
	buffer_load_dwordx4 v136, s[48:51], s40 offen lds
	s_waitcnt vmcnt(10)
	s_setprio 1
	s_barrier
	s_waitcnt lgkmcnt(6)
	v_mfma_f32_16x16x32_bf16 v[60:63], v[218:221], v[132:135], 0
	v_mfma_f32_16x16x32_bf16 v[56:59], v[218:221], v[160:163], 0
	v_mfma_f32_16x16x32_bf16 v[52:55], v[226:229], v[132:135], 0
	v_mfma_f32_16x16x32_bf16 v[48:51], v[226:229], v[160:163], 0
	v_mfma_f32_16x16x32_bf16 v[44:47], v[238:241], v[132:135], 0
	v_mfma_f32_16x16x32_bf16 v[40:43], v[238:241], v[160:163], 0
	v_mfma_f32_16x16x32_bf16 v[36:39], v[246:249], v[132:135], 0
	v_mfma_f32_16x16x32_bf16 v[32:35], v[246:249], v[160:163], 0
	v_mfma_f32_16x16x32_bf16 v[60:63], v[222:225], v[156:159], v[60:63]
	v_mfma_f32_16x16x32_bf16 v[56:59], v[222:225], v[164:167], v[56:59]
	v_mfma_f32_16x16x32_bf16 v[52:55], v[230:233], v[156:159], v[52:55]
	v_mfma_f32_16x16x32_bf16 v[48:51], v[230:233], v[164:167], v[48:51]
	v_mfma_f32_16x16x32_bf16 v[44:47], v[242:245], v[156:159], v[44:47]
	v_mfma_f32_16x16x32_bf16 v[40:43], v[242:245], v[164:167], v[40:43]
	v_mfma_f32_16x16x32_bf16 v[36:39], v[250:253], v[156:159], v[36:39]
	v_mfma_f32_16x16x32_bf16 v[32:35], v[250:253], v[164:167], v[32:35]
	s_barrier
; #define STAGE_A(POFF, h, kt) STAGE_AX(POFF, h, kt, brow)
; #define STAGE_B(POFF, h, kt) STAGE_BX(POFF, h, kt, bcol)
; #define LDA(dst, b, h) _Pragma("unroll") for (int m = 0; m < 4; ++m) _Pragma("unroll") for (int k = 0; k < 2; ++k) \
;     dst[m][k] = *reinterpret_cast<const bf16x8*>((char*)SA(b, h) + lds_byte(wr * 64 + m * 16 + fr, k * 32 + fq * 8))
; #define LDB(dst, b, h) _Pragma("unroll") for (int n = 0; n < 2; ++n) _Pragma("unroll") for (int k = 0; k < 2; ++k) \
;     dst[n][k] = *reinterpret_cast<const bf16x8*>((char*)SB(b, h) + lds_byte(wc * 32 + n * 16 + fr, k * 32 + fq * 8))
; #define MMA(ai, bj, At_, Bt_) do { __builtin_amdgcn_s_setprio(1); \
;     _Pragma("unroll") for (int k = 0; k < 2; ++k) _Pragma("unroll") for (int m = 0; m < 4; ++m) _Pragma("unroll") for (int n = 0; n < 2; ++n) \
;       acc[ai][bj][m][n] = __builtin_amdgcn_mfma_f32_16x16x32_bf16(At_[m][k], Bt_[n][k], acc[ai][bj][m][n], 0, 0, 0); \
;     __builtin_amdgcn_s_setprio(0); } while (0)
; #define WAIT_V(n) asm volatile("s_waitcnt vmcnt(" #n ")" ::: "memory")
; #define BAR __builtin_amdgcn_s_barrier()
; #define SCHED __builtin_amdgcn_sched_barrier(0)
; template <int EPI, int N, int K>
; __device__ __forceinline__ void gemm_phase(const bf16_t* __restrict__ A, const bf16_t* __restrict__ Bt, const EpiArgs ea) {
;     ...
;       BAR; WAIT_L(0); MMA(1, 0, At, B0); BAR; SCHED;
;       STAGE_B(SB_OFF(0, 1), 1, t + 2);
;       WAIT_V(6); BAR; MMA(1, 1, At, B1); BAR;
;       LDB(B0, 1, 0); SCHED; LDA(At, 1, 0); STAGE_A(SA_OFF(0, 1), 1, t + 2);
;       WAIT_L(8); BAR; WAIT_L(0); MMA(0, 0, At, B0); BAR; SCHED;
;       LDB(B1, 1, 1); STAGE_B(SB_OFF(1, 0), 0, t + 3);
;       BAR; WAIT_L(0); MMA(0, 1, At, B1); BAR;
;       LDA(At, 1, 1); STAGE_A(SA_OFF(1, 0), 0, t + 3);
;       BAR; WAIT_L(0); MMA(1, 0, At, B0); BAR; SCHED;
	s_setprio 0
	ds_read_b128 v[132:135], v154
	ds_read_b128 v[156:159], v154 offset:1024
	ds_read_b128 v[160:163], v154 offset:2048
	ds_read_b128 v[164:167], v154 offset:3072
	ds_read_b128 v[192:195], v152 offset:32768
	ds_read_b128 v[196:199], v152 offset:33792
	s_mov_b32 m0, s18
	s_add_i32 s40, s38, 0x2100
	buffer_load_dwordx4 v137, s[80:83], s40 offen lds
	s_mov_b32 m0, s19
	s_add_i32 s40, s38, 0x82100
	buffer_load_dwordx4 v137, s[80:83], s40 offen lds
	s_waitcnt vmcnt(6)
	s_setprio 1
	s_barrier
	v_mfma_f32_16x16x32_bf16 v[28:31], v[218:221], v[200:203], 0
	v_mfma_f32_16x16x32_bf16 v[24:27], v[218:221], v[208:211], 0
	v_mfma_f32_16x16x32_bf16 v[20:23], v[226:229], v[200:203], 0
	v_mfma_f32_16x16x32_bf16 v[16:19], v[226:229], v[208:211], 0
	v_mfma_f32_16x16x32_bf16 v[12:15], v[238:241], v[200:203], 0
	v_mfma_f32_16x16x32_bf16 v[8:11], v[238:241], v[208:211], 0
	v_mfma_f32_16x16x32_bf16 v[4:7], v[246:249], v[200:203], 0
	v_mfma_f32_16x16x32_bf16 v[0:3], v[246:249], v[208:211], 0
	v_mfma_f32_16x16x32_bf16 v[28:31], v[222:225], v[204:207], v[28:31]
	v_mfma_f32_16x16x32_bf16 v[24:27], v[222:225], v[212:215], v[24:27]
	v_mfma_f32_16x16x32_bf16 v[20:23], v[230:233], v[204:207], v[20:23]
	v_mfma_f32_16x16x32_bf16 v[16:19], v[230:233], v[212:215], v[16:19]
	v_mfma_f32_16x16x32_bf16 v[12:15], v[242:245], v[204:207], v[12:15]
	v_mfma_f32_16x16x32_bf16 v[8:11], v[242:245], v[212:215], v[8:11]
	v_mfma_f32_16x16x32_bf16 v[4:7], v[250:253], v[204:207], v[4:7]
	v_mfma_f32_16x16x32_bf16 v[0:3], v[250:253], v[212:215], v[0:3]
	s_barrier
	s_setprio 0
	ds_read_b128 v[218:221], v149 offset:49152
	ds_read_b128 v[222:225], v149 offset:50176
	ds_read_b128 v[226:229], v150 offset:49152
	ds_read_b128 v[230:233], v150 offset:50176
	ds_read_b128 v[238:241], v151 offset:49152
	ds_read_b128 v[242:245], v151 offset:50176
	s_mov_b32 m0, s21
	s_or_b32 s40, s39, 0x80000
	buffer_load_dwordx4 v136, s[48:51], s40 offen lds
	s_mov_b32 m0, s22
	s_or_b32 s39, s39, 0xc0000
	buffer_load_dwordx4 v136, s[48:51], s39 offen lds
	s_setprio 1
	s_barrier
	s_waitcnt lgkmcnt(6)
	v_mfma_f32_16x16x32_bf16 v[124:127], v[168:171], v[132:135], v[124:127]
	v_mfma_f32_16x16x32_bf16 v[120:123], v[168:171], v[160:163], v[120:123]
	v_mfma_f32_16x16x32_bf16 v[116:119], v[176:179], v[132:135], v[116:119]
	v_mfma_f32_16x16x32_bf16 v[112:115], v[176:179], v[160:163], v[112:115]
	v_mfma_f32_16x16x32_bf16 v[108:111], v[184:187], v[132:135], v[108:111]
	v_mfma_f32_16x16x32_bf16 v[104:107], v[184:187], v[160:163], v[104:107]
	v_mfma_f32_16x16x32_bf16 v[100:103], v[192:195], v[132:135], v[100:103]
	v_mfma_f32_16x16x32_bf16 v[96:99], v[192:195], v[160:163], v[96:99]
	v_mfma_f32_16x16x32_bf16 v[124:127], v[172:175], v[156:159], v[124:127]
	v_mfma_f32_16x16x32_bf16 v[120:123], v[172:175], v[164:167], v[120:123]
	v_mfma_f32_16x16x32_bf16 v[116:119], v[180:183], v[156:159], v[116:119]
	v_mfma_f32_16x16x32_bf16 v[112:115], v[180:183], v[164:167], v[112:115]
	v_mfma_f32_16x16x32_bf16 v[108:111], v[188:191], v[156:159], v[108:111]
	v_mfma_f32_16x16x32_bf16 v[104:107], v[188:191], v[164:167], v[104:107]
	v_mfma_f32_16x16x32_bf16 v[100:103], v[196:199], v[156:159], v[100:103]
	v_mfma_f32_16x16x32_bf16 v[96:99], v[196:199], v[164:167], v[96:99]
	s_barrier
	s_setprio 0
	ds_read_b128 v[200:203], v155
	ds_read_b128 v[204:207], v155 offset:1024
	ds_read_b128 v[208:211], v155 offset:2048
	ds_read_b128 v[212:215], v155 offset:3072
	ds_read_b128 v[246:249], v152 offset:49152
	ds_read_b128 v[250:253], v152 offset:50176
	s_mov_b32 m0, s23
	s_add_i32 s39, s38, 0x180
	buffer_load_dwordx4 v137, s[80:83], s39 offen lds
	s_mov_b32 m0, s24
	s_add_i32 s39, s38, 0x80180
	buffer_load_dwordx4 v137, s[80:83], s39 offen lds
	s_waitcnt vmcnt(6)
	s_setprio 1
	s_barrier
	s_waitcnt lgkmcnt(2)
	v_mfma_f32_16x16x32_bf16 v[92:95], v[168:171], v[200:203], v[92:95]
	v_mfma_f32_16x16x32_bf16 v[88:91], v[168:171], v[208:211], v[88:91]
	v_mfma_f32_16x16x32_bf16 v[84:87], v[176:179], v[200:203], v[84:87]
	v_mfma_f32_16x16x32_bf16 v[80:83], v[176:179], v[208:211], v[80:83]
	v_mfma_f32_16x16x32_bf16 v[76:79], v[184:187], v[200:203], v[76:79]
	v_mfma_f32_16x16x32_bf16 v[72:75], v[184:187], v[208:211], v[72:75]
	v_mfma_f32_16x16x32_bf16 v[68:71], v[192:195], v[200:203], v[68:71]
	v_mfma_f32_16x16x32_bf16 v[64:67], v[192:195], v[208:211], v[64:67]
	v_mfma_f32_16x16x32_bf16 v[92:95], v[172:175], v[204:207], v[92:95]
	v_mfma_f32_16x16x32_bf16 v[88:91], v[172:175], v[212:215], v[88:91]
	v_mfma_f32_16x16x32_bf16 v[84:87], v[180:183], v[204:207], v[84:87]
	v_mfma_f32_16x16x32_bf16 v[80:83], v[180:183], v[212:215], v[80:83]
	v_mfma_f32_16x16x32_bf16 v[76:79], v[188:191], v[204:207], v[76:79]
	v_mfma_f32_16x16x32_bf16 v[72:75], v[188:191], v[212:215], v[72:75]
	v_mfma_f32_16x16x32_bf16 v[68:71], v[196:199], v[204:207], v[68:71]
	v_mfma_f32_16x16x32_bf16 v[64:67], v[196:199], v[212:215], v[64:67]
	s_barrier
	s_setprio 0
	ds_read_b128 v[168:171], v149
	ds_read_b128 v[172:175], v149 offset:1024
	ds_read_b128 v[176:179], v150
	ds_read_b128 v[180:183], v150 offset:1024
	ds_read_b128 v[184:187], v151
	ds_read_b128 v[188:191], v151 offset:1024
	s_mov_b32 m0, s25
	s_add_i32 s39, s37, 0x180
	buffer_load_dwordx4 v136, s[48:51], s39 offen lds
	s_mov_b32 m0, s26
	s_add_i32 s37, s37, 0x40180
	buffer_load_dwordx4 v136, s[48:51], s37 offen lds
	s_waitcnt vmcnt(10)
	s_setprio 1
	s_barrier
; #define STAGE_A(POFF, h, kt) STAGE_AX(POFF, h, kt, brow)
; #define STAGE_B(POFF, h, kt) STAGE_BX(POFF, h, kt, bcol)
; #define LDA(dst, b, h) _Pragma("unroll") for (int m = 0; m < 4; ++m) _Pragma("unroll") for (int k = 0; k < 2; ++k) \
;     dst[m][k] = *reinterpret_cast<const bf16x8*>((char*)SA(b, h) + lds_byte(wr * 64 + m * 16 + fr, k * 32 + fq * 8))
; #define LDB(dst, b, h) _Pragma("unroll") for (int n = 0; n < 2; ++n) _Pragma("unroll") for (int k = 0; k < 2; ++k) \
;     dst[n][k] = *reinterpret_cast<const bf16x8*>((char*)SB(b, h) + lds_byte(wc * 32 + n * 16 + fr, k * 32 + fq * 8))
; #define MMA(ai, bj, At_, Bt_) do { __builtin_amdgcn_s_setprio(1); \
;     _Pragma("unroll") for (int k = 0; k < 2; ++k) _Pragma("unroll") for (int m = 0; m < 4; ++m) _Pragma("unroll") for (int n = 0; n < 2; ++n) \
;       acc[ai][bj][m][n] = __builtin_amdgcn_mfma_f32_16x16x32_bf16(At_[m][k], Bt_[n][k], acc[ai][bj][m][n], 0, 0, 0); \
;     __builtin_amdgcn_s_setprio(0); } while (0)
; #define WAIT_V(n) asm volatile("s_waitcnt vmcnt(" #n ")" ::: "memory")
; #define BAR __builtin_amdgcn_s_barrier()
; #define SCHED __builtin_amdgcn_sched_barrier(0)
; template <int EPI, int N, int K>
; __device__ __forceinline__ void gemm_phase(const bf16_t* __restrict__ A, const bf16_t* __restrict__ Bt, const EpiArgs ea) {
;     ...
;       LDB(B0, 0, 0); SCHED; LDA(At, 0, 0); STAGE_A(SA_OFF(1, 1), 1, t + 1);
;       WAIT_L(8); BAR; WAIT_L(0); MMA(0, 0, At, B0); BAR; SCHED;
;       LDB(B1, 0, 1); STAGE_B(SB_OFF(0, 0), 0, t + 2);
;       BAR; WAIT_L(0); MMA(0, 1, At, B1); BAR;
;       LDA(At, 0, 1); STAGE_A(SA_OFF(0, 0), 0, t + 2);
;       BAR; WAIT_L(0); MMA(1, 0, At, B0); BAR; SCHED;
;       STAGE_B(SB_OFF(0, 1), 1, t + 2);
;       WAIT_V(6); BAR; MMA(1, 1, At, B1); BAR;
;       LDB(B0, 1, 0); SCHED; LDA(At, 1, 0); STAGE_A(SA_OFF(0, 1), 1, t + 2);
;       WAIT_L(8); BAR; WAIT_L(0); MMA(0, 0, At, B0); BAR; SCHED;
;       LDB(B1, 1, 1); STAGE_B(SB_OFF(1, 0), 0, t + 3);
;       BAR; WAIT_L(0); MMA(0, 1, At, B1); BAR;
;       LDA(At, 1, 1); STAGE_A(SA_OFF(1, 0), 0, t + 3);
;       BAR; WAIT_L(0); MMA(1, 0, At, B0); BAR; SCHED;
;       STAGE_B(SB_OFF(1, 1), 1, t + 3);
;       WAIT_V(6); BAR; MMA(1, 1, At, B1); BAR;
	s_waitcnt lgkmcnt(6)
	v_mfma_f32_16x16x32_bf16 v[60:63], v[218:221], v[132:135], v[60:63]
	v_mfma_f32_16x16x32_bf16 v[56:59], v[218:221], v[160:163], v[56:59]
	v_mfma_f32_16x16x32_bf16 v[52:55], v[226:229], v[132:135], v[52:55]
	v_mfma_f32_16x16x32_bf16 v[48:51], v[226:229], v[160:163], v[48:51]
	v_mfma_f32_16x16x32_bf16 v[44:47], v[238:241], v[132:135], v[44:47]
	v_mfma_f32_16x16x32_bf16 v[40:43], v[238:241], v[160:163], v[40:43]
	v_mfma_f32_16x16x32_bf16 v[36:39], v[246:249], v[132:135], v[36:39]
	v_mfma_f32_16x16x32_bf16 v[32:35], v[246:249], v[160:163], v[32:35]
	v_mfma_f32_16x16x32_bf16 v[60:63], v[222:225], v[156:159], v[60:63]
	v_mfma_f32_16x16x32_bf16 v[56:59], v[222:225], v[164:167], v[56:59]
	v_mfma_f32_16x16x32_bf16 v[52:55], v[230:233], v[156:159], v[52:55]
	v_mfma_f32_16x16x32_bf16 v[48:51], v[230:233], v[164:167], v[48:51]
	v_mfma_f32_16x16x32_bf16 v[44:47], v[242:245], v[156:159], v[44:47]
	v_mfma_f32_16x16x32_bf16 v[40:43], v[242:245], v[164:167], v[40:43]
	v_mfma_f32_16x16x32_bf16 v[36:39], v[250:253], v[156:159], v[36:39]
	v_mfma_f32_16x16x32_bf16 v[32:35], v[250:253], v[164:167], v[32:35]
	s_barrier
	s_setprio 0
	ds_read_b128 v[132:135], v148
	ds_read_b128 v[156:159], v148 offset:1024
	ds_read_b128 v[160:163], v148 offset:2048
	ds_read_b128 v[164:167], v148 offset:3072
	ds_read_b128 v[192:195], v152
	ds_read_b128 v[196:199], v152 offset:1024
	s_mov_b32 m0, s27
	s_add_i32 s37, s38, 0x2180
	buffer_load_dwordx4 v137, s[80:83], s37 offen lds
	s_mov_b32 m0, s28
	s_add_i32 s38, s38, 0x82180
	buffer_load_dwordx4 v137, s[80:83], s38 offen lds
	s_waitcnt vmcnt(6)
	s_setprio 1
	s_barrier
	v_mfma_f32_16x16x32_bf16 v[28:31], v[218:221], v[200:203], v[28:31]
	v_mfma_f32_16x16x32_bf16 v[24:27], v[218:221], v[208:211], v[24:27]
	v_mfma_f32_16x16x32_bf16 v[20:23], v[226:229], v[200:203], v[20:23]
	v_mfma_f32_16x16x32_bf16 v[16:19], v[226:229], v[208:211], v[16:19]
	v_mfma_f32_16x16x32_bf16 v[12:15], v[238:241], v[200:203], v[12:15]
	v_mfma_f32_16x16x32_bf16 v[8:11], v[238:241], v[208:211], v[8:11]
	v_mfma_f32_16x16x32_bf16 v[4:7], v[246:249], v[200:203], v[4:7]
	v_mfma_f32_16x16x32_bf16 v[0:3], v[246:249], v[208:211], v[0:3]
	v_mfma_f32_16x16x32_bf16 v[28:31], v[222:225], v[204:207], v[28:31]
	v_mfma_f32_16x16x32_bf16 v[24:27], v[222:225], v[212:215], v[24:27]
	v_mfma_f32_16x16x32_bf16 v[20:23], v[230:233], v[204:207], v[20:23]
	v_mfma_f32_16x16x32_bf16 v[16:19], v[230:233], v[212:215], v[16:19]
	v_mfma_f32_16x16x32_bf16 v[12:15], v[242:245], v[204:207], v[12:15]
	v_mfma_f32_16x16x32_bf16 v[8:11], v[242:245], v[212:215], v[8:11]
	v_mfma_f32_16x16x32_bf16 v[4:7], v[250:253], v[204:207], v[4:7]
	v_mfma_f32_16x16x32_bf16 v[0:3], v[250:253], v[212:215], v[0:3]
	s_barrier
	s_setprio 0
	s_add_i32 s35, s35, 2
	s_addk_i32 s36, 0x100
	s_cmp_lt_u32 s35, 28
.LBB0_509:
	ds_read_b128 v[218:221], v149 offset:16384
	ds_read_b128 v[222:225], v149 offset:17408
	ds_read_b128 v[226:229], v150 offset:16384
	ds_read_b128 v[230:233], v150 offset:17408
	ds_read_b128 v[238:241], v151 offset:16384
	ds_read_b128 v[242:245], v151 offset:17408
	s_add_i32 s37, s34, s36
	s_mov_b32 m0, s29
	s_or_b32 s38, s37, 0x80080
	buffer_load_dwordx4 v136, s[48:51], s38 offen lds
	s_mov_b32 m0, s30
	s_or_b32 s38, s37, 0xc0080
	buffer_load_dwordx4 v136, s[48:51], s38 offen lds
	s_setprio 1
	s_barrier
	s_waitcnt lgkmcnt(6)
	v_mfma_f32_16x16x32_bf16 v[124:127], v[168:171], v[132:135], v[124:127]
	v_mfma_f32_16x16x32_bf16 v[120:123], v[168:171], v[160:163], v[120:123]
	v_mfma_f32_16x16x32_bf16 v[116:119], v[176:179], v[132:135], v[116:119]
	v_mfma_f32_16x16x32_bf16 v[112:115], v[176:179], v[160:163], v[112:115]
	v_mfma_f32_16x16x32_bf16 v[108:111], v[184:187], v[132:135], v[108:111]
	v_mfma_f32_16x16x32_bf16 v[104:107], v[184:187], v[160:163], v[104:107]
	v_mfma_f32_16x16x32_bf16 v[100:103], v[192:195], v[132:135], v[100:103]
	v_mfma_f32_16x16x32_bf16 v[96:99], v[192:195], v[160:163], v[96:99]
	v_mfma_f32_16x16x32_bf16 v[124:127], v[172:175], v[156:159], v[124:127]
	v_mfma_f32_16x16x32_bf16 v[120:123], v[172:175], v[164:167], v[120:123]
	v_mfma_f32_16x16x32_bf16 v[116:119], v[180:183], v[156:159], v[116:119]
	v_mfma_f32_16x16x32_bf16 v[112:115], v[180:183], v[164:167], v[112:115]
	v_mfma_f32_16x16x32_bf16 v[108:111], v[188:191], v[156:159], v[108:111]
	v_mfma_f32_16x16x32_bf16 v[104:107], v[188:191], v[164:167], v[104:107]
	v_mfma_f32_16x16x32_bf16 v[100:103], v[196:199], v[156:159], v[100:103]
	v_mfma_f32_16x16x32_bf16 v[96:99], v[196:199], v[164:167], v[96:99]
	s_barrier
	s_setprio 0
	ds_read_b128 v[200:203], v153
	ds_read_b128 v[204:207], v153 offset:1024
	ds_read_b128 v[208:211], v153 offset:2048
	ds_read_b128 v[212:215], v153 offset:3072
	ds_read_b128 v[246:249], v152 offset:16384
	ds_read_b128 v[250:253], v152 offset:17408
	s_add_i32 s38, s13, s36
	s_mov_b32 m0, s15
	s_add_i32 s39, s38, 0x100
	buffer_load_dwordx4 v137, s[80:83], s39 offen lds
	s_mov_b32 m0, s16
	s_add_i32 s39, s38, 0x80100
	buffer_load_dwordx4 v137, s[80:83], s39 offen lds
	s_waitcnt vmcnt(6)
	s_setprio 1
	s_barrier
	s_waitcnt lgkmcnt(2)
	v_mfma_f32_16x16x32_bf16 v[92:95], v[168:171], v[200:203], v[92:95]
	v_mfma_f32_16x16x32_bf16 v[88:91], v[168:171], v[208:211], v[88:91]
	v_mfma_f32_16x16x32_bf16 v[84:87], v[176:179], v[200:203], v[84:87]
	v_mfma_f32_16x16x32_bf16 v[80:83], v[176:179], v[208:211], v[80:83]
	v_mfma_f32_16x16x32_bf16 v[76:79], v[184:187], v[200:203], v[76:79]
	v_mfma_f32_16x16x32_bf16 v[72:75], v[184:187], v[208:211], v[72:75]
	v_mfma_f32_16x16x32_bf16 v[68:71], v[192:195], v[200:203], v[68:71]
	v_mfma_f32_16x16x32_bf16 v[64:67], v[192:195], v[208:211], v[64:67]
	v_mfma_f32_16x16x32_bf16 v[92:95], v[172:175], v[204:207], v[92:95]
	v_mfma_f32_16x16x32_bf16 v[88:91], v[172:175], v[212:215], v[88:91]
	v_mfma_f32_16x16x32_bf16 v[84:87], v[180:183], v[204:207], v[84:87]
	v_mfma_f32_16x16x32_bf16 v[80:83], v[180:183], v[212:215], v[80:83]
	v_mfma_f32_16x16x32_bf16 v[76:79], v[188:191], v[204:207], v[76:79]
	v_mfma_f32_16x16x32_bf16 v[72:75], v[188:191], v[212:215], v[72:75]
	v_mfma_f32_16x16x32_bf16 v[68:71], v[196:199], v[204:207], v[68:71]
	v_mfma_f32_16x16x32_bf16 v[64:67], v[196:199], v[212:215], v[64:67]
	s_barrier
; #define STAGE_A(POFF, h, kt) STAGE_AX(POFF, h, kt, brow)
; #define STAGE_B(POFF, h, kt) STAGE_BX(POFF, h, kt, bcol)
; #define LDA(dst, b, h) _Pragma("unroll") for (int m = 0; m < 4; ++m) _Pragma("unroll") for (int k = 0; k < 2; ++k) \
;     dst[m][k] = *reinterpret_cast<const bf16x8*>((char*)SA(b, h) + lds_byte(wr * 64 + m * 16 + fr, k * 32 + fq * 8))
; #define LDB(dst, b, h) _Pragma("unroll") for (int n = 0; n < 2; ++n) _Pragma("unroll") for (int k = 0; k < 2; ++k) \
;     dst[n][k] = *reinterpret_cast<const bf16x8*>((char*)SB(b, h) + lds_byte(wc * 32 + n * 16 + fr, k * 32 + fq * 8))
; #define MMA(ai, bj, At_, Bt_) do { __builtin_amdgcn_s_setprio(1); \
;     _Pragma("unroll") for (int k = 0; k < 2; ++k) _Pragma("unroll") for (int m = 0; m < 4; ++m) _Pragma("unroll") for (int n = 0; n < 2; ++n) \
;       acc[ai][bj][m][n] = __builtin_amdgcn_mfma_f32_16x16x32_bf16(At_[m][k], Bt_[n][k], acc[ai][bj][m][n], 0, 0, 0); \
;     __builtin_amdgcn_s_setprio(0); } while (0)
; #define WAIT_V(n) asm volatile("s_waitcnt vmcnt(" #n ")" ::: "memory")
; #define BAR __builtin_amdgcn_s_barrier()
; #define SCHED __builtin_amdgcn_sched_barrier(0)
; template <int EPI, int N, int K>
; __device__ __forceinline__ void gemm_phase(const bf16_t* __restrict__ A, const bf16_t* __restrict__ Bt, const EpiArgs ea) {
;     ...
;       LDA(At, 0, 1); STAGE_A(SA_OFF(0, 0), 0, t + 2);
;       BAR; WAIT_L(0); MMA(1, 0, At, B0); BAR; SCHED;
;       STAGE_B(SB_OFF(0, 1), 1, t + 2);
;       WAIT_V(6); BAR; MMA(1, 1, At, B1); BAR;
;       LDB(B0, 1, 0); SCHED; LDA(At, 1, 0); STAGE_A(SA_OFF(0, 1), 1, t + 2);
;       WAIT_L(8); BAR; WAIT_L(0); MMA(0, 0, At, B0); BAR; SCHED;
;       LDB(B1, 1, 1); STAGE_B(SB_OFF(1, 0), 0, t + 3);
;       BAR; WAIT_L(0); MMA(0, 1, At, B1); BAR;
	s_setprio 0
	ds_read_b128 v[168:171], v149 offset:32768
	ds_read_b128 v[172:175], v149 offset:33792
	ds_read_b128 v[176:179], v150 offset:32768
	ds_read_b128 v[180:183], v150 offset:33792
	ds_read_b128 v[184:187], v151 offset:32768
	ds_read_b128 v[188:191], v151 offset:33792
	s_mov_b32 m0, s14
	s_add_i32 s39, s37, 0x100
	buffer_load_dwordx4 v136, s[48:51], s39 offen lds
	s_mov_b32 m0, s17
	s_add_i32 s40, s37, 0x40100
	buffer_load_dwordx4 v136, s[48:51], s40 offen lds
	s_waitcnt vmcnt(10)
	s_setprio 1
	s_barrier
	s_waitcnt lgkmcnt(6)
	v_mfma_f32_16x16x32_bf16 v[60:63], v[218:221], v[132:135], v[60:63]
	v_mfma_f32_16x16x32_bf16 v[56:59], v[218:221], v[160:163], v[56:59]
	v_mfma_f32_16x16x32_bf16 v[52:55], v[226:229], v[132:135], v[52:55]
	v_mfma_f32_16x16x32_bf16 v[48:51], v[226:229], v[160:163], v[48:51]
	v_mfma_f32_16x16x32_bf16 v[44:47], v[238:241], v[132:135], v[44:47]
	v_mfma_f32_16x16x32_bf16 v[40:43], v[238:241], v[160:163], v[40:43]
	v_mfma_f32_16x16x32_bf16 v[36:39], v[246:249], v[132:135], v[36:39]
	v_mfma_f32_16x16x32_bf16 v[32:35], v[246:249], v[160:163], v[32:35]
	v_mfma_f32_16x16x32_bf16 v[60:63], v[222:225], v[156:159], v[60:63]
	v_mfma_f32_16x16x32_bf16 v[56:59], v[222:225], v[164:167], v[56:59]
	v_mfma_f32_16x16x32_bf16 v[52:55], v[230:233], v[156:159], v[52:55]
	v_mfma_f32_16x16x32_bf16 v[48:51], v[230:233], v[164:167], v[48:51]
	v_mfma_f32_16x16x32_bf16 v[44:47], v[242:245], v[156:159], v[44:47]
	v_mfma_f32_16x16x32_bf16 v[40:43], v[242:245], v[164:167], v[40:43]
	v_mfma_f32_16x16x32_bf16 v[36:39], v[250:253], v[156:159], v[36:39]
	v_mfma_f32_16x16x32_bf16 v[32:35], v[250:253], v[164:167], v[32:35]
	s_barrier
	s_setprio 0
	ds_read_b128 v[132:135], v154
	ds_read_b128 v[156:159], v154 offset:1024
	ds_read_b128 v[160:163], v154 offset:2048
	ds_read_b128 v[164:167], v154 offset:3072
	ds_read_b128 v[192:195], v152 offset:32768
	ds_read_b128 v[196:199], v152 offset:33792
	s_mov_b32 m0, s18
	s_add_i32 s40, s38, 0x2100
	buffer_load_dwordx4 v137, s[80:83], s40 offen lds
	s_mov_b32 m0, s19
	s_add_i32 s40, s38, 0x82100
	buffer_load_dwordx4 v137, s[80:83], s40 offen lds
	s_waitcnt vmcnt(6)
	s_setprio 1
	s_barrier
	v_mfma_f32_16x16x32_bf16 v[28:31], v[218:221], v[200:203], v[28:31]
	v_mfma_f32_16x16x32_bf16 v[24:27], v[218:221], v[208:211], v[24:27]
	v_mfma_f32_16x16x32_bf16 v[20:23], v[226:229], v[200:203], v[20:23]
	v_mfma_f32_16x16x32_bf16 v[16:19], v[226:229], v[208:211], v[16:19]
	v_mfma_f32_16x16x32_bf16 v[12:15], v[238:241], v[200:203], v[12:15]
	v_mfma_f32_16x16x32_bf16 v[8:11], v[238:241], v[208:211], v[8:11]
	v_mfma_f32_16x16x32_bf16 v[4:7], v[246:249], v[200:203], v[4:7]
	v_mfma_f32_16x16x32_bf16 v[0:3], v[246:249], v[208:211], v[0:3]
	v_mfma_f32_16x16x32_bf16 v[28:31], v[222:225], v[204:207], v[28:31]
	v_mfma_f32_16x16x32_bf16 v[24:27], v[222:225], v[212:215], v[24:27]
	v_mfma_f32_16x16x32_bf16 v[20:23], v[230:233], v[204:207], v[20:23]
	v_mfma_f32_16x16x32_bf16 v[16:19], v[230:233], v[212:215], v[16:19]
	v_mfma_f32_16x16x32_bf16 v[12:15], v[242:245], v[204:207], v[12:15]
	v_mfma_f32_16x16x32_bf16 v[8:11], v[242:245], v[212:215], v[8:11]
	v_mfma_f32_16x16x32_bf16 v[4:7], v[250:253], v[204:207], v[4:7]
	v_mfma_f32_16x16x32_bf16 v[0:3], v[250:253], v[212:215], v[0:3]
	s_barrier
	s_setprio 0
	ds_read_b128 v[218:221], v149 offset:49152
	ds_read_b128 v[222:225], v149 offset:50176
	ds_read_b128 v[226:229], v150 offset:49152
	ds_read_b128 v[230:233], v150 offset:50176
	ds_read_b128 v[238:241], v151 offset:49152
	ds_read_b128 v[242:245], v151 offset:50176
	s_mov_b32 m0, s21
	s_or_b32 s40, s39, 0x80000
	buffer_load_dwordx4 v136, s[48:51], s40 offen lds
	s_mov_b32 m0, s22
	s_or_b32 s39, s39, 0xc0000
	buffer_load_dwordx4 v136, s[48:51], s39 offen lds
	s_setprio 1
	s_barrier
	s_waitcnt lgkmcnt(6)
	v_mfma_f32_16x16x32_bf16 v[124:127], v[168:171], v[132:135], v[124:127]
	v_mfma_f32_16x16x32_bf16 v[120:123], v[168:171], v[160:163], v[120:123]
	v_mfma_f32_16x16x32_bf16 v[116:119], v[176:179], v[132:135], v[116:119]
	v_mfma_f32_16x16x32_bf16 v[112:115], v[176:179], v[160:163], v[112:115]
	v_mfma_f32_16x16x32_bf16 v[108:111], v[184:187], v[132:135], v[108:111]
	v_mfma_f32_16x16x32_bf16 v[104:107], v[184:187], v[160:163], v[104:107]
	v_mfma_f32_16x16x32_bf16 v[100:103], v[192:195], v[132:135], v[100:103]
	v_mfma_f32_16x16x32_bf16 v[96:99], v[192:195], v[160:163], v[96:99]
	v_mfma_f32_16x16x32_bf16 v[124:127], v[172:175], v[156:159], v[124:127]
	v_mfma_f32_16x16x32_bf16 v[120:123], v[172:175], v[164:167], v[120:123]
	v_mfma_f32_16x16x32_bf16 v[116:119], v[180:183], v[156:159], v[116:119]
	v_mfma_f32_16x16x32_bf16 v[112:115], v[180:183], v[164:167], v[112:115]
	v_mfma_f32_16x16x32_bf16 v[108:111], v[188:191], v[156:159], v[108:111]
	v_mfma_f32_16x16x32_bf16 v[104:107], v[188:191], v[164:167], v[104:107]
	v_mfma_f32_16x16x32_bf16 v[100:103], v[196:199], v[156:159], v[100:103]
	v_mfma_f32_16x16x32_bf16 v[96:99], v[196:199], v[164:167], v[96:99]
	s_barrier
	s_setprio 0
	ds_read_b128 v[200:203], v155
	ds_read_b128 v[204:207], v155 offset:1024
	ds_read_b128 v[208:211], v155 offset:2048
	ds_read_b128 v[212:215], v155 offset:3072
	ds_read_b128 v[246:249], v152 offset:49152
	ds_read_b128 v[250:253], v152 offset:50176
	s_mov_b32 m0, s23
	s_add_i32 s39, s38, 0x180
	buffer_load_dwordx4 v137, s[80:83], s39 offen lds
	s_mov_b32 m0, s24
	s_add_i32 s39, s38, 0x80180
	buffer_load_dwordx4 v137, s[80:83], s39 offen lds
	s_waitcnt vmcnt(6)
	s_setprio 1
	s_barrier
; #define STAGE_A(POFF, h, kt) STAGE_AX(POFF, h, kt, brow)
; #define STAGE_B(POFF, h, kt) STAGE_BX(POFF, h, kt, bcol)
; #define LDA(dst, b, h) _Pragma("unroll") for (int m = 0; m < 4; ++m) _Pragma("unroll") for (int k = 0; k < 2; ++k) \
;     dst[m][k] = *reinterpret_cast<const bf16x8*>((char*)SA(b, h) + lds_byte(wr * 64 + m * 16 + fr, k * 32 + fq * 8))
; #define LDB(dst, b, h) _Pragma("unroll") for (int n = 0; n < 2; ++n) _Pragma("unroll") for (int k = 0; k < 2; ++k) \
;     dst[n][k] = *reinterpret_cast<const bf16x8*>((char*)SB(b, h) + lds_byte(wc * 32 + n * 16 + fr, k * 32 + fq * 8))
; #define MMA(ai, bj, At_, Bt_) do { __builtin_amdgcn_s_setprio(1); \
;     _Pragma("unroll") for (int k = 0; k < 2; ++k) _Pragma("unroll") for (int m = 0; m < 4; ++m) _Pragma("unroll") for (int n = 0; n < 2; ++n) \
;       acc[ai][bj][m][n] = __builtin_amdgcn_mfma_f32_16x16x32_bf16(At_[m][k], Bt_[n][k], acc[ai][bj][m][n], 0, 0, 0); \
;     __builtin_amdgcn_s_setprio(0); } while (0)
; #define WAIT_V(n) asm volatile("s_waitcnt vmcnt(" #n ")" ::: "memory")
; #define BAR __builtin_amdgcn_s_barrier()
; #define SCHED __builtin_amdgcn_sched_barrier(0)
; template <int EPI, int N, int K>
; __device__ __forceinline__ void gemm_phase(const bf16_t* __restrict__ A, const bf16_t* __restrict__ Bt, const EpiArgs ea) {
;     ...
;       LDA(At, 1, 1); STAGE_A(SA_OFF(1, 0), 0, t + 3);
;       BAR; WAIT_L(0); MMA(1, 0, At, B0); BAR; SCHED;
;       STAGE_B(SB_OFF(1, 1), 1, t + 3);
;       WAIT_V(6); BAR; MMA(1, 1, At, B1); BAR;
;     }
;     { LDB(B0, 0, 0); LDA(At, 0, 0); STAGE_A(SA_OFF(1, 1), 1, nt - 1);
;       BAR; WAIT_L(0); MMA(0, 0, At, B0); BAR;
	s_waitcnt lgkmcnt(2)
	v_mfma_f32_16x16x32_bf16 v[92:95], v[168:171], v[200:203], v[92:95]
	v_mfma_f32_16x16x32_bf16 v[88:91], v[168:171], v[208:211], v[88:91]
	v_mfma_f32_16x16x32_bf16 v[84:87], v[176:179], v[200:203], v[84:87]
	v_mfma_f32_16x16x32_bf16 v[80:83], v[176:179], v[208:211], v[80:83]
	v_mfma_f32_16x16x32_bf16 v[76:79], v[184:187], v[200:203], v[76:79]
	v_mfma_f32_16x16x32_bf16 v[72:75], v[184:187], v[208:211], v[72:75]
	v_mfma_f32_16x16x32_bf16 v[68:71], v[192:195], v[200:203], v[68:71]
	v_mfma_f32_16x16x32_bf16 v[64:67], v[192:195], v[208:211], v[64:67]
	v_mfma_f32_16x16x32_bf16 v[92:95], v[172:175], v[204:207], v[92:95]
	v_mfma_f32_16x16x32_bf16 v[88:91], v[172:175], v[212:215], v[88:91]
	v_mfma_f32_16x16x32_bf16 v[84:87], v[180:183], v[204:207], v[84:87]
	v_mfma_f32_16x16x32_bf16 v[80:83], v[180:183], v[212:215], v[80:83]
	v_mfma_f32_16x16x32_bf16 v[76:79], v[188:191], v[204:207], v[76:79]
	v_mfma_f32_16x16x32_bf16 v[72:75], v[188:191], v[212:215], v[72:75]
	v_mfma_f32_16x16x32_bf16 v[68:71], v[196:199], v[204:207], v[68:71]
	v_mfma_f32_16x16x32_bf16 v[64:67], v[196:199], v[212:215], v[64:67]
	s_barrier
	s_setprio 0
	ds_read_b128 v[168:171], v149
	ds_read_b128 v[172:175], v149 offset:1024
	ds_read_b128 v[176:179], v150
	ds_read_b128 v[180:183], v150 offset:1024
	ds_read_b128 v[184:187], v151
	ds_read_b128 v[188:191], v151 offset:1024
	s_mov_b32 m0, s25
	s_add_i32 s39, s37, 0x180
	buffer_load_dwordx4 v136, s[48:51], s39 offen lds
	s_mov_b32 m0, s26
	s_add_i32 s37, s37, 0x40180
	buffer_load_dwordx4 v136, s[48:51], s37 offen lds
	s_waitcnt vmcnt(10)
	s_setprio 1
	s_barrier
	s_waitcnt lgkmcnt(6)
	v_mfma_f32_16x16x32_bf16 v[60:63], v[218:221], v[132:135], v[60:63]
	v_mfma_f32_16x16x32_bf16 v[56:59], v[218:221], v[160:163], v[56:59]
	v_mfma_f32_16x16x32_bf16 v[52:55], v[226:229], v[132:135], v[52:55]
	v_mfma_f32_16x16x32_bf16 v[48:51], v[226:229], v[160:163], v[48:51]
	v_mfma_f32_16x16x32_bf16 v[44:47], v[238:241], v[132:135], v[44:47]
	v_mfma_f32_16x16x32_bf16 v[40:43], v[238:241], v[160:163], v[40:43]
	v_mfma_f32_16x16x32_bf16 v[36:39], v[246:249], v[132:135], v[36:39]
	v_mfma_f32_16x16x32_bf16 v[32:35], v[246:249], v[160:163], v[32:35]
	v_mfma_f32_16x16x32_bf16 v[60:63], v[222:225], v[156:159], v[60:63]
	v_mfma_f32_16x16x32_bf16 v[56:59], v[222:225], v[164:167], v[56:59]
	v_mfma_f32_16x16x32_bf16 v[52:55], v[230:233], v[156:159], v[52:55]
	v_mfma_f32_16x16x32_bf16 v[48:51], v[230:233], v[164:167], v[48:51]
	v_mfma_f32_16x16x32_bf16 v[44:47], v[242:245], v[156:159], v[44:47]
	v_mfma_f32_16x16x32_bf16 v[40:43], v[242:245], v[164:167], v[40:43]
	v_mfma_f32_16x16x32_bf16 v[36:39], v[250:253], v[156:159], v[36:39]
	v_mfma_f32_16x16x32_bf16 v[32:35], v[250:253], v[164:167], v[32:35]
	s_barrier
	s_setprio 0
	ds_read_b128 v[132:135], v148
	ds_read_b128 v[156:159], v148 offset:1024
	ds_read_b128 v[160:163], v148 offset:2048
	ds_read_b128 v[164:167], v148 offset:3072
	ds_read_b128 v[192:195], v152
	ds_read_b128 v[196:199], v152 offset:1024
	s_mov_b32 m0, s27
	s_add_i32 s37, s38, 0x2180
	buffer_load_dwordx4 v137, s[80:83], s37 offen lds
	s_mov_b32 m0, s28
	s_add_i32 s38, s38, 0x82180
	buffer_load_dwordx4 v137, s[80:83], s38 offen lds
	s_waitcnt vmcnt(6)
	s_setprio 1
	s_barrier
	v_mfma_f32_16x16x32_bf16 v[28:31], v[218:221], v[200:203], v[28:31]
	v_mfma_f32_16x16x32_bf16 v[24:27], v[218:221], v[208:211], v[24:27]
	v_mfma_f32_16x16x32_bf16 v[20:23], v[226:229], v[200:203], v[20:23]
	v_mfma_f32_16x16x32_bf16 v[16:19], v[226:229], v[208:211], v[16:19]
	v_mfma_f32_16x16x32_bf16 v[12:15], v[238:241], v[200:203], v[12:15]
	v_mfma_f32_16x16x32_bf16 v[8:11], v[238:241], v[208:211], v[8:11]
	v_mfma_f32_16x16x32_bf16 v[4:7], v[246:249], v[200:203], v[4:7]
	v_mfma_f32_16x16x32_bf16 v[0:3], v[246:249], v[208:211], v[0:3]
	v_mfma_f32_16x16x32_bf16 v[28:31], v[222:225], v[204:207], v[28:31]
	v_mfma_f32_16x16x32_bf16 v[24:27], v[222:225], v[212:215], v[24:27]
	v_mfma_f32_16x16x32_bf16 v[20:23], v[230:233], v[204:207], v[20:23]
	v_mfma_f32_16x16x32_bf16 v[16:19], v[230:233], v[212:215], v[16:19]
	v_mfma_f32_16x16x32_bf16 v[12:15], v[242:245], v[204:207], v[12:15]
	v_mfma_f32_16x16x32_bf16 v[8:11], v[242:245], v[212:215], v[8:11]
	v_mfma_f32_16x16x32_bf16 v[4:7], v[250:253], v[204:207], v[4:7]
	v_mfma_f32_16x16x32_bf16 v[0:3], v[250:253], v[212:215], v[0:3]
	s_barrier
	s_setprio 0
	s_add_i32 s35, s35, 2
	s_addk_i32 s36, 0x100
	s_cmp_lt_u32 s35, 28
	s_cbranch_scc1 .LBB0_509
	s_and_b32 s3, s3, 0x700
	s_lshl_b32 s2, s2, 11
	s_or_b32 s34, s3, s2
	s_lshl_b32 s2, s34, 12
	s_or_b32 s3, s2, 0x80f80
	s_mov_b32 m0, s29
	s_nop 0
	buffer_load_dwordx4 v136, s[48:51], s3 offen lds
	s_or_b32 s2, s2, 0xc0f80
	s_mov_b32 m0, s30
	s_nop 0
	buffer_load_dwordx4 v136, s[48:51], s2 offen lds
	s_barrier
	s_waitcnt lgkmcnt(0)
	s_setprio 1
	v_mfma_f32_16x16x32_bf16 v[124:127], v[168:171], v[132:135], v[124:127]
	v_mfma_f32_16x16x32_bf16 v[120:123], v[168:171], v[160:163], v[120:123]
	v_mfma_f32_16x16x32_bf16 v[116:119], v[176:179], v[132:135], v[116:119]
	v_mfma_f32_16x16x32_bf16 v[112:115], v[176:179], v[160:163], v[112:115]
	v_mfma_f32_16x16x32_bf16 v[108:111], v[184:187], v[132:135], v[108:111]
	v_mfma_f32_16x16x32_bf16 v[104:107], v[184:187], v[160:163], v[104:107]
	v_mfma_f32_16x16x32_bf16 v[100:103], v[192:195], v[132:135], v[100:103]
	v_mfma_f32_16x16x32_bf16 v[96:99], v[192:195], v[160:163], v[96:99]
	v_mfma_f32_16x16x32_bf16 v[124:127], v[172:175], v[156:159], v[124:127]
	v_mfma_f32_16x16x32_bf16 v[120:123], v[172:175], v[164:167], v[120:123]
	v_mfma_f32_16x16x32_bf16 v[116:119], v[180:183], v[156:159], v[116:119]
	v_mfma_f32_16x16x32_bf16 v[112:115], v[180:183], v[164:167], v[112:115]
	v_mfma_f32_16x16x32_bf16 v[108:111], v[188:191], v[156:159], v[108:111]
	v_mfma_f32_16x16x32_bf16 v[104:107], v[188:191], v[164:167], v[104:107]
	v_mfma_f32_16x16x32_bf16 v[100:103], v[196:199], v[156:159], v[100:103]
	v_mfma_f32_16x16x32_bf16 v[96:99], v[196:199], v[164:167], v[96:99]
	s_setprio 0
	s_barrier
; #define LDA(dst, b, h) _Pragma("unroll") for (int m = 0; m < 4; ++m) _Pragma("unroll") for (int k = 0; k < 2; ++k) \
;     dst[m][k] = *reinterpret_cast<const bf16x8*>((char*)SA(b, h) + lds_byte(wr * 64 + m * 16 + fr, k * 32 + fq * 8))
; #define LDB(dst, b, h) _Pragma("unroll") for (int n = 0; n < 2; ++n) _Pragma("unroll") for (int k = 0; k < 2; ++k) \
;     dst[n][k] = *reinterpret_cast<const bf16x8*>((char*)SB(b, h) + lds_byte(wc * 32 + n * 16 + fr, k * 32 + fq * 8))
; #define MMA(ai, bj, At_, Bt_) do { __builtin_amdgcn_s_setprio(1); \
;     _Pragma("unroll") for (int k = 0; k < 2; ++k) _Pragma("unroll") for (int m = 0; m < 4; ++m) _Pragma("unroll") for (int n = 0; n < 2; ++n) \
;       acc[ai][bj][m][n] = __builtin_amdgcn_mfma_f32_16x16x32_bf16(At_[m][k], Bt_[n][k], acc[ai][bj][m][n], 0, 0, 0); \
;     __builtin_amdgcn_s_setprio(0); } while (0)
; #define WAIT_V(n) asm volatile("s_waitcnt vmcnt(" #n ")" ::: "memory")
; #define BAR __builtin_amdgcn_s_barrier()
; template <int EPI, int N, int K>
; __device__ __forceinline__ void gemm_phase(const bf16_t* __restrict__ A, const bf16_t* __restrict__ Bt, const EpiArgs ea) {
;     ...
;       LDB(B1, 0, 1); BAR; WAIT_L(0); MMA(0, 1, At, B1); BAR;
;       LDA(At, 0, 1); WAIT_V(4); BAR; WAIT_L(0); MMA(1, 0, At, B0); MMA(1, 1, At, B1); BAR; }
;     { LDB(B0, 1, 0); LDA(At, 1, 0); WAIT_V(2); BAR; WAIT_L(0); MMA(0, 0, At, B0); BAR;
	ds_read_b128 v[200:203], v153
	ds_read_b128 v[204:207], v153 offset:1024
	ds_read_b128 v[208:211], v153 offset:2048
	ds_read_b128 v[212:215], v153 offset:3072
	s_barrier
	s_waitcnt lgkmcnt(0)
	s_setprio 1
	v_mfma_f32_16x16x32_bf16 v[92:95], v[168:171], v[200:203], v[92:95]
	v_mfma_f32_16x16x32_bf16 v[88:91], v[168:171], v[208:211], v[88:91]
	v_mfma_f32_16x16x32_bf16 v[76:79], v[184:187], v[200:203], v[76:79]
	v_mfma_f32_16x16x32_bf16 v[72:75], v[184:187], v[208:211], v[72:75]
	v_mfma_f32_16x16x32_bf16 v[84:87], v[176:179], v[200:203], v[84:87]
	v_mfma_f32_16x16x32_bf16 v[80:83], v[176:179], v[208:211], v[80:83]
	v_mfma_f32_16x16x32_bf16 v[68:71], v[192:195], v[200:203], v[68:71]
	v_mfma_f32_16x16x32_bf16 v[64:67], v[192:195], v[208:211], v[64:67]
	v_mfma_f32_16x16x32_bf16 v[92:95], v[172:175], v[204:207], v[92:95]
	v_mfma_f32_16x16x32_bf16 v[88:91], v[172:175], v[212:215], v[88:91]
	v_mfma_f32_16x16x32_bf16 v[76:79], v[188:191], v[204:207], v[76:79]
	v_mfma_f32_16x16x32_bf16 v[72:75], v[188:191], v[212:215], v[72:75]
	v_mfma_f32_16x16x32_bf16 v[168:171], v[180:183], v[204:207], v[84:87]
	v_mfma_f32_16x16x32_bf16 v[172:175], v[180:183], v[212:215], v[80:83]
	v_mfma_f32_16x16x32_bf16 v[176:179], v[196:199], v[204:207], v[68:71]
	v_mfma_f32_16x16x32_bf16 v[180:183], v[196:199], v[212:215], v[64:67]
	s_setprio 0
	s_barrier
	s_nop 0
	ds_read_b128 v[64:67], v149 offset:16384
	ds_read_b128 v[68:71], v149 offset:17408
	ds_read_b128 v[80:83], v150 offset:16384
	ds_read_b128 v[84:87], v150 offset:17408
	ds_read_b128 v[184:187], v151 offset:16384
	ds_read_b128 v[188:191], v151 offset:17408
	ds_read_b128 v[192:195], v152 offset:16384
	ds_read_b128 v[196:199], v152 offset:17408
	s_waitcnt vmcnt(4)
	s_barrier
	s_waitcnt lgkmcnt(0)
	s_setprio 1
	v_mfma_f32_16x16x32_bf16 v[60:63], v[64:67], v[132:135], v[60:63]
	v_mfma_f32_16x16x32_bf16 v[56:59], v[64:67], v[160:163], v[56:59]
	v_mfma_f32_16x16x32_bf16 v[52:55], v[80:83], v[132:135], v[52:55]
	v_mfma_f32_16x16x32_bf16 v[48:51], v[80:83], v[160:163], v[48:51]
	v_mfma_f32_16x16x32_bf16 v[44:47], v[184:187], v[132:135], v[44:47]
	v_mfma_f32_16x16x32_bf16 v[40:43], v[184:187], v[160:163], v[40:43]
	v_mfma_f32_16x16x32_bf16 v[36:39], v[192:195], v[132:135], v[36:39]
	v_mfma_f32_16x16x32_bf16 v[32:35], v[192:195], v[160:163], v[32:35]
	v_mfma_f32_16x16x32_bf16 v[60:63], v[68:71], v[156:159], v[60:63]
	v_mfma_f32_16x16x32_bf16 v[56:59], v[68:71], v[164:167], v[56:59]
	v_mfma_f32_16x16x32_bf16 v[52:55], v[84:87], v[156:159], v[52:55]
	v_mfma_f32_16x16x32_bf16 v[48:51], v[84:87], v[164:167], v[48:51]
	v_mfma_f32_16x16x32_bf16 v[44:47], v[188:191], v[156:159], v[44:47]
	v_mfma_f32_16x16x32_bf16 v[40:43], v[188:191], v[164:167], v[40:43]
	v_mfma_f32_16x16x32_bf16 v[36:39], v[196:199], v[156:159], v[36:39]
	v_mfma_f32_16x16x32_bf16 v[32:35], v[196:199], v[164:167], v[32:35]
	s_setprio 0
	s_setprio 1
	v_mfma_f32_16x16x32_bf16 v[28:31], v[64:67], v[200:203], v[28:31]
	v_mfma_f32_16x16x32_bf16 v[24:27], v[64:67], v[208:211], v[24:27]
	v_mfma_f32_16x16x32_bf16 v[12:15], v[184:187], v[200:203], v[12:15]
	v_mfma_f32_16x16x32_bf16 v[8:11], v[184:187], v[208:211], v[8:11]
	v_mfma_f32_16x16x32_bf16 v[20:23], v[80:83], v[200:203], v[20:23]
	v_mfma_f32_16x16x32_bf16 v[16:19], v[80:83], v[208:211], v[16:19]
	v_mfma_f32_16x16x32_bf16 v[4:7], v[192:195], v[200:203], v[4:7]
	v_mfma_f32_16x16x32_bf16 v[0:3], v[192:195], v[208:211], v[0:3]
	v_mfma_f32_16x16x32_bf16 v[28:31], v[68:71], v[204:207], v[28:31]
	v_mfma_f32_16x16x32_bf16 v[24:27], v[68:71], v[212:215], v[24:27]
	v_mfma_f32_16x16x32_bf16 v[12:15], v[188:191], v[204:207], v[12:15]
	v_mfma_f32_16x16x32_bf16 v[8:11], v[188:191], v[212:215], v[8:11]
	v_mfma_f32_16x16x32_bf16 v[132:135], v[84:87], v[204:207], v[20:23]
	v_mfma_f32_16x16x32_bf16 v[156:159], v[84:87], v[212:215], v[16:19]
	v_mfma_f32_16x16x32_bf16 v[160:163], v[196:199], v[204:207], v[4:7]
	v_mfma_f32_16x16x32_bf16 v[164:167], v[196:199], v[212:215], v[0:3]
	s_setprio 0
	s_barrier
	s_nop 0
	ds_read_b128 v[0:3], v154
	ds_read_b128 v[4:7], v154 offset:1024
	ds_read_b128 v[16:19], v154 offset:2048
	ds_read_b128 v[184:187], v154 offset:3072
	ds_read_b128 v[20:23], v149 offset:32768
	ds_read_b128 v[188:191], v149 offset:33792
	ds_read_b128 v[192:195], v150 offset:32768
	ds_read_b128 v[196:199], v150 offset:33792
	ds_read_b128 v[200:203], v151 offset:32768
	ds_read_b128 v[204:207], v151 offset:33792
	ds_read_b128 v[208:211], v152 offset:32768
	ds_read_b128 v[212:215], v152 offset:33792
	s_waitcnt vmcnt(2)
	s_barrier
; #define LDA(dst, b, h) _Pragma("unroll") for (int m = 0; m < 4; ++m) _Pragma("unroll") for (int k = 0; k < 2; ++k) \
;     dst[m][k] = *reinterpret_cast<const bf16x8*>((char*)SA(b, h) + lds_byte(wr * 64 + m * 16 + fr, k * 32 + fq * 8))
; #define LDB(dst, b, h) _Pragma("unroll") for (int n = 0; n < 2; ++n) _Pragma("unroll") for (int k = 0; k < 2; ++k) \
;     dst[n][k] = *reinterpret_cast<const bf16x8*>((char*)SB(b, h) + lds_byte(wc * 32 + n * 16 + fr, k * 32 + fq * 8))
; #define MMA(ai, bj, At_, Bt_) do { __builtin_amdgcn_s_setprio(1); \
;     _Pragma("unroll") for (int k = 0; k < 2; ++k) _Pragma("unroll") for (int m = 0; m < 4; ++m) _Pragma("unroll") for (int n = 0; n < 2; ++n) \
;       acc[ai][bj][m][n] = __builtin_amdgcn_mfma_f32_16x16x32_bf16(At_[m][k], Bt_[n][k], acc[ai][bj][m][n], 0, 0, 0); \
;     __builtin_amdgcn_s_setprio(0); } while (0)
; #define WAIT_V(n) asm volatile("s_waitcnt vmcnt(" #n ")" ::: "memory")
; #define BAR __builtin_amdgcn_s_barrier()
; template <int EPI, int N, int K>
; __device__ __forceinline__ void gemm_phase(const bf16_t* __restrict__ A, const bf16_t* __restrict__ Bt, const EpiArgs ea) {
;     ...
;     { LDB(B0, 1, 0); LDA(At, 1, 0); WAIT_V(2); BAR; WAIT_L(0); MMA(0, 0, At, B0); BAR;
;       LDB(B1, 1, 1); WAIT_V(0); BAR; WAIT_L(0); MMA(0, 1, At, B1); BAR;
;       LDA(At, 1, 1); BAR; WAIT_L(0); MMA(1, 0, At, B0); MMA(1, 1, At, B1); BAR; }
;     if (wr == 0) BAR;
	s_waitcnt lgkmcnt(0)
	s_setprio 1
	v_mfma_f32_16x16x32_bf16 v[64:67], v[20:23], v[0:3], v[124:127]
	v_mfma_f32_16x16x32_bf16 v[68:71], v[20:23], v[16:19], v[120:123]
	v_mfma_f32_16x16x32_bf16 v[80:83], v[192:195], v[0:3], v[116:119]
	v_mfma_f32_16x16x32_bf16 v[84:87], v[192:195], v[16:19], v[112:115]
	v_mfma_f32_16x16x32_bf16 v[108:111], v[200:203], v[0:3], v[108:111]
	v_mfma_f32_16x16x32_bf16 v[104:107], v[200:203], v[16:19], v[104:107]
	v_mfma_f32_16x16x32_bf16 v[120:123], v[208:211], v[0:3], v[100:103]
	v_mfma_f32_16x16x32_bf16 v[124:127], v[208:211], v[16:19], v[96:99]
	v_mfma_f32_16x16x32_bf16 v[112:115], v[188:191], v[4:7], v[64:67]
	v_mfma_f32_16x16x32_bf16 v[116:119], v[188:191], v[184:187], v[68:71]
	v_mfma_f32_16x16x32_bf16 v[96:99], v[196:199], v[4:7], v[80:83]
	v_mfma_f32_16x16x32_bf16 v[100:103], v[196:199], v[184:187], v[84:87]
	v_mfma_f32_16x16x32_bf16 v[80:83], v[204:207], v[4:7], v[108:111]
	v_mfma_f32_16x16x32_bf16 v[84:87], v[204:207], v[184:187], v[104:107]
	v_mfma_f32_16x16x32_bf16 v[64:67], v[212:215], v[4:7], v[120:123]
	v_mfma_f32_16x16x32_bf16 v[68:71], v[212:215], v[184:187], v[124:127]
	s_setprio 0
	s_barrier
	ds_read_b128 v[216:219], v155
	ds_read_b128 v[220:223], v155 offset:1024
	ds_read_b128 v[224:227], v155 offset:2048
	ds_read_b128 v[228:231], v155 offset:3072
	s_waitcnt vmcnt(0)
	s_barrier
	s_waitcnt lgkmcnt(0)
	s_setprio 1
	v_mfma_f32_16x16x32_bf16 v[92:95], v[20:23], v[216:219], v[92:95]
	v_mfma_f32_16x16x32_bf16 v[20:23], v[20:23], v[224:227], v[88:91]
	v_mfma_f32_16x16x32_bf16 v[88:91], v[192:195], v[216:219], v[168:171]
	v_mfma_f32_16x16x32_bf16 v[108:111], v[192:195], v[224:227], v[172:175]
	v_mfma_f32_16x16x32_bf16 v[76:79], v[200:203], v[216:219], v[76:79]
	v_mfma_f32_16x16x32_bf16 v[72:75], v[200:203], v[224:227], v[72:75]
	v_mfma_f32_16x16x32_bf16 v[168:171], v[208:211], v[216:219], v[176:179]
	v_mfma_f32_16x16x32_bf16 v[172:175], v[208:211], v[224:227], v[180:183]
	v_mfma_f32_16x16x32_bf16 v[120:123], v[188:191], v[220:223], v[92:95]
	v_mfma_f32_16x16x32_bf16 v[124:127], v[188:191], v[228:231], v[20:23]
	v_mfma_f32_16x16x32_bf16 v[104:107], v[196:199], v[220:223], v[88:91]
	v_mfma_f32_16x16x32_bf16 v[108:111], v[196:199], v[228:231], v[108:111]
	v_mfma_f32_16x16x32_bf16 v[88:91], v[204:207], v[220:223], v[76:79]
	v_mfma_f32_16x16x32_bf16 v[92:95], v[204:207], v[228:231], v[72:75]
	v_mfma_f32_16x16x32_bf16 v[72:75], v[212:215], v[220:223], v[168:171]
	v_mfma_f32_16x16x32_bf16 v[76:79], v[212:215], v[228:231], v[172:175]
	s_setprio 0
	s_barrier
	ds_read_b128 v[168:171], v149 offset:49152
	ds_read_b128 v[172:175], v149 offset:50176
	ds_read_b128 v[176:179], v150 offset:49152
	ds_read_b128 v[180:183], v150 offset:50176
	ds_read_b128 v[188:191], v151 offset:49152
	ds_read_b128 v[192:195], v151 offset:50176
	ds_read_b128 v[196:199], v152 offset:49152
	ds_read_b128 v[200:203], v152 offset:50176
	s_barrier
	s_waitcnt lgkmcnt(0)
	s_setprio 1
	v_mfma_f32_16x16x32_bf16 v[20:23], v[168:171], v[0:3], v[60:63]
	v_mfma_f32_16x16x32_bf16 v[56:59], v[168:171], v[16:19], v[56:59]
	v_mfma_f32_16x16x32_bf16 v[60:63], v[176:179], v[0:3], v[52:55]
	v_mfma_f32_16x16x32_bf16 v[204:207], v[176:179], v[16:19], v[48:51]
	v_mfma_f32_16x16x32_bf16 v[44:47], v[188:191], v[0:3], v[44:47]
	v_mfma_f32_16x16x32_bf16 v[40:43], v[188:191], v[16:19], v[40:43]
	v_mfma_f32_16x16x32_bf16 v[0:3], v[196:199], v[0:3], v[36:39]
	v_mfma_f32_16x16x32_bf16 v[208:211], v[196:199], v[16:19], v[32:35]
	v_mfma_f32_16x16x32_bf16 v[48:51], v[172:175], v[4:7], v[20:23]
	v_mfma_f32_16x16x32_bf16 v[52:55], v[172:175], v[184:187], v[56:59]
	v_mfma_f32_16x16x32_bf16 v[32:35], v[180:183], v[4:7], v[60:63]
	v_mfma_f32_16x16x32_bf16 v[36:39], v[180:183], v[184:187], v[204:207]
	v_mfma_f32_16x16x32_bf16 v[16:19], v[192:195], v[4:7], v[44:47]
	v_mfma_f32_16x16x32_bf16 v[20:23], v[192:195], v[184:187], v[40:43]
	v_mfma_f32_16x16x32_bf16 v[0:3], v[200:203], v[4:7], v[0:3]
	v_mfma_f32_16x16x32_bf16 v[4:7], v[200:203], v[184:187], v[208:211]
	s_setprio 0
	s_setprio 1
	v_mfma_f32_16x16x32_bf16 v[28:31], v[168:171], v[216:219], v[28:31]
	v_mfma_f32_16x16x32_bf16 v[24:27], v[168:171], v[224:227], v[24:27]
	v_mfma_f32_16x16x32_bf16 v[40:43], v[176:179], v[216:219], v[132:135]
	v_mfma_f32_16x16x32_bf16 v[44:47], v[176:179], v[224:227], v[156:159]
	v_mfma_f32_16x16x32_bf16 v[12:15], v[188:191], v[216:219], v[12:15]
	v_mfma_f32_16x16x32_bf16 v[8:11], v[188:191], v[224:227], v[8:11]
	v_mfma_f32_16x16x32_bf16 v[132:135], v[196:199], v[216:219], v[160:163]
	v_mfma_f32_16x16x32_bf16 v[156:159], v[196:199], v[224:227], v[164:167]
	v_mfma_f32_16x16x32_bf16 v[56:59], v[172:175], v[220:223], v[28:31]
	v_mfma_f32_16x16x32_bf16 v[60:63], v[172:175], v[228:231], v[24:27]
	v_mfma_f32_16x16x32_bf16 v[40:43], v[180:183], v[220:223], v[40:43]
	v_mfma_f32_16x16x32_bf16 v[44:47], v[180:183], v[228:231], v[44:47]
	v_mfma_f32_16x16x32_bf16 v[24:27], v[192:195], v[220:223], v[12:15]
	v_mfma_f32_16x16x32_bf16 v[28:31], v[192:195], v[228:231], v[8:11]
	v_mfma_f32_16x16x32_bf16 v[8:11], v[200:203], v[220:223], v[132:135]
	v_mfma_f32_16x16x32_bf16 v[12:15], v[200:203], v[228:231], v[156:159]
	s_setprio 0
	s_barrier
	s_and_saveexec_b64 s[2:3], s[8:9]
	s_cbranch_execz .LBB0_512
	s_barrier

; #define STAGE_A(POFF, h, kt) STAGE_AX(POFF, h, kt, brow)
; #define STAGE_B(POFF, h, kt) STAGE_BX(POFF, h, kt, bcol)
; #define LDA(dst, b, h) _Pragma("unroll") for (int m = 0; m < 4; ++m) _Pragma("unroll") for (int k = 0; k < 2; ++k) \
;     dst[m][k] = *reinterpret_cast<const bf16x8*>((char*)SA(b, h) + lds_byte(wr * 64 + m * 16 + fr, k * 32 + fq * 8))
; #define LDB(dst, b, h) _Pragma("unroll") for (int n = 0; n < 2; ++n) _Pragma("unroll") for (int k = 0; k < 2; ++k) \
;     dst[n][k] = *reinterpret_cast<const bf16x8*>((char*)SB(b, h) + lds_byte(wc * 32 + n * 16 + fr, k * 32 + fq * 8))
; #define MMA(ai, bj, At_, Bt_) do { __builtin_amdgcn_s_setprio(1); \
;     _Pragma("unroll") for (int k = 0; k < 2; ++k) _Pragma("unroll") for (int m = 0; m < 4; ++m) _Pragma("unroll") for (int n = 0; n < 2; ++n) \
;       acc[ai][bj][m][n] = __builtin_amdgcn_mfma_f32_16x16x32_bf16(At_[m][k], Bt_[n][k], acc[ai][bj][m][n], 0, 0, 0); \
;     __builtin_amdgcn_s_setprio(0); } while (0)
; #define WAIT_V(n) asm volatile("s_waitcnt vmcnt(" #n ")" ::: "memory")
; #define BAR __builtin_amdgcn_s_barrier()
; #define SCHED __builtin_amdgcn_sched_barrier(0)
; template <int EPI, int N, int K>
; __device__ __forceinline__ void gemm_phase(const bf16_t* __restrict__ A, const bf16_t* __restrict__ Bt, const EpiArgs ea) {
;     ...
;     int brow, bcol; TILE_RC(w, brow, bcol);
;     f32x4 acc[2][2][4][2];
; #pragma unroll
;     for (int a = 0; a < 2; ++a)
; #pragma unroll
;       for (int b = 0; b < 2; ++b)
; #pragma unroll
;         for (int m = 0; m < 4; ++m)
; #pragma unroll
;           for (int n = 0; n < 2; ++n) acc[a][b][m][n] = (f32x4){0.f, 0.f, 0.f, 0.f};
;     bf16x8 At[4][2], B0[2][2], B1[2][2];
;     if (wr == 1) BAR;
;     if (w == (int)blockIdx.x) { WAIT_V(0); } else { WAIT_V(24); }
;     BAR;
;     BAR;
;     for (int t = 0; t < nt - 2; t += 2) {
;       LDB(B0, 0, 0); SCHED; LDA(At, 0, 0); STAGE_A(SA_OFF(1, 1), 1, t + 1);
;       WAIT_L(8); BAR; WAIT_L(0); MMA(0, 0, At, B0); BAR; SCHED;
;       LDB(B1, 0, 1); STAGE_B(SB_OFF(0, 0), 0, t + 2);
;       BAR; WAIT_L(0); MMA(0, 1, At, B1); BAR;
;       LDA(At, 0, 1); STAGE_A(SA_OFF(0, 0), 0, t + 2);
;       BAR; WAIT_L(0); MMA(1, 0, At, B0); BAR; SCHED;
;       STAGE_B(SB_OFF(0, 1), 1, t + 2);
;       WAIT_V(6); BAR; MMA(1, 1, At, B1); BAR;
.LBB0_567:
	s_lshl_b32 s2, s28, 6
	s_and_b32 s2, s2, 0x1c0
	s_ashr_i32 s3, s28, 3
	s_add_i32 s3, s2, s3
	s_ashr_i32 s2, s3, 31
	s_lshr_b32 s2, s2, 26
	s_add_i32 s10, s3, s2
	s_ashr_i32 s2, s10, 6
	s_andn2_b32 s10, s10, 63
	s_sub_i32 s29, s3, s10
	s_lshl_b32 s3, s29, 8
	s_lshl_b32 s10, s29, 5
	s_lshl_b32 s11, s29, 19
	s_and_b32 s29, s29, 7
	s_lshl_b32 s30, s2, 25
	s_lshl_b32 s29, s29, 22
	s_and_b32 s11, s11, 0xffc00000
	s_or_b32 s29, s30, s29
	s_mov_b32 s30, -2
	s_mov_b32 s31, 0
	s_barrier
	s_barrier
	ds_read_b128 v[132:135], v147
	ds_read_b128 v[156:159], v147 offset:1024
	ds_read_b128 v[160:163], v147 offset:2048
	ds_read_b128 v[164:167], v147 offset:3072
	ds_read_b128 v[168:171], v148
	ds_read_b128 v[172:175], v148 offset:1024
	ds_read_b128 v[176:179], v149
	ds_read_b128 v[180:183], v149 offset:1024
	ds_read_b128 v[184:187], v150
	ds_read_b128 v[188:191], v150 offset:1024
	ds_read_b128 v[192:195], v151
	ds_read_b128 v[196:199], v151 offset:1024
	ds_read_b128 v[218:221], v148 offset:16384
	ds_read_b128 v[222:225], v148 offset:17408
	ds_read_b128 v[226:229], v149 offset:16384
	ds_read_b128 v[230:233], v149 offset:17408
	ds_read_b128 v[238:241], v150 offset:16384
	ds_read_b128 v[242:245], v150 offset:17408
	s_add_i32 s34, s29, s31
	s_mov_b32 m0, s26
	s_or_b32 s35, s34, 0x200080
	buffer_load_dwordx4 v131, s[64:67], s35 offen lds
	s_mov_b32 m0, s27
	s_or_b32 s35, s34, 0x300080
	buffer_load_dwordx4 v131, s[64:67], s35 offen lds
	s_setprio 1
	s_barrier
	s_waitcnt lgkmcnt(6)
	v_mfma_f32_16x16x32_bf16 v[124:127], v[168:171], v[132:135], 0
	v_mfma_f32_16x16x32_bf16 v[120:123], v[168:171], v[160:163], 0
	v_mfma_f32_16x16x32_bf16 v[116:119], v[176:179], v[132:135], 0
	v_mfma_f32_16x16x32_bf16 v[112:115], v[176:179], v[160:163], 0
	v_mfma_f32_16x16x32_bf16 v[108:111], v[184:187], v[132:135], 0
	v_mfma_f32_16x16x32_bf16 v[104:107], v[184:187], v[160:163], 0
	v_mfma_f32_16x16x32_bf16 v[100:103], v[192:195], v[132:135], 0
	v_mfma_f32_16x16x32_bf16 v[96:99], v[192:195], v[160:163], 0
	v_mfma_f32_16x16x32_bf16 v[124:127], v[172:175], v[156:159], v[124:127]
	v_mfma_f32_16x16x32_bf16 v[120:123], v[172:175], v[164:167], v[120:123]
	v_mfma_f32_16x16x32_bf16 v[116:119], v[180:183], v[156:159], v[116:119]
	v_mfma_f32_16x16x32_bf16 v[112:115], v[180:183], v[164:167], v[112:115]
	v_mfma_f32_16x16x32_bf16 v[108:111], v[188:191], v[156:159], v[108:111]
	v_mfma_f32_16x16x32_bf16 v[104:107], v[188:191], v[164:167], v[104:107]
	v_mfma_f32_16x16x32_bf16 v[100:103], v[196:199], v[156:159], v[100:103]
	v_mfma_f32_16x16x32_bf16 v[96:99], v[196:199], v[164:167], v[96:99]
	s_barrier
	s_setprio 0
	ds_read_b128 v[200:203], v152
	ds_read_b128 v[204:207], v152 offset:1024
	ds_read_b128 v[208:211], v152 offset:2048
	ds_read_b128 v[212:215], v152 offset:3072
	ds_read_b128 v[246:249], v151 offset:16384
	ds_read_b128 v[250:253], v151 offset:17408
	s_add_i32 s35, s11, s31
	s_mov_b32 m0, s13
	s_add_i32 s36, s35, 0x100
	buffer_load_dwordx4 v144, s[80:83], s36 offen lds
	s_mov_b32 m0, s14
	s_add_i32 s36, s35, 0x200100
	buffer_load_dwordx4 v144, s[80:83], s36 offen lds
	s_waitcnt vmcnt(6)
	s_setprio 1
	s_barrier
	s_waitcnt lgkmcnt(2)
	v_mfma_f32_16x16x32_bf16 v[92:95], v[168:171], v[200:203], 0
	v_mfma_f32_16x16x32_bf16 v[88:91], v[168:171], v[208:211], 0
	v_mfma_f32_16x16x32_bf16 v[84:87], v[176:179], v[200:203], 0
	v_mfma_f32_16x16x32_bf16 v[80:83], v[176:179], v[208:211], 0
	v_mfma_f32_16x16x32_bf16 v[76:79], v[184:187], v[200:203], 0
	v_mfma_f32_16x16x32_bf16 v[72:75], v[184:187], v[208:211], 0
	v_mfma_f32_16x16x32_bf16 v[68:71], v[192:195], v[200:203], 0
	v_mfma_f32_16x16x32_bf16 v[64:67], v[192:195], v[208:211], 0
	v_mfma_f32_16x16x32_bf16 v[92:95], v[172:175], v[204:207], v[92:95]
	v_mfma_f32_16x16x32_bf16 v[88:91], v[172:175], v[212:215], v[88:91]
	v_mfma_f32_16x16x32_bf16 v[84:87], v[180:183], v[204:207], v[84:87]
	v_mfma_f32_16x16x32_bf16 v[80:83], v[180:183], v[212:215], v[80:83]
	v_mfma_f32_16x16x32_bf16 v[76:79], v[188:191], v[204:207], v[76:79]
	v_mfma_f32_16x16x32_bf16 v[72:75], v[188:191], v[212:215], v[72:75]
	v_mfma_f32_16x16x32_bf16 v[68:71], v[196:199], v[204:207], v[68:71]
	v_mfma_f32_16x16x32_bf16 v[64:67], v[196:199], v[212:215], v[64:67]
	s_barrier
	s_setprio 0
	ds_read_b128 v[168:171], v148 offset:32768
	ds_read_b128 v[172:175], v148 offset:33792
	ds_read_b128 v[176:179], v149 offset:32768
	ds_read_b128 v[180:183], v149 offset:33792
	ds_read_b128 v[184:187], v150 offset:32768
	ds_read_b128 v[188:191], v150 offset:33792
	s_mov_b32 m0, s12
	s_add_i32 s36, s34, 0x100
	buffer_load_dwordx4 v131, s[64:67], s36 offen lds
	s_mov_b32 m0, s15
	s_add_i32 s37, s34, 0x100100
	buffer_load_dwordx4 v131, s[64:67], s37 offen lds
	s_waitcnt vmcnt(10)
	s_setprio 1
	s_barrier
	s_waitcnt lgkmcnt(6)
	v_mfma_f32_16x16x32_bf16 v[60:63], v[218:221], v[132:135], 0
	v_mfma_f32_16x16x32_bf16 v[56:59], v[218:221], v[160:163], 0
	v_mfma_f32_16x16x32_bf16 v[52:55], v[226:229], v[132:135], 0
	v_mfma_f32_16x16x32_bf16 v[48:51], v[226:229], v[160:163], 0
	v_mfma_f32_16x16x32_bf16 v[44:47], v[238:241], v[132:135], 0
	v_mfma_f32_16x16x32_bf16 v[40:43], v[238:241], v[160:163], 0
	v_mfma_f32_16x16x32_bf16 v[36:39], v[246:249], v[132:135], 0
	v_mfma_f32_16x16x32_bf16 v[32:35], v[246:249], v[160:163], 0
	v_mfma_f32_16x16x32_bf16 v[60:63], v[222:225], v[156:159], v[60:63]
	v_mfma_f32_16x16x32_bf16 v[56:59], v[222:225], v[164:167], v[56:59]
	v_mfma_f32_16x16x32_bf16 v[52:55], v[230:233], v[156:159], v[52:55]
	v_mfma_f32_16x16x32_bf16 v[48:51], v[230:233], v[164:167], v[48:51]
	v_mfma_f32_16x16x32_bf16 v[44:47], v[242:245], v[156:159], v[44:47]
	v_mfma_f32_16x16x32_bf16 v[40:43], v[242:245], v[164:167], v[40:43]
	v_mfma_f32_16x16x32_bf16 v[36:39], v[250:253], v[156:159], v[36:39]
	v_mfma_f32_16x16x32_bf16 v[32:35], v[250:253], v[164:167], v[32:35]
	s_barrier
; #define STAGE_A(POFF, h, kt) STAGE_AX(POFF, h, kt, brow)
; #define STAGE_B(POFF, h, kt) STAGE_BX(POFF, h, kt, bcol)
; #define LDA(dst, b, h) _Pragma("unroll") for (int m = 0; m < 4; ++m) _Pragma("unroll") for (int k = 0; k < 2; ++k) \
;     dst[m][k] = *reinterpret_cast<const bf16x8*>((char*)SA(b, h) + lds_byte(wr * 64 + m * 16 + fr, k * 32 + fq * 8))
; #define LDB(dst, b, h) _Pragma("unroll") for (int n = 0; n < 2; ++n) _Pragma("unroll") for (int k = 0; k < 2; ++k) \
;     dst[n][k] = *reinterpret_cast<const bf16x8*>((char*)SB(b, h) + lds_byte(wc * 32 + n * 16 + fr, k * 32 + fq * 8))
; #define MMA(ai, bj, At_, Bt_) do { __builtin_amdgcn_s_setprio(1); \
;     _Pragma("unroll") for (int k = 0; k < 2; ++k) _Pragma("unroll") for (int m = 0; m < 4; ++m) _Pragma("unroll") for (int n = 0; n < 2; ++n) \
;       acc[ai][bj][m][n] = __builtin_amdgcn_mfma_f32_16x16x32_bf16(At_[m][k], Bt_[n][k], acc[ai][bj][m][n], 0, 0, 0); \
;     __builtin_amdgcn_s_setprio(0); } while (0)
; #define WAIT_V(n) asm volatile("s_waitcnt vmcnt(" #n ")" ::: "memory")
; #define BAR __builtin_amdgcn_s_barrier()
; #define SCHED __builtin_amdgcn_sched_barrier(0)
; template <int EPI, int N, int K>
; __device__ __forceinline__ void gemm_phase(const bf16_t* __restrict__ A, const bf16_t* __restrict__ Bt, const EpiArgs ea) {
;     ...
;       WAIT_V(6); BAR; MMA(1, 1, At, B1); BAR;
;       LDB(B0, 1, 0); SCHED; LDA(At, 1, 0); STAGE_A(SA_OFF(0, 1), 1, t + 2);
;       WAIT_L(8); BAR; WAIT_L(0); MMA(0, 0, At, B0); BAR; SCHED;
;       LDB(B1, 1, 1); STAGE_B(SB_OFF(1, 0), 0, t + 3);
;       BAR; WAIT_L(0); MMA(0, 1, At, B1); BAR;
;       LDA(At, 1, 1); STAGE_A(SA_OFF(1, 0), 0, t + 3);
;       BAR; WAIT_L(0); MMA(1, 0, At, B0); BAR; SCHED;
;       STAGE_B(SB_OFF(1, 1), 1, t + 3);
;       WAIT_V(6); BAR; MMA(1, 1, At, B1); BAR;
	s_setprio 0
	ds_read_b128 v[132:135], v153
	ds_read_b128 v[156:159], v153 offset:1024
	ds_read_b128 v[160:163], v153 offset:2048
	ds_read_b128 v[164:167], v153 offset:3072
	ds_read_b128 v[192:195], v151 offset:32768
	ds_read_b128 v[196:199], v151 offset:33792
	s_mov_b32 m0, s16
	s_add_i32 s37, s35, 0x8100
	buffer_load_dwordx4 v144, s[80:83], s37 offen lds
	s_mov_b32 m0, s17
	s_add_i32 s37, s35, 0x208100
	buffer_load_dwordx4 v144, s[80:83], s37 offen lds
	s_waitcnt vmcnt(6)
	s_setprio 1
	s_barrier
	v_mfma_f32_16x16x32_bf16 v[28:31], v[218:221], v[200:203], 0
	v_mfma_f32_16x16x32_bf16 v[24:27], v[218:221], v[208:211], 0
	v_mfma_f32_16x16x32_bf16 v[20:23], v[226:229], v[200:203], 0
	v_mfma_f32_16x16x32_bf16 v[16:19], v[226:229], v[208:211], 0
	v_mfma_f32_16x16x32_bf16 v[12:15], v[238:241], v[200:203], 0
	v_mfma_f32_16x16x32_bf16 v[8:11], v[238:241], v[208:211], 0
	v_mfma_f32_16x16x32_bf16 v[4:7], v[246:249], v[200:203], 0
	v_mfma_f32_16x16x32_bf16 v[0:3], v[246:249], v[208:211], 0
	v_mfma_f32_16x16x32_bf16 v[28:31], v[222:225], v[204:207], v[28:31]
	v_mfma_f32_16x16x32_bf16 v[24:27], v[222:225], v[212:215], v[24:27]
	v_mfma_f32_16x16x32_bf16 v[20:23], v[230:233], v[204:207], v[20:23]
	v_mfma_f32_16x16x32_bf16 v[16:19], v[230:233], v[212:215], v[16:19]
	v_mfma_f32_16x16x32_bf16 v[12:15], v[242:245], v[204:207], v[12:15]
	v_mfma_f32_16x16x32_bf16 v[8:11], v[242:245], v[212:215], v[8:11]
	v_mfma_f32_16x16x32_bf16 v[4:7], v[250:253], v[204:207], v[4:7]
	v_mfma_f32_16x16x32_bf16 v[0:3], v[250:253], v[212:215], v[0:3]
	s_barrier
	s_setprio 0
	ds_read_b128 v[218:221], v148 offset:49152
	ds_read_b128 v[222:225], v148 offset:50176
	ds_read_b128 v[226:229], v149 offset:49152
	ds_read_b128 v[230:233], v149 offset:50176
	ds_read_b128 v[238:241], v150 offset:49152
	ds_read_b128 v[242:245], v150 offset:50176
	s_mov_b32 m0, s18
	s_or_b32 s37, s36, 0x200000
	buffer_load_dwordx4 v131, s[64:67], s37 offen lds
	s_mov_b32 m0, s19
	s_or_b32 s36, s36, 0x300000
	buffer_load_dwordx4 v131, s[64:67], s36 offen lds
	s_setprio 1
	s_barrier
	s_waitcnt lgkmcnt(6)
	v_mfma_f32_16x16x32_bf16 v[124:127], v[168:171], v[132:135], v[124:127]
	v_mfma_f32_16x16x32_bf16 v[120:123], v[168:171], v[160:163], v[120:123]
	v_mfma_f32_16x16x32_bf16 v[116:119], v[176:179], v[132:135], v[116:119]
	v_mfma_f32_16x16x32_bf16 v[112:115], v[176:179], v[160:163], v[112:115]
	v_mfma_f32_16x16x32_bf16 v[108:111], v[184:187], v[132:135], v[108:111]
	v_mfma_f32_16x16x32_bf16 v[104:107], v[184:187], v[160:163], v[104:107]
	v_mfma_f32_16x16x32_bf16 v[100:103], v[192:195], v[132:135], v[100:103]
	v_mfma_f32_16x16x32_bf16 v[96:99], v[192:195], v[160:163], v[96:99]
	v_mfma_f32_16x16x32_bf16 v[124:127], v[172:175], v[156:159], v[124:127]
	v_mfma_f32_16x16x32_bf16 v[120:123], v[172:175], v[164:167], v[120:123]
	v_mfma_f32_16x16x32_bf16 v[116:119], v[180:183], v[156:159], v[116:119]
	v_mfma_f32_16x16x32_bf16 v[112:115], v[180:183], v[164:167], v[112:115]
	v_mfma_f32_16x16x32_bf16 v[108:111], v[188:191], v[156:159], v[108:111]
	v_mfma_f32_16x16x32_bf16 v[104:107], v[188:191], v[164:167], v[104:107]
	v_mfma_f32_16x16x32_bf16 v[100:103], v[196:199], v[156:159], v[100:103]
	v_mfma_f32_16x16x32_bf16 v[96:99], v[196:199], v[164:167], v[96:99]
	s_barrier
	s_setprio 0
	ds_read_b128 v[200:203], v154
	ds_read_b128 v[204:207], v154 offset:1024
	ds_read_b128 v[208:211], v154 offset:2048
	ds_read_b128 v[212:215], v154 offset:3072
	ds_read_b128 v[246:249], v151 offset:49152
	ds_read_b128 v[250:253], v151 offset:50176
	s_mov_b32 m0, s20
	s_add_i32 s36, s35, 0x180
	buffer_load_dwordx4 v144, s[80:83], s36 offen lds
	s_mov_b32 m0, s21
	s_add_i32 s36, s35, 0x200180
	buffer_load_dwordx4 v144, s[80:83], s36 offen lds
	s_waitcnt vmcnt(6)
	s_setprio 1
	s_barrier
	s_waitcnt lgkmcnt(2)
	v_mfma_f32_16x16x32_bf16 v[92:95], v[168:171], v[200:203], v[92:95]
	v_mfma_f32_16x16x32_bf16 v[88:91], v[168:171], v[208:211], v[88:91]
	v_mfma_f32_16x16x32_bf16 v[84:87], v[176:179], v[200:203], v[84:87]
	v_mfma_f32_16x16x32_bf16 v[80:83], v[176:179], v[208:211], v[80:83]
	v_mfma_f32_16x16x32_bf16 v[76:79], v[184:187], v[200:203], v[76:79]
	v_mfma_f32_16x16x32_bf16 v[72:75], v[184:187], v[208:211], v[72:75]
	v_mfma_f32_16x16x32_bf16 v[68:71], v[192:195], v[200:203], v[68:71]
	v_mfma_f32_16x16x32_bf16 v[64:67], v[192:195], v[208:211], v[64:67]
	v_mfma_f32_16x16x32_bf16 v[92:95], v[172:175], v[204:207], v[92:95]
	v_mfma_f32_16x16x32_bf16 v[88:91], v[172:175], v[212:215], v[88:91]
	v_mfma_f32_16x16x32_bf16 v[84:87], v[180:183], v[204:207], v[84:87]
	v_mfma_f32_16x16x32_bf16 v[80:83], v[180:183], v[212:215], v[80:83]
	v_mfma_f32_16x16x32_bf16 v[76:79], v[188:191], v[204:207], v[76:79]
	v_mfma_f32_16x16x32_bf16 v[72:75], v[188:191], v[212:215], v[72:75]
	v_mfma_f32_16x16x32_bf16 v[68:71], v[196:199], v[204:207], v[68:71]
	v_mfma_f32_16x16x32_bf16 v[64:67], v[196:199], v[212:215], v[64:67]
	s_barrier
	s_setprio 0
	ds_read_b128 v[168:171], v148
	ds_read_b128 v[172:175], v148 offset:1024
	ds_read_b128 v[176:179], v149
	ds_read_b128 v[180:183], v149 offset:1024
	ds_read_b128 v[184:187], v150
	ds_read_b128 v[188:191], v150 offset:1024
	s_mov_b32 m0, s22
	s_add_i32 s36, s34, 0x180
	buffer_load_dwordx4 v131, s[64:67], s36 offen lds
	s_mov_b32 m0, s23
	s_add_i32 s34, s34, 0x100180
	buffer_load_dwordx4 v131, s[64:67], s34 offen lds
	s_waitcnt vmcnt(10)
	s_setprio 1
	s_barrier
; #define STAGE_A(POFF, h, kt) STAGE_AX(POFF, h, kt, brow)
; #define STAGE_B(POFF, h, kt) STAGE_BX(POFF, h, kt, bcol)
; #define LDA(dst, b, h) _Pragma("unroll") for (int m = 0; m < 4; ++m) _Pragma("unroll") for (int k = 0; k < 2; ++k) \
;     dst[m][k] = *reinterpret_cast<const bf16x8*>((char*)SA(b, h) + lds_byte(wr * 64 + m * 16 + fr, k * 32 + fq * 8))
; #define LDB(dst, b, h) _Pragma("unroll") for (int n = 0; n < 2; ++n) _Pragma("unroll") for (int k = 0; k < 2; ++k) \
;     dst[n][k] = *reinterpret_cast<const bf16x8*>((char*)SB(b, h) + lds_byte(wc * 32 + n * 16 + fr, k * 32 + fq * 8))
; #define MMA(ai, bj, At_, Bt_) do { __builtin_amdgcn_s_setprio(1); \
;     _Pragma("unroll") for (int k = 0; k < 2; ++k) _Pragma("unroll") for (int m = 0; m < 4; ++m) _Pragma("unroll") for (int n = 0; n < 2; ++n) \
;       acc[ai][bj][m][n] = __builtin_amdgcn_mfma_f32_16x16x32_bf16(At_[m][k], Bt_[n][k], acc[ai][bj][m][n], 0, 0, 0); \
;     __builtin_amdgcn_s_setprio(0); } while (0)
; #define WAIT_V(n) asm volatile("s_waitcnt vmcnt(" #n ")" ::: "memory")
; #define BAR __builtin_amdgcn_s_barrier()
; #define SCHED __builtin_amdgcn_sched_barrier(0)
; template <int EPI, int N, int K>
; __device__ __forceinline__ void gemm_phase(const bf16_t* __restrict__ A, const bf16_t* __restrict__ Bt, const EpiArgs ea) {
;     ...
;       LDB(B0, 0, 0); SCHED; LDA(At, 0, 0); STAGE_A(SA_OFF(1, 1), 1, t + 1);
;       WAIT_L(8); BAR; WAIT_L(0); MMA(0, 0, At, B0); BAR; SCHED;
;       LDB(B1, 0, 1); STAGE_B(SB_OFF(0, 0), 0, t + 2);
;       BAR; WAIT_L(0); MMA(0, 1, At, B1); BAR;
;       LDA(At, 0, 1); STAGE_A(SA_OFF(0, 0), 0, t + 2);
;       BAR; WAIT_L(0); MMA(1, 0, At, B0); BAR; SCHED;
;       STAGE_B(SB_OFF(0, 1), 1, t + 2);
;       WAIT_V(6); BAR; MMA(1, 1, At, B1); BAR;
;       LDB(B0, 1, 0); SCHED; LDA(At, 1, 0); STAGE_A(SA_OFF(0, 1), 1, t + 2);
;       WAIT_L(8); BAR; WAIT_L(0); MMA(0, 0, At, B0); BAR; SCHED;
;       LDB(B1, 1, 1); STAGE_B(SB_OFF(1, 0), 0, t + 3);
;       BAR; WAIT_L(0); MMA(0, 1, At, B1); BAR;
;       LDA(At, 1, 1); STAGE_A(SA_OFF(1, 0), 0, t + 3);
;       BAR; WAIT_L(0); MMA(1, 0, At, B0); BAR; SCHED;
;       STAGE_B(SB_OFF(1, 1), 1, t + 3);
;       WAIT_V(6); BAR; MMA(1, 1, At, B1); BAR;
	s_waitcnt lgkmcnt(6)
	v_mfma_f32_16x16x32_bf16 v[60:63], v[218:221], v[132:135], v[60:63]
	v_mfma_f32_16x16x32_bf16 v[56:59], v[218:221], v[160:163], v[56:59]
	v_mfma_f32_16x16x32_bf16 v[52:55], v[226:229], v[132:135], v[52:55]
	v_mfma_f32_16x16x32_bf16 v[48:51], v[226:229], v[160:163], v[48:51]
	v_mfma_f32_16x16x32_bf16 v[44:47], v[238:241], v[132:135], v[44:47]
	v_mfma_f32_16x16x32_bf16 v[40:43], v[238:241], v[160:163], v[40:43]
	v_mfma_f32_16x16x32_bf16 v[36:39], v[246:249], v[132:135], v[36:39]
	v_mfma_f32_16x16x32_bf16 v[32:35], v[246:249], v[160:163], v[32:35]
	v_mfma_f32_16x16x32_bf16 v[60:63], v[222:225], v[156:159], v[60:63]
	v_mfma_f32_16x16x32_bf16 v[56:59], v[222:225], v[164:167], v[56:59]
	v_mfma_f32_16x16x32_bf16 v[52:55], v[230:233], v[156:159], v[52:55]
	v_mfma_f32_16x16x32_bf16 v[48:51], v[230:233], v[164:167], v[48:51]
	v_mfma_f32_16x16x32_bf16 v[44:47], v[242:245], v[156:159], v[44:47]
	v_mfma_f32_16x16x32_bf16 v[40:43], v[242:245], v[164:167], v[40:43]
	v_mfma_f32_16x16x32_bf16 v[36:39], v[250:253], v[156:159], v[36:39]
	v_mfma_f32_16x16x32_bf16 v[32:35], v[250:253], v[164:167], v[32:35]
	s_barrier
	s_setprio 0
	ds_read_b128 v[132:135], v147
	ds_read_b128 v[156:159], v147 offset:1024
	ds_read_b128 v[160:163], v147 offset:2048
	ds_read_b128 v[164:167], v147 offset:3072
	ds_read_b128 v[192:195], v151
	ds_read_b128 v[196:199], v151 offset:1024
	s_mov_b32 m0, s24
	s_add_i32 s34, s35, 0x8180
	buffer_load_dwordx4 v144, s[80:83], s34 offen lds
	s_mov_b32 m0, s25
	s_add_i32 s35, s35, 0x208180
	buffer_load_dwordx4 v144, s[80:83], s35 offen lds
	s_waitcnt vmcnt(6)
	s_setprio 1
	s_barrier
	v_mfma_f32_16x16x32_bf16 v[28:31], v[218:221], v[200:203], v[28:31]
	v_mfma_f32_16x16x32_bf16 v[24:27], v[218:221], v[208:211], v[24:27]
	v_mfma_f32_16x16x32_bf16 v[20:23], v[226:229], v[200:203], v[20:23]
	v_mfma_f32_16x16x32_bf16 v[16:19], v[226:229], v[208:211], v[16:19]
	v_mfma_f32_16x16x32_bf16 v[12:15], v[238:241], v[200:203], v[12:15]
	v_mfma_f32_16x16x32_bf16 v[8:11], v[238:241], v[208:211], v[8:11]
	v_mfma_f32_16x16x32_bf16 v[4:7], v[246:249], v[200:203], v[4:7]
	v_mfma_f32_16x16x32_bf16 v[0:3], v[246:249], v[208:211], v[0:3]
	v_mfma_f32_16x16x32_bf16 v[28:31], v[222:225], v[204:207], v[28:31]
	v_mfma_f32_16x16x32_bf16 v[24:27], v[222:225], v[212:215], v[24:27]
	v_mfma_f32_16x16x32_bf16 v[20:23], v[230:233], v[204:207], v[20:23]
	v_mfma_f32_16x16x32_bf16 v[16:19], v[230:233], v[212:215], v[16:19]
	v_mfma_f32_16x16x32_bf16 v[12:15], v[242:245], v[204:207], v[12:15]
	v_mfma_f32_16x16x32_bf16 v[8:11], v[242:245], v[212:215], v[8:11]
	v_mfma_f32_16x16x32_bf16 v[4:7], v[250:253], v[204:207], v[4:7]
	v_mfma_f32_16x16x32_bf16 v[0:3], v[250:253], v[212:215], v[0:3]
	s_barrier
	s_setprio 0
	s_add_i32 s30, s30, 2
	s_addk_i32 s31, 0x100
	s_cmpk_lt_u32 s30, 0x7c
.LBB0_568:
	ds_read_b128 v[218:221], v148 offset:16384
	ds_read_b128 v[222:225], v148 offset:17408
	ds_read_b128 v[226:229], v149 offset:16384
	ds_read_b128 v[230:233], v149 offset:17408
	ds_read_b128 v[238:241], v150 offset:16384
	ds_read_b128 v[242:245], v150 offset:17408
	s_add_i32 s34, s29, s31
	s_mov_b32 m0, s26
	s_or_b32 s35, s34, 0x200080
	buffer_load_dwordx4 v131, s[64:67], s35 offen lds
	s_mov_b32 m0, s27
	s_or_b32 s35, s34, 0x300080
	buffer_load_dwordx4 v131, s[64:67], s35 offen lds
	s_setprio 1
	s_barrier
	s_waitcnt lgkmcnt(6)
	v_mfma_f32_16x16x32_bf16 v[124:127], v[168:171], v[132:135], v[124:127]
	v_mfma_f32_16x16x32_bf16 v[120:123], v[168:171], v[160:163], v[120:123]
	v_mfma_f32_16x16x32_bf16 v[116:119], v[176:179], v[132:135], v[116:119]
	v_mfma_f32_16x16x32_bf16 v[112:115], v[176:179], v[160:163], v[112:115]
	v_mfma_f32_16x16x32_bf16 v[108:111], v[184:187], v[132:135], v[108:111]
	v_mfma_f32_16x16x32_bf16 v[104:107], v[184:187], v[160:163], v[104:107]
	v_mfma_f32_16x16x32_bf16 v[100:103], v[192:195], v[132:135], v[100:103]
	v_mfma_f32_16x16x32_bf16 v[96:99], v[192:195], v[160:163], v[96:99]
	v_mfma_f32_16x16x32_bf16 v[124:127], v[172:175], v[156:159], v[124:127]
	v_mfma_f32_16x16x32_bf16 v[120:123], v[172:175], v[164:167], v[120:123]
	v_mfma_f32_16x16x32_bf16 v[116:119], v[180:183], v[156:159], v[116:119]
	v_mfma_f32_16x16x32_bf16 v[112:115], v[180:183], v[164:167], v[112:115]
	v_mfma_f32_16x16x32_bf16 v[108:111], v[188:191], v[156:159], v[108:111]
	v_mfma_f32_16x16x32_bf16 v[104:107], v[188:191], v[164:167], v[104:107]
	v_mfma_f32_16x16x32_bf16 v[100:103], v[196:199], v[156:159], v[100:103]
	v_mfma_f32_16x16x32_bf16 v[96:99], v[196:199], v[164:167], v[96:99]
	s_barrier
	s_setprio 0
	ds_read_b128 v[200:203], v152
	ds_read_b128 v[204:207], v152 offset:1024
	ds_read_b128 v[208:211], v152 offset:2048
	ds_read_b128 v[212:215], v152 offset:3072
	ds_read_b128 v[246:249], v151 offset:16384
	ds_read_b128 v[250:253], v151 offset:17408
	s_add_i32 s35, s11, s31
	s_mov_b32 m0, s13
	s_add_i32 s36, s35, 0x100
	buffer_load_dwordx4 v144, s[80:83], s36 offen lds
	s_mov_b32 m0, s14
	s_add_i32 s36, s35, 0x200100
	buffer_load_dwordx4 v144, s[80:83], s36 offen lds
	s_waitcnt vmcnt(6)
	s_setprio 1
	s_barrier
	s_waitcnt lgkmcnt(2)
	v_mfma_f32_16x16x32_bf16 v[92:95], v[168:171], v[200:203], v[92:95]
	v_mfma_f32_16x16x32_bf16 v[88:91], v[168:171], v[208:211], v[88:91]
	v_mfma_f32_16x16x32_bf16 v[84:87], v[176:179], v[200:203], v[84:87]
	v_mfma_f32_16x16x32_bf16 v[80:83], v[176:179], v[208:211], v[80:83]
	v_mfma_f32_16x16x32_bf16 v[76:79], v[184:187], v[200:203], v[76:79]
	v_mfma_f32_16x16x32_bf16 v[72:75], v[184:187], v[208:211], v[72:75]
	v_mfma_f32_16x16x32_bf16 v[68:71], v[192:195], v[200:203], v[68:71]
	v_mfma_f32_16x16x32_bf16 v[64:67], v[192:195], v[208:211], v[64:67]
	v_mfma_f32_16x16x32_bf16 v[92:95], v[172:175], v[204:207], v[92:95]
	v_mfma_f32_16x16x32_bf16 v[88:91], v[172:175], v[212:215], v[88:91]
	v_mfma_f32_16x16x32_bf16 v[84:87], v[180:183], v[204:207], v[84:87]
	v_mfma_f32_16x16x32_bf16 v[80:83], v[180:183], v[212:215], v[80:83]
	v_mfma_f32_16x16x32_bf16 v[76:79], v[188:191], v[204:207], v[76:79]
	v_mfma_f32_16x16x32_bf16 v[72:75], v[188:191], v[212:215], v[72:75]
	v_mfma_f32_16x16x32_bf16 v[68:71], v[196:199], v[204:207], v[68:71]
	v_mfma_f32_16x16x32_bf16 v[64:67], v[196:199], v[212:215], v[64:67]
	s_barrier
; #define STAGE_A(POFF, h, kt) STAGE_AX(POFF, h, kt, brow)
; #define STAGE_B(POFF, h, kt) STAGE_BX(POFF, h, kt, bcol)
; #define LDA(dst, b, h) _Pragma("unroll") for (int m = 0; m < 4; ++m) _Pragma("unroll") for (int k = 0; k < 2; ++k) \
;     dst[m][k] = *reinterpret_cast<const bf16x8*>((char*)SA(b, h) + lds_byte(wr * 64 + m * 16 + fr, k * 32 + fq * 8))
; #define LDB(dst, b, h) _Pragma("unroll") for (int n = 0; n < 2; ++n) _Pragma("unroll") for (int k = 0; k < 2; ++k) \
;     dst[n][k] = *reinterpret_cast<const bf16x8*>((char*)SB(b, h) + lds_byte(wc * 32 + n * 16 + fr, k * 32 + fq * 8))
; #define MMA(ai, bj, At_, Bt_) do { __builtin_amdgcn_s_setprio(1); \
;     _Pragma("unroll") for (int k = 0; k < 2; ++k) _Pragma("unroll") for (int m = 0; m < 4; ++m) _Pragma("unroll") for (int n = 0; n < 2; ++n) \
;       acc[ai][bj][m][n] = __builtin_amdgcn_mfma_f32_16x16x32_bf16(At_[m][k], Bt_[n][k], acc[ai][bj][m][n], 0, 0, 0); \
;     __builtin_amdgcn_s_setprio(0); } while (0)
; #define WAIT_V(n) asm volatile("s_waitcnt vmcnt(" #n ")" ::: "memory")
; #define BAR __builtin_amdgcn_s_barrier()
; #define SCHED __builtin_amdgcn_sched_barrier(0)
; template <int EPI, int N, int K>
; __device__ __forceinline__ void gemm_phase(const bf16_t* __restrict__ A, const bf16_t* __restrict__ Bt, const EpiArgs ea) {
;     ...
;       LDA(At, 0, 1); STAGE_A(SA_OFF(0, 0), 0, t + 2);
;       BAR; WAIT_L(0); MMA(1, 0, At, B0); BAR; SCHED;
;       STAGE_B(SB_OFF(0, 1), 1, t + 2);
;       WAIT_V(6); BAR; MMA(1, 1, At, B1); BAR;
;       LDB(B0, 1, 0); SCHED; LDA(At, 1, 0); STAGE_A(SA_OFF(0, 1), 1, t + 2);
;       WAIT_L(8); BAR; WAIT_L(0); MMA(0, 0, At, B0); BAR; SCHED;
;       LDB(B1, 1, 1); STAGE_B(SB_OFF(1, 0), 0, t + 3);
;       BAR; WAIT_L(0); MMA(0, 1, At, B1); BAR;
	s_setprio 0
	ds_read_b128 v[168:171], v148 offset:32768
	ds_read_b128 v[172:175], v148 offset:33792
	ds_read_b128 v[176:179], v149 offset:32768
	ds_read_b128 v[180:183], v149 offset:33792
	ds_read_b128 v[184:187], v150 offset:32768
	ds_read_b128 v[188:191], v150 offset:33792
	s_mov_b32 m0, s12
	s_add_i32 s36, s34, 0x100
	buffer_load_dwordx4 v131, s[64:67], s36 offen lds
	s_mov_b32 m0, s15
	s_add_i32 s37, s34, 0x100100
	buffer_load_dwordx4 v131, s[64:67], s37 offen lds
	s_waitcnt vmcnt(10)
	s_setprio 1
	s_barrier
	s_waitcnt lgkmcnt(6)
	v_mfma_f32_16x16x32_bf16 v[60:63], v[218:221], v[132:135], v[60:63]
	v_mfma_f32_16x16x32_bf16 v[56:59], v[218:221], v[160:163], v[56:59]
	v_mfma_f32_16x16x32_bf16 v[52:55], v[226:229], v[132:135], v[52:55]
	v_mfma_f32_16x16x32_bf16 v[48:51], v[226:229], v[160:163], v[48:51]
	v_mfma_f32_16x16x32_bf16 v[44:47], v[238:241], v[132:135], v[44:47]
	v_mfma_f32_16x16x32_bf16 v[40:43], v[238:241], v[160:163], v[40:43]
	v_mfma_f32_16x16x32_bf16 v[36:39], v[246:249], v[132:135], v[36:39]
	v_mfma_f32_16x16x32_bf16 v[32:35], v[246:249], v[160:163], v[32:35]
	v_mfma_f32_16x16x32_bf16 v[60:63], v[222:225], v[156:159], v[60:63]
	v_mfma_f32_16x16x32_bf16 v[56:59], v[222:225], v[164:167], v[56:59]
	v_mfma_f32_16x16x32_bf16 v[52:55], v[230:233], v[156:159], v[52:55]
	v_mfma_f32_16x16x32_bf16 v[48:51], v[230:233], v[164:167], v[48:51]
	v_mfma_f32_16x16x32_bf16 v[44:47], v[242:245], v[156:159], v[44:47]
	v_mfma_f32_16x16x32_bf16 v[40:43], v[242:245], v[164:167], v[40:43]
	v_mfma_f32_16x16x32_bf16 v[36:39], v[250:253], v[156:159], v[36:39]
	v_mfma_f32_16x16x32_bf16 v[32:35], v[250:253], v[164:167], v[32:35]
	s_barrier
	s_setprio 0
	ds_read_b128 v[132:135], v153
	ds_read_b128 v[156:159], v153 offset:1024
	ds_read_b128 v[160:163], v153 offset:2048
	ds_read_b128 v[164:167], v153 offset:3072
	ds_read_b128 v[192:195], v151 offset:32768
	ds_read_b128 v[196:199], v151 offset:33792
	s_mov_b32 m0, s16
	s_add_i32 s37, s35, 0x8100
	buffer_load_dwordx4 v144, s[80:83], s37 offen lds
	s_mov_b32 m0, s17
	s_add_i32 s37, s35, 0x208100
	buffer_load_dwordx4 v144, s[80:83], s37 offen lds
	s_waitcnt vmcnt(6)
	s_setprio 1
	s_barrier
	v_mfma_f32_16x16x32_bf16 v[28:31], v[218:221], v[200:203], v[28:31]
	v_mfma_f32_16x16x32_bf16 v[24:27], v[218:221], v[208:211], v[24:27]
	v_mfma_f32_16x16x32_bf16 v[20:23], v[226:229], v[200:203], v[20:23]
	v_mfma_f32_16x16x32_bf16 v[16:19], v[226:229], v[208:211], v[16:19]
	v_mfma_f32_16x16x32_bf16 v[12:15], v[238:241], v[200:203], v[12:15]
	v_mfma_f32_16x16x32_bf16 v[8:11], v[238:241], v[208:211], v[8:11]
	v_mfma_f32_16x16x32_bf16 v[4:7], v[246:249], v[200:203], v[4:7]
	v_mfma_f32_16x16x32_bf16 v[0:3], v[246:249], v[208:211], v[0:3]
	v_mfma_f32_16x16x32_bf16 v[28:31], v[222:225], v[204:207], v[28:31]
	v_mfma_f32_16x16x32_bf16 v[24:27], v[222:225], v[212:215], v[24:27]
	v_mfma_f32_16x16x32_bf16 v[20:23], v[230:233], v[204:207], v[20:23]
	v_mfma_f32_16x16x32_bf16 v[16:19], v[230:233], v[212:215], v[16:19]
	v_mfma_f32_16x16x32_bf16 v[12:15], v[242:245], v[204:207], v[12:15]
	v_mfma_f32_16x16x32_bf16 v[8:11], v[242:245], v[212:215], v[8:11]
	v_mfma_f32_16x16x32_bf16 v[4:7], v[250:253], v[204:207], v[4:7]
	v_mfma_f32_16x16x32_bf16 v[0:3], v[250:253], v[212:215], v[0:3]
	s_barrier
	s_setprio 0
	ds_read_b128 v[218:221], v148 offset:49152
	ds_read_b128 v[222:225], v148 offset:50176
	ds_read_b128 v[226:229], v149 offset:49152
	ds_read_b128 v[230:233], v149 offset:50176
	ds_read_b128 v[238:241], v150 offset:49152
	ds_read_b128 v[242:245], v150 offset:50176
	s_mov_b32 m0, s18
	s_or_b32 s37, s36, 0x200000
	buffer_load_dwordx4 v131, s[64:67], s37 offen lds
	s_mov_b32 m0, s19
	s_or_b32 s36, s36, 0x300000
	buffer_load_dwordx4 v131, s[64:67], s36 offen lds
	s_setprio 1
	s_barrier
	s_waitcnt lgkmcnt(6)
	v_mfma_f32_16x16x32_bf16 v[124:127], v[168:171], v[132:135], v[124:127]
	v_mfma_f32_16x16x32_bf16 v[120:123], v[168:171], v[160:163], v[120:123]
	v_mfma_f32_16x16x32_bf16 v[116:119], v[176:179], v[132:135], v[116:119]
	v_mfma_f32_16x16x32_bf16 v[112:115], v[176:179], v[160:163], v[112:115]
	v_mfma_f32_16x16x32_bf16 v[108:111], v[184:187], v[132:135], v[108:111]
	v_mfma_f32_16x16x32_bf16 v[104:107], v[184:187], v[160:163], v[104:107]
	v_mfma_f32_16x16x32_bf16 v[100:103], v[192:195], v[132:135], v[100:103]
	v_mfma_f32_16x16x32_bf16 v[96:99], v[192:195], v[160:163], v[96:99]
	v_mfma_f32_16x16x32_bf16 v[124:127], v[172:175], v[156:159], v[124:127]
	v_mfma_f32_16x16x32_bf16 v[120:123], v[172:175], v[164:167], v[120:123]
	v_mfma_f32_16x16x32_bf16 v[116:119], v[180:183], v[156:159], v[116:119]
	v_mfma_f32_16x16x32_bf16 v[112:115], v[180:183], v[164:167], v[112:115]
	v_mfma_f32_16x16x32_bf16 v[108:111], v[188:191], v[156:159], v[108:111]
	v_mfma_f32_16x16x32_bf16 v[104:107], v[188:191], v[164:167], v[104:107]
	v_mfma_f32_16x16x32_bf16 v[100:103], v[196:199], v[156:159], v[100:103]
	v_mfma_f32_16x16x32_bf16 v[96:99], v[196:199], v[164:167], v[96:99]
	s_barrier
	s_setprio 0
	ds_read_b128 v[200:203], v154
	ds_read_b128 v[204:207], v154 offset:1024
	ds_read_b128 v[208:211], v154 offset:2048
	ds_read_b128 v[212:215], v154 offset:3072
	ds_read_b128 v[246:249], v151 offset:49152
	ds_read_b128 v[250:253], v151 offset:50176
	s_mov_b32 m0, s20
	s_add_i32 s36, s35, 0x180
	buffer_load_dwordx4 v144, s[80:83], s36 offen lds
	s_mov_b32 m0, s21
	s_add_i32 s36, s35, 0x200180
	buffer_load_dwordx4 v144, s[80:83], s36 offen lds
	s_waitcnt vmcnt(6)
	s_setprio 1
	s_barrier
; #define STAGE_A(POFF, h, kt) STAGE_AX(POFF, h, kt, brow)
; #define STAGE_B(POFF, h, kt) STAGE_BX(POFF, h, kt, bcol)
; #define LDA(dst, b, h) _Pragma("unroll") for (int m = 0; m < 4; ++m) _Pragma("unroll") for (int k = 0; k < 2; ++k) \
;     dst[m][k] = *reinterpret_cast<const bf16x8*>((char*)SA(b, h) + lds_byte(wr * 64 + m * 16 + fr, k * 32 + fq * 8))
; #define LDB(dst, b, h) _Pragma("unroll") for (int n = 0; n < 2; ++n) _Pragma("unroll") for (int k = 0; k < 2; ++k) \
;     dst[n][k] = *reinterpret_cast<const bf16x8*>((char*)SB(b, h) + lds_byte(wc * 32 + n * 16 + fr, k * 32 + fq * 8))
; #define MMA(ai, bj, At_, Bt_) do { __builtin_amdgcn_s_setprio(1); \
;     _Pragma("unroll") for (int k = 0; k < 2; ++k) _Pragma("unroll") for (int m = 0; m < 4; ++m) _Pragma("unroll") for (int n = 0; n < 2; ++n) \
;       acc[ai][bj][m][n] = __builtin_amdgcn_mfma_f32_16x16x32_bf16(At_[m][k], Bt_[n][k], acc[ai][bj][m][n], 0, 0, 0); \
;     __builtin_amdgcn_s_setprio(0); } while (0)
; #define WAIT_V(n) asm volatile("s_waitcnt vmcnt(" #n ")" ::: "memory")
; #define BAR __builtin_amdgcn_s_barrier()
; #define SCHED __builtin_amdgcn_sched_barrier(0)
; template <int EPI, int N, int K>
; __device__ __forceinline__ void gemm_phase(const bf16_t* __restrict__ A, const bf16_t* __restrict__ Bt, const EpiArgs ea) {
;     ...
;       LDA(At, 1, 1); STAGE_A(SA_OFF(1, 0), 0, t + 3);
;       BAR; WAIT_L(0); MMA(1, 0, At, B0); BAR; SCHED;
;       STAGE_B(SB_OFF(1, 1), 1, t + 3);
;       WAIT_V(6); BAR; MMA(1, 1, At, B1); BAR;
;     }
;     { LDB(B0, 0, 0); LDA(At, 0, 0); STAGE_A(SA_OFF(1, 1), 1, nt - 1);
;       BAR; WAIT_L(0); MMA(0, 0, At, B0); BAR;
	s_waitcnt lgkmcnt(2)
	v_mfma_f32_16x16x32_bf16 v[92:95], v[168:171], v[200:203], v[92:95]
	v_mfma_f32_16x16x32_bf16 v[88:91], v[168:171], v[208:211], v[88:91]
	v_mfma_f32_16x16x32_bf16 v[84:87], v[176:179], v[200:203], v[84:87]
	v_mfma_f32_16x16x32_bf16 v[80:83], v[176:179], v[208:211], v[80:83]
	v_mfma_f32_16x16x32_bf16 v[76:79], v[184:187], v[200:203], v[76:79]
	v_mfma_f32_16x16x32_bf16 v[72:75], v[184:187], v[208:211], v[72:75]
	v_mfma_f32_16x16x32_bf16 v[68:71], v[192:195], v[200:203], v[68:71]
	v_mfma_f32_16x16x32_bf16 v[64:67], v[192:195], v[208:211], v[64:67]
	v_mfma_f32_16x16x32_bf16 v[92:95], v[172:175], v[204:207], v[92:95]
	v_mfma_f32_16x16x32_bf16 v[88:91], v[172:175], v[212:215], v[88:91]
	v_mfma_f32_16x16x32_bf16 v[84:87], v[180:183], v[204:207], v[84:87]
	v_mfma_f32_16x16x32_bf16 v[80:83], v[180:183], v[212:215], v[80:83]
	v_mfma_f32_16x16x32_bf16 v[76:79], v[188:191], v[204:207], v[76:79]
	v_mfma_f32_16x16x32_bf16 v[72:75], v[188:191], v[212:215], v[72:75]
	v_mfma_f32_16x16x32_bf16 v[68:71], v[196:199], v[204:207], v[68:71]
	v_mfma_f32_16x16x32_bf16 v[64:67], v[196:199], v[212:215], v[64:67]
	s_barrier
	s_setprio 0
	ds_read_b128 v[168:171], v148
	ds_read_b128 v[172:175], v148 offset:1024
	ds_read_b128 v[176:179], v149
	ds_read_b128 v[180:183], v149 offset:1024
	ds_read_b128 v[184:187], v150
	ds_read_b128 v[188:191], v150 offset:1024
	s_mov_b32 m0, s22
	s_add_i32 s36, s34, 0x180
	buffer_load_dwordx4 v131, s[64:67], s36 offen lds
	s_mov_b32 m0, s23
	s_add_i32 s34, s34, 0x100180
	buffer_load_dwordx4 v131, s[64:67], s34 offen lds
	s_waitcnt vmcnt(10)
	s_setprio 1
	s_barrier
	s_waitcnt lgkmcnt(6)
	v_mfma_f32_16x16x32_bf16 v[60:63], v[218:221], v[132:135], v[60:63]
	v_mfma_f32_16x16x32_bf16 v[56:59], v[218:221], v[160:163], v[56:59]
	v_mfma_f32_16x16x32_bf16 v[52:55], v[226:229], v[132:135], v[52:55]
	v_mfma_f32_16x16x32_bf16 v[48:51], v[226:229], v[160:163], v[48:51]
	v_mfma_f32_16x16x32_bf16 v[44:47], v[238:241], v[132:135], v[44:47]
	v_mfma_f32_16x16x32_bf16 v[40:43], v[238:241], v[160:163], v[40:43]
	v_mfma_f32_16x16x32_bf16 v[36:39], v[246:249], v[132:135], v[36:39]
	v_mfma_f32_16x16x32_bf16 v[32:35], v[246:249], v[160:163], v[32:35]
	v_mfma_f32_16x16x32_bf16 v[60:63], v[222:225], v[156:159], v[60:63]
	v_mfma_f32_16x16x32_bf16 v[56:59], v[222:225], v[164:167], v[56:59]
	v_mfma_f32_16x16x32_bf16 v[52:55], v[230:233], v[156:159], v[52:55]
	v_mfma_f32_16x16x32_bf16 v[48:51], v[230:233], v[164:167], v[48:51]
	v_mfma_f32_16x16x32_bf16 v[44:47], v[242:245], v[156:159], v[44:47]
	v_mfma_f32_16x16x32_bf16 v[40:43], v[242:245], v[164:167], v[40:43]
	v_mfma_f32_16x16x32_bf16 v[36:39], v[250:253], v[156:159], v[36:39]
	v_mfma_f32_16x16x32_bf16 v[32:35], v[250:253], v[164:167], v[32:35]
	s_barrier
	s_setprio 0
	ds_read_b128 v[132:135], v147
	ds_read_b128 v[156:159], v147 offset:1024
	ds_read_b128 v[160:163], v147 offset:2048
	ds_read_b128 v[164:167], v147 offset:3072
	ds_read_b128 v[192:195], v151
	ds_read_b128 v[196:199], v151 offset:1024
	s_mov_b32 m0, s24
	s_add_i32 s34, s35, 0x8180
	buffer_load_dwordx4 v144, s[80:83], s34 offen lds
	s_mov_b32 m0, s25
	s_add_i32 s35, s35, 0x208180
	buffer_load_dwordx4 v144, s[80:83], s35 offen lds
	s_waitcnt vmcnt(6)
	s_setprio 1
	s_barrier
	v_mfma_f32_16x16x32_bf16 v[28:31], v[218:221], v[200:203], v[28:31]
	v_mfma_f32_16x16x32_bf16 v[24:27], v[218:221], v[208:211], v[24:27]
	v_mfma_f32_16x16x32_bf16 v[20:23], v[226:229], v[200:203], v[20:23]
	v_mfma_f32_16x16x32_bf16 v[16:19], v[226:229], v[208:211], v[16:19]
	v_mfma_f32_16x16x32_bf16 v[12:15], v[238:241], v[200:203], v[12:15]
	v_mfma_f32_16x16x32_bf16 v[8:11], v[238:241], v[208:211], v[8:11]
	v_mfma_f32_16x16x32_bf16 v[4:7], v[246:249], v[200:203], v[4:7]
	v_mfma_f32_16x16x32_bf16 v[0:3], v[246:249], v[208:211], v[0:3]
	v_mfma_f32_16x16x32_bf16 v[28:31], v[222:225], v[204:207], v[28:31]
	v_mfma_f32_16x16x32_bf16 v[24:27], v[222:225], v[212:215], v[24:27]
	v_mfma_f32_16x16x32_bf16 v[20:23], v[230:233], v[204:207], v[20:23]
	v_mfma_f32_16x16x32_bf16 v[16:19], v[230:233], v[212:215], v[16:19]
	v_mfma_f32_16x16x32_bf16 v[12:15], v[242:245], v[204:207], v[12:15]
	v_mfma_f32_16x16x32_bf16 v[8:11], v[242:245], v[212:215], v[8:11]
	v_mfma_f32_16x16x32_bf16 v[4:7], v[250:253], v[204:207], v[4:7]
	v_mfma_f32_16x16x32_bf16 v[0:3], v[250:253], v[212:215], v[0:3]
	s_barrier
	s_setprio 0
	s_add_i32 s30, s30, 2
	s_addk_i32 s31, 0x100
	s_cmpk_lt_u32 s30, 0x7c
	s_cbranch_scc1 .LBB0_568
	s_and_b32 s3, s3, 0x700
	s_lshl_b32 s2, s2, 11
	s_or_b32 s29, s3, s2
	s_lshl_b32 s2, s29, 14
	s_or_b32 s3, s2, 0x203f80
	s_mov_b32 m0, s26
	s_nop 0
	buffer_load_dwordx4 v131, s[64:67], s3 offen lds
	s_or_b32 s2, s2, 0x303f80
	s_mov_b32 m0, s27
	s_nop 0
	buffer_load_dwordx4 v131, s[64:67], s2 offen lds
	s_barrier
	s_waitcnt lgkmcnt(0)
	s_setprio 1
	v_mfma_f32_16x16x32_bf16 v[124:127], v[168:171], v[132:135], v[124:127]
	v_mfma_f32_16x16x32_bf16 v[120:123], v[168:171], v[160:163], v[120:123]
	v_mfma_f32_16x16x32_bf16 v[116:119], v[176:179], v[132:135], v[116:119]
	v_mfma_f32_16x16x32_bf16 v[112:115], v[176:179], v[160:163], v[112:115]
	v_mfma_f32_16x16x32_bf16 v[108:111], v[184:187], v[132:135], v[108:111]
	v_mfma_f32_16x16x32_bf16 v[104:107], v[184:187], v[160:163], v[104:107]
	v_mfma_f32_16x16x32_bf16 v[100:103], v[192:195], v[132:135], v[100:103]
	v_mfma_f32_16x16x32_bf16 v[96:99], v[192:195], v[160:163], v[96:99]
	v_mfma_f32_16x16x32_bf16 v[124:127], v[172:175], v[156:159], v[124:127]
	v_mfma_f32_16x16x32_bf16 v[120:123], v[172:175], v[164:167], v[120:123]
	v_mfma_f32_16x16x32_bf16 v[116:119], v[180:183], v[156:159], v[116:119]
	v_mfma_f32_16x16x32_bf16 v[112:115], v[180:183], v[164:167], v[112:115]
	v_mfma_f32_16x16x32_bf16 v[108:111], v[188:191], v[156:159], v[108:111]
	v_mfma_f32_16x16x32_bf16 v[104:107], v[188:191], v[164:167], v[104:107]
	v_mfma_f32_16x16x32_bf16 v[100:103], v[196:199], v[156:159], v[100:103]
	v_mfma_f32_16x16x32_bf16 v[96:99], v[196:199], v[164:167], v[96:99]
	s_setprio 0
	s_barrier
; #define LDA(dst, b, h) _Pragma("unroll") for (int m = 0; m < 4; ++m) _Pragma("unroll") for (int k = 0; k < 2; ++k) \
;     dst[m][k] = *reinterpret_cast<const bf16x8*>((char*)SA(b, h) + lds_byte(wr * 64 + m * 16 + fr, k * 32 + fq * 8))
; #define LDB(dst, b, h) _Pragma("unroll") for (int n = 0; n < 2; ++n) _Pragma("unroll") for (int k = 0; k < 2; ++k) \
;     dst[n][k] = *reinterpret_cast<const bf16x8*>((char*)SB(b, h) + lds_byte(wc * 32 + n * 16 + fr, k * 32 + fq * 8))
; #define MMA(ai, bj, At_, Bt_) do { __builtin_amdgcn_s_setprio(1); \
;     _Pragma("unroll") for (int k = 0; k < 2; ++k) _Pragma("unroll") for (int m = 0; m < 4; ++m) _Pragma("unroll") for (int n = 0; n < 2; ++n) \
;       acc[ai][bj][m][n] = __builtin_amdgcn_mfma_f32_16x16x32_bf16(At_[m][k], Bt_[n][k], acc[ai][bj][m][n], 0, 0, 0); \
;     __builtin_amdgcn_s_setprio(0); } while (0)
; #define WAIT_V(n) asm volatile("s_waitcnt vmcnt(" #n ")" ::: "memory")
; #define BAR __builtin_amdgcn_s_barrier()
; template <int EPI, int N, int K>
; __device__ __forceinline__ void gemm_phase(const bf16_t* __restrict__ A, const bf16_t* __restrict__ Bt, const EpiArgs ea) {
;     ...
;       BAR; WAIT_L(0); MMA(0, 0, At, B0); BAR;
;       LDB(B1, 0, 1); BAR; WAIT_L(0); MMA(0, 1, At, B1); BAR;
;       LDA(At, 0, 1); WAIT_V(4); BAR; WAIT_L(0); MMA(1, 0, At, B0); MMA(1, 1, At, B1); BAR; }
;     { LDB(B0, 1, 0); LDA(At, 1, 0); WAIT_V(2); BAR; WAIT_L(0); MMA(0, 0, At, B0); BAR;
	ds_read_b128 v[200:203], v152
	ds_read_b128 v[204:207], v152 offset:1024
	ds_read_b128 v[208:211], v152 offset:2048
	ds_read_b128 v[212:215], v152 offset:3072
	s_barrier
	s_waitcnt lgkmcnt(0)
	s_setprio 1
	v_mfma_f32_16x16x32_bf16 v[92:95], v[168:171], v[200:203], v[92:95]
	v_mfma_f32_16x16x32_bf16 v[88:91], v[168:171], v[208:211], v[88:91]
	v_mfma_f32_16x16x32_bf16 v[76:79], v[184:187], v[200:203], v[76:79]
	v_mfma_f32_16x16x32_bf16 v[72:75], v[184:187], v[208:211], v[72:75]
	v_mfma_f32_16x16x32_bf16 v[84:87], v[176:179], v[200:203], v[84:87]
	v_mfma_f32_16x16x32_bf16 v[80:83], v[176:179], v[208:211], v[80:83]
	v_mfma_f32_16x16x32_bf16 v[68:71], v[192:195], v[200:203], v[68:71]
	v_mfma_f32_16x16x32_bf16 v[64:67], v[192:195], v[208:211], v[64:67]
	v_mfma_f32_16x16x32_bf16 v[92:95], v[172:175], v[204:207], v[92:95]
	v_mfma_f32_16x16x32_bf16 v[88:91], v[172:175], v[212:215], v[88:91]
	v_mfma_f32_16x16x32_bf16 v[76:79], v[188:191], v[204:207], v[76:79]
	v_mfma_f32_16x16x32_bf16 v[72:75], v[188:191], v[212:215], v[72:75]
	v_mfma_f32_16x16x32_bf16 v[168:171], v[180:183], v[204:207], v[84:87]
	v_mfma_f32_16x16x32_bf16 v[172:175], v[180:183], v[212:215], v[80:83]
	v_mfma_f32_16x16x32_bf16 v[176:179], v[196:199], v[204:207], v[68:71]
	v_mfma_f32_16x16x32_bf16 v[180:183], v[196:199], v[212:215], v[64:67]
	s_setprio 0
	s_barrier
	s_nop 0
	ds_read_b128 v[64:67], v148 offset:16384
	ds_read_b128 v[68:71], v148 offset:17408
	ds_read_b128 v[80:83], v149 offset:16384
	ds_read_b128 v[84:87], v149 offset:17408
	ds_read_b128 v[184:187], v150 offset:16384
	ds_read_b128 v[188:191], v150 offset:17408
	ds_read_b128 v[192:195], v151 offset:16384
	ds_read_b128 v[196:199], v151 offset:17408
	s_waitcnt vmcnt(4)
	s_barrier
	s_waitcnt lgkmcnt(0)
	s_setprio 1
	v_mfma_f32_16x16x32_bf16 v[60:63], v[64:67], v[132:135], v[60:63]
	v_mfma_f32_16x16x32_bf16 v[56:59], v[64:67], v[160:163], v[56:59]
	v_mfma_f32_16x16x32_bf16 v[52:55], v[80:83], v[132:135], v[52:55]
	v_mfma_f32_16x16x32_bf16 v[48:51], v[80:83], v[160:163], v[48:51]
	v_mfma_f32_16x16x32_bf16 v[44:47], v[184:187], v[132:135], v[44:47]
	v_mfma_f32_16x16x32_bf16 v[40:43], v[184:187], v[160:163], v[40:43]
	v_mfma_f32_16x16x32_bf16 v[36:39], v[192:195], v[132:135], v[36:39]
	v_mfma_f32_16x16x32_bf16 v[32:35], v[192:195], v[160:163], v[32:35]
	v_mfma_f32_16x16x32_bf16 v[60:63], v[68:71], v[156:159], v[60:63]
	v_mfma_f32_16x16x32_bf16 v[56:59], v[68:71], v[164:167], v[56:59]
	v_mfma_f32_16x16x32_bf16 v[52:55], v[84:87], v[156:159], v[52:55]
	v_mfma_f32_16x16x32_bf16 v[48:51], v[84:87], v[164:167], v[48:51]
	v_mfma_f32_16x16x32_bf16 v[44:47], v[188:191], v[156:159], v[44:47]
	v_mfma_f32_16x16x32_bf16 v[40:43], v[188:191], v[164:167], v[40:43]
	v_mfma_f32_16x16x32_bf16 v[36:39], v[196:199], v[156:159], v[36:39]
	v_mfma_f32_16x16x32_bf16 v[32:35], v[196:199], v[164:167], v[32:35]
	s_setprio 0
	s_setprio 1
	v_mfma_f32_16x16x32_bf16 v[28:31], v[64:67], v[200:203], v[28:31]
	v_mfma_f32_16x16x32_bf16 v[24:27], v[64:67], v[208:211], v[24:27]
	v_mfma_f32_16x16x32_bf16 v[4:7], v[192:195], v[200:203], v[4:7]
	v_mfma_f32_16x16x32_bf16 v[0:3], v[192:195], v[208:211], v[0:3]
	v_mfma_f32_16x16x32_bf16 v[20:23], v[80:83], v[200:203], v[20:23]
	v_mfma_f32_16x16x32_bf16 v[16:19], v[80:83], v[208:211], v[16:19]
	v_mfma_f32_16x16x32_bf16 v[12:15], v[184:187], v[200:203], v[12:15]
	v_mfma_f32_16x16x32_bf16 v[8:11], v[184:187], v[208:211], v[8:11]
	v_mfma_f32_16x16x32_bf16 v[28:31], v[68:71], v[204:207], v[28:31]
	v_mfma_f32_16x16x32_bf16 v[24:27], v[68:71], v[212:215], v[24:27]
	v_mfma_f32_16x16x32_bf16 v[4:7], v[196:199], v[204:207], v[4:7]
	v_mfma_f32_16x16x32_bf16 v[0:3], v[196:199], v[212:215], v[0:3]
	v_mfma_f32_16x16x32_bf16 v[132:135], v[84:87], v[204:207], v[20:23]
	v_mfma_f32_16x16x32_bf16 v[156:159], v[84:87], v[212:215], v[16:19]
	v_mfma_f32_16x16x32_bf16 v[160:163], v[188:191], v[204:207], v[12:15]
	v_mfma_f32_16x16x32_bf16 v[164:167], v[188:191], v[212:215], v[8:11]
	s_setprio 0
	s_barrier
	s_nop 0
	ds_read_b128 v[8:11], v153
	ds_read_b128 v[12:15], v153 offset:1024
	ds_read_b128 v[16:19], v153 offset:2048
	ds_read_b128 v[184:187], v153 offset:3072
	ds_read_b128 v[20:23], v148 offset:32768
	ds_read_b128 v[188:191], v148 offset:33792
	ds_read_b128 v[192:195], v149 offset:32768
	ds_read_b128 v[196:199], v149 offset:33792
	ds_read_b128 v[200:203], v150 offset:32768
	ds_read_b128 v[204:207], v150 offset:33792
	ds_read_b128 v[208:211], v151 offset:32768
	ds_read_b128 v[212:215], v151 offset:33792
	s_waitcnt vmcnt(2)
	s_barrier
; #define LDA(dst, b, h) _Pragma("unroll") for (int m = 0; m < 4; ++m) _Pragma("unroll") for (int k = 0; k < 2; ++k) \
;     dst[m][k] = *reinterpret_cast<const bf16x8*>((char*)SA(b, h) + lds_byte(wr * 64 + m * 16 + fr, k * 32 + fq * 8))
; #define LDB(dst, b, h) _Pragma("unroll") for (int n = 0; n < 2; ++n) _Pragma("unroll") for (int k = 0; k < 2; ++k) \
;     dst[n][k] = *reinterpret_cast<const bf16x8*>((char*)SB(b, h) + lds_byte(wc * 32 + n * 16 + fr, k * 32 + fq * 8))
; #define MMA(ai, bj, At_, Bt_) do { __builtin_amdgcn_s_setprio(1); \
;     _Pragma("unroll") for (int k = 0; k < 2; ++k) _Pragma("unroll") for (int m = 0; m < 4; ++m) _Pragma("unroll") for (int n = 0; n < 2; ++n) \
;       acc[ai][bj][m][n] = __builtin_amdgcn_mfma_f32_16x16x32_bf16(At_[m][k], Bt_[n][k], acc[ai][bj][m][n], 0, 0, 0); \
;     __builtin_amdgcn_s_setprio(0); } while (0)
; #define WAIT_V(n) asm volatile("s_waitcnt vmcnt(" #n ")" ::: "memory")
; #define BAR __builtin_amdgcn_s_barrier()
; template <int EPI, int N, int K>
; __device__ __forceinline__ void gemm_phase(const bf16_t* __restrict__ A, const bf16_t* __restrict__ Bt, const EpiArgs ea) {
;     ...
;     { LDB(B0, 1, 0); LDA(At, 1, 0); WAIT_V(2); BAR; WAIT_L(0); MMA(0, 0, At, B0); BAR;
;       LDB(B1, 1, 1); WAIT_V(0); BAR; WAIT_L(0); MMA(0, 1, At, B1); BAR;
;       LDA(At, 1, 1); BAR; WAIT_L(0); MMA(1, 0, At, B0); MMA(1, 1, At, B1); BAR; }
;     if (wr == 0) BAR;
	s_waitcnt lgkmcnt(0)
	s_setprio 1
	v_mfma_f32_16x16x32_bf16 v[64:67], v[20:23], v[8:11], v[124:127]
	v_mfma_f32_16x16x32_bf16 v[68:71], v[20:23], v[16:19], v[120:123]
	v_mfma_f32_16x16x32_bf16 v[80:83], v[192:195], v[8:11], v[116:119]
	v_mfma_f32_16x16x32_bf16 v[84:87], v[192:195], v[16:19], v[112:115]
	v_mfma_f32_16x16x32_bf16 v[108:111], v[200:203], v[8:11], v[108:111]
	v_mfma_f32_16x16x32_bf16 v[104:107], v[200:203], v[16:19], v[104:107]
	v_mfma_f32_16x16x32_bf16 v[120:123], v[208:211], v[8:11], v[100:103]
	v_mfma_f32_16x16x32_bf16 v[124:127], v[208:211], v[16:19], v[96:99]
	v_mfma_f32_16x16x32_bf16 v[116:119], v[188:191], v[12:15], v[64:67]
	v_mfma_f32_16x16x32_bf16 v[112:115], v[188:191], v[184:187], v[68:71]
	v_mfma_f32_16x16x32_bf16 v[100:103], v[196:199], v[12:15], v[80:83]
	v_mfma_f32_16x16x32_bf16 v[96:99], v[196:199], v[184:187], v[84:87]
	v_mfma_f32_16x16x32_bf16 v[84:87], v[204:207], v[12:15], v[108:111]
	v_mfma_f32_16x16x32_bf16 v[80:83], v[204:207], v[184:187], v[104:107]
	v_mfma_f32_16x16x32_bf16 v[68:71], v[212:215], v[12:15], v[120:123]
	v_mfma_f32_16x16x32_bf16 v[64:67], v[212:215], v[184:187], v[124:127]
	s_setprio 0
	s_barrier
	ds_read_b128 v[216:219], v154
	ds_read_b128 v[220:223], v154 offset:1024
	ds_read_b128 v[224:227], v154 offset:2048
	ds_read_b128 v[228:231], v154 offset:3072
	s_waitcnt vmcnt(0)
	s_barrier
	s_waitcnt lgkmcnt(0)
	s_setprio 1
	v_mfma_f32_16x16x32_bf16 v[92:95], v[20:23], v[216:219], v[92:95]
	v_mfma_f32_16x16x32_bf16 v[20:23], v[20:23], v[224:227], v[88:91]
	v_mfma_f32_16x16x32_bf16 v[88:91], v[192:195], v[216:219], v[168:171]
	v_mfma_f32_16x16x32_bf16 v[104:107], v[192:195], v[224:227], v[172:175]
	v_mfma_f32_16x16x32_bf16 v[76:79], v[200:203], v[216:219], v[76:79]
	v_mfma_f32_16x16x32_bf16 v[72:75], v[200:203], v[224:227], v[72:75]
	v_mfma_f32_16x16x32_bf16 v[168:171], v[208:211], v[216:219], v[176:179]
	v_mfma_f32_16x16x32_bf16 v[172:175], v[208:211], v[224:227], v[180:183]
	v_mfma_f32_16x16x32_bf16 v[124:127], v[188:191], v[220:223], v[92:95]
	v_mfma_f32_16x16x32_bf16 v[120:123], v[188:191], v[228:231], v[20:23]
	v_mfma_f32_16x16x32_bf16 v[108:111], v[196:199], v[220:223], v[88:91]
	v_mfma_f32_16x16x32_bf16 v[104:107], v[196:199], v[228:231], v[104:107]
	v_mfma_f32_16x16x32_bf16 v[92:95], v[204:207], v[220:223], v[76:79]
	v_mfma_f32_16x16x32_bf16 v[88:91], v[204:207], v[228:231], v[72:75]
	v_mfma_f32_16x16x32_bf16 v[76:79], v[212:215], v[220:223], v[168:171]
	v_mfma_f32_16x16x32_bf16 v[72:75], v[212:215], v[228:231], v[172:175]
	s_setprio 0
	s_barrier
	ds_read_b128 v[168:171], v148 offset:49152
	ds_read_b128 v[172:175], v148 offset:50176
	ds_read_b128 v[176:179], v149 offset:49152
	ds_read_b128 v[180:183], v149 offset:50176
	ds_read_b128 v[188:191], v150 offset:49152
	ds_read_b128 v[192:195], v150 offset:50176
	ds_read_b128 v[196:199], v151 offset:49152
	ds_read_b128 v[200:203], v151 offset:50176
	s_barrier
	s_waitcnt lgkmcnt(0)
	s_setprio 1
	v_mfma_f32_16x16x32_bf16 v[20:23], v[168:171], v[8:11], v[60:63]
	v_mfma_f32_16x16x32_bf16 v[56:59], v[168:171], v[16:19], v[56:59]
	v_mfma_f32_16x16x32_bf16 v[60:63], v[176:179], v[8:11], v[52:55]
	v_mfma_f32_16x16x32_bf16 v[204:207], v[176:179], v[16:19], v[48:51]
	v_mfma_f32_16x16x32_bf16 v[44:47], v[188:191], v[8:11], v[44:47]
	v_mfma_f32_16x16x32_bf16 v[40:43], v[188:191], v[16:19], v[40:43]
	v_mfma_f32_16x16x32_bf16 v[8:11], v[196:199], v[8:11], v[36:39]
	v_mfma_f32_16x16x32_bf16 v[208:211], v[196:199], v[16:19], v[32:35]
	v_mfma_f32_16x16x32_bf16 v[52:55], v[172:175], v[12:15], v[20:23]
	v_mfma_f32_16x16x32_bf16 v[48:51], v[172:175], v[184:187], v[56:59]
	v_mfma_f32_16x16x32_bf16 v[36:39], v[180:183], v[12:15], v[60:63]
	v_mfma_f32_16x16x32_bf16 v[32:35], v[180:183], v[184:187], v[204:207]
	v_mfma_f32_16x16x32_bf16 v[20:23], v[192:195], v[12:15], v[44:47]
	v_mfma_f32_16x16x32_bf16 v[16:19], v[192:195], v[184:187], v[40:43]
	v_mfma_f32_16x16x32_bf16 v[8:11], v[200:203], v[12:15], v[8:11]
	v_mfma_f32_16x16x32_bf16 v[12:15], v[200:203], v[184:187], v[208:211]
	s_setprio 0
	s_setprio 1
	v_mfma_f32_16x16x32_bf16 v[28:31], v[168:171], v[216:219], v[28:31]
	v_mfma_f32_16x16x32_bf16 v[24:27], v[168:171], v[224:227], v[24:27]
	v_mfma_f32_16x16x32_bf16 v[40:43], v[176:179], v[216:219], v[132:135]
	v_mfma_f32_16x16x32_bf16 v[132:135], v[176:179], v[224:227], v[156:159]
	v_mfma_f32_16x16x32_bf16 v[156:159], v[188:191], v[216:219], v[160:163]
	v_mfma_f32_16x16x32_bf16 v[160:163], v[188:191], v[224:227], v[164:167]
	v_mfma_f32_16x16x32_bf16 v[4:7], v[196:199], v[216:219], v[4:7]
	v_mfma_f32_16x16x32_bf16 v[0:3], v[196:199], v[224:227], v[0:3]
	v_mfma_f32_16x16x32_bf16 v[60:63], v[172:175], v[220:223], v[28:31]
	v_mfma_f32_16x16x32_bf16 v[56:59], v[172:175], v[228:231], v[24:27]
	v_mfma_f32_16x16x32_bf16 v[44:47], v[180:183], v[220:223], v[40:43]
	v_mfma_f32_16x16x32_bf16 v[40:43], v[180:183], v[228:231], v[132:135]
	v_mfma_f32_16x16x32_bf16 v[28:31], v[192:195], v[220:223], v[156:159]
	v_mfma_f32_16x16x32_bf16 v[24:27], v[192:195], v[228:231], v[160:163]
	v_mfma_f32_16x16x32_bf16 v[4:7], v[200:203], v[220:223], v[4:7]
	v_mfma_f32_16x16x32_bf16 v[0:3], v[200:203], v[228:231], v[0:3]
	s_setprio 0
	s_barrier
	s_and_saveexec_b64 s[2:3], s[6:7]
	s_cbranch_execz .LBB0_571
	s_barrier
